# GEMM k-loops: ds_reads issued before counted lgkmcnt(n) wait instead of after lgkmcnt(0)
# baseline (speedup 1.0000x reference)
; DEV int stage_next(int s) { return (s == 2 * GS_STAGE) ? 0 : s + GS_STAGE; }
; template <int WAIT0>
; DEV void gk_main(f32x16 (&acc)[2][2], const GTile& t, int s0) {
;     ...
;   vm_wait_bar<WAIT0>();
;   int stc = s0, std_ = stage_next(stage_next(s0));
; #pragma nounroll
;   for (int kt = 0; kt < nk - 2; ++kt) {
;     GK_DMA(std_, kt + 2);
;     GK_COMPUTE(stc);
;     vm_wait_bar<6>();
;     stc = stage_next(stc); std_ = stage_next(std_);
;   }
.LBB0_75:
	s_add_i32 s21, s19, s20
	s_mov_b32 s98, s21
	s_mov_b64 s[100:101], s[6:7]
	v_add_u32_e32 v100, s99, v80
	s_add_i32 s21, s18, 0xc000
	s_cmp_lg_u32 s18, 0x18000
	s_cselect_b32 s18, s21, 0
	s_add_i32 s21, s20, 0xc000
	s_cmp_lg_u32 s20, 0x18000
	s_cselect_b32 s20, s21, 0
	ds_read_b128 v[236:239], v101 offset:20480
	s_waitcnt lgkmcnt(1)
	v_mfma_f32_32x32x16_bf16 v[48:63], v[84:87], v[88:91], v[48:63]
	v_mfma_f32_32x32x16_bf16 v[16:31], v[84:87], v[92:95], v[16:31]
	s_mov_b32 m0, s98
	v_lshl_add_u64 v[254:255], v[64:65], 0, s[100:101]
	global_load_lds_dwordx4 v[254:255], off
	v_add_u32_e32 v101, s99, v81
	s_add_u32 s6, s6, 0x80
	s_addc_u32 s7, s7, 0
	ds_read_b128 v[84:87], v101 offset:16384
	ds_read_b128 v[240:243], v100
	ds_read_b128 v[244:247], v100 offset:4096
	s_waitcnt lgkmcnt(3)
	v_mfma_f32_32x32x16_bf16 v[32:47], v[236:239], v[88:91], v[32:47]
	v_mfma_f32_32x32x16_bf16 v[0:15], v[236:239], v[92:95], v[0:15]
	s_add_i32 m0, s98, 0x2000
	v_lshl_add_u64 v[254:255], v[66:67], 0, s[100:101]
	global_load_lds_dwordx4 v[254:255], off
	v_add_u32_e32 v100, s99, v78
	ds_read_b128 v[236:239], v101 offset:20480
	s_waitcnt lgkmcnt(1)
	v_mfma_f32_32x32x16_bf16 v[48:63], v[84:87], v[240:243], v[48:63]
	v_mfma_f32_32x32x16_bf16 v[16:31], v[84:87], v[244:247], v[16:31]
	s_add_i32 m0, s98, 0x4000
	v_lshl_add_u64 v[254:255], v[68:69], 0, s[100:101]
	global_load_lds_dwordx4 v[254:255], off
	v_add_u32_e32 v101, s99, v79
	ds_read_b128 v[84:87], v101 offset:16384
	ds_read_b128 v[88:91], v100
	ds_read_b128 v[92:95], v100 offset:4096
	s_waitcnt lgkmcnt(3)
	v_mfma_f32_32x32x16_bf16 v[32:47], v[236:239], v[240:243], v[32:47]
	v_mfma_f32_32x32x16_bf16 v[0:15], v[236:239], v[244:247], v[0:15]
	s_add_i32 m0, s98, 0x6000
	v_lshl_add_u64 v[254:255], v[70:71], 0, s[100:101]
	global_load_lds_dwordx4 v[254:255], off
	v_add_u32_e32 v100, s99, v76
	ds_read_b128 v[236:239], v101 offset:20480
	s_waitcnt lgkmcnt(1)
	v_mfma_f32_32x32x16_bf16 v[48:63], v[84:87], v[88:91], v[48:63]
	v_mfma_f32_32x32x16_bf16 v[16:31], v[84:87], v[92:95], v[16:31]
	s_add_i32 m0, s98, 0x8000
	v_lshl_add_u64 v[254:255], v[72:73], 0, s[100:101]
	global_load_lds_dwordx4 v[254:255], off
	v_add_u32_e32 v101, s99, v77
	ds_read_b128 v[84:87], v101 offset:16384
	ds_read_b128 v[240:243], v100
	ds_read_b128 v[244:247], v100 offset:4096
	s_waitcnt lgkmcnt(3)
	v_mfma_f32_32x32x16_bf16 v[32:47], v[236:239], v[88:91], v[32:47]
	v_mfma_f32_32x32x16_bf16 v[0:15], v[236:239], v[92:95], v[0:15]
	s_add_i32 m0, s98, 0xa000
	v_lshl_add_u64 v[254:255], v[74:75], 0, s[100:101]
	global_load_lds_dwordx4 v[254:255], off
	ds_read_b128 v[236:239], v101 offset:20480
	s_waitcnt lgkmcnt(1)
	v_mfma_f32_32x32x16_bf16 v[48:63], v[84:87], v[240:243], v[48:63]
	v_mfma_f32_32x32x16_bf16 v[16:31], v[84:87], v[244:247], v[16:31]
	s_waitcnt vmcnt(6) lgkmcnt(0)
	s_barrier
	s_add_i32 s99, s18, 0
	v_add_u32_e32 v100, s99, v82
	v_add_u32_e32 v101, s99, v83
	ds_read_b128 v[84:87], v101 offset:16384
	ds_read_b128 v[88:91], v100
	ds_read_b128 v[92:95], v100 offset:4096
	s_waitcnt lgkmcnt(3)
	v_mfma_f32_32x32x16_bf16 v[32:47], v[236:239], v[240:243], v[32:47]
	v_mfma_f32_32x32x16_bf16 v[0:15], v[236:239], v[244:247], v[0:15]
	s_cmpk_lg_i32 s6, 0x700
	s_cbranch_scc1 .LBB0_75
; DEV int stage_next(int s) { return (s == 2 * GS_STAGE) ? 0 : s + GS_STAGE; }
; template <int WAIT0>
; DEV void gk_main(f32x16 (&acc)[2][2], const GTile& t, int s0) {
;     ...
;   vm_wait_bar<WAIT0>();
;   int stc = s0, std_ = stage_next(stage_next(s0));
; #pragma nounroll
;   for (int kt = 0; kt < nk - 2; ++kt) {
;     GK_DMA(std_, kt + 2);
;     GK_COMPUTE(stc);
;     vm_wait_bar<6>();
;     stc = stage_next(stc); std_ = stage_next(std_);
;   }
;   GK_COMPUTE(stc);
;   vm_wait_bar<0>();
;   stc = stage_next(stc);
;   GK_COMPUTE(stc);
;   vm_wait_bar<0>();
	s_waitcnt lgkmcnt(0)
	s_add_i32 s6, s18, 0
	v_add_u32_e32 v84, s6, v83
	ds_read_b128 v[64:67], v84 offset:16384
	v_add_u32_e32 v72, s6, v82
	ds_read_b128 v[68:71], v72
	ds_read_b128 v[72:75], v72 offset:4096
	s_waitcnt lgkmcnt(0)
	v_mfma_f32_32x32x16_bf16 v[48:63], v[64:67], v[68:71], v[48:63]
	v_mfma_f32_32x32x16_bf16 v[16:31], v[64:67], v[72:75], v[16:31]
	ds_read_b128 v[64:67], v84 offset:20480
	v_add_u32_e32 v84, s6, v81
	s_waitcnt lgkmcnt(0)
	v_mfma_f32_32x32x16_bf16 v[32:47], v[64:67], v[68:71], v[32:47]
	v_mfma_f32_32x32x16_bf16 v[0:15], v[64:67], v[72:75], v[0:15]
	ds_read_b128 v[64:67], v84 offset:16384
	v_add_u32_e32 v72, s6, v80
	ds_read_b128 v[68:71], v72
	ds_read_b128 v[72:75], v72 offset:4096
	s_waitcnt lgkmcnt(0)
	v_mfma_f32_32x32x16_bf16 v[48:63], v[64:67], v[68:71], v[48:63]
	v_mfma_f32_32x32x16_bf16 v[16:31], v[64:67], v[72:75], v[16:31]
	ds_read_b128 v[64:67], v84 offset:20480
	v_add_u32_e32 v84, s6, v79
	s_waitcnt lgkmcnt(0)
	v_mfma_f32_32x32x16_bf16 v[32:47], v[64:67], v[68:71], v[32:47]
	v_mfma_f32_32x32x16_bf16 v[0:15], v[64:67], v[72:75], v[0:15]
	ds_read_b128 v[64:67], v84 offset:16384
	v_add_u32_e32 v72, s6, v78
	ds_read_b128 v[68:71], v72
	ds_read_b128 v[72:75], v72 offset:4096
	s_waitcnt lgkmcnt(0)
	v_mfma_f32_32x32x16_bf16 v[48:63], v[64:67], v[68:71], v[48:63]
	v_mfma_f32_32x32x16_bf16 v[16:31], v[64:67], v[72:75], v[16:31]
	ds_read_b128 v[64:67], v84 offset:20480
	v_add_u32_e32 v84, s6, v77
	s_waitcnt lgkmcnt(0)
	v_mfma_f32_32x32x16_bf16 v[32:47], v[64:67], v[68:71], v[32:47]
	v_mfma_f32_32x32x16_bf16 v[0:15], v[64:67], v[72:75], v[0:15]
	ds_read_b128 v[64:67], v84 offset:16384
	v_add_u32_e32 v72, s6, v76
	ds_read_b128 v[68:71], v72
	ds_read_b128 v[72:75], v72 offset:4096
	s_add_i32 s6, s18, 0xc000
	s_cmp_lg_u32 s18, 0x18000
	s_cselect_b32 s6, s6, 0
	s_waitcnt lgkmcnt(0)
	v_mfma_f32_32x32x16_bf16 v[48:63], v[64:67], v[68:71], v[48:63]
	s_add_i32 s6, s6, 0
	v_add_u32_e32 v83, s6, v83
	v_add_u32_e32 v81, s6, v81
	v_add_u32_e32 v79, s6, v79
	v_add_u32_e32 v77, s6, v77
	v_mfma_f32_32x32x16_bf16 v[16:31], v[64:67], v[72:75], v[16:31]
	ds_read_b128 v[64:67], v84 offset:20480
	s_waitcnt vmcnt(0) lgkmcnt(0)
	s_barrier
	s_waitcnt lgkmcnt(0)
	v_mfma_f32_32x32x16_bf16 v[32:47], v[64:67], v[68:71], v[32:47]
	v_mfma_f32_32x32x16_bf16 v[0:15], v[64:67], v[72:75], v[0:15]
	ds_read_b128 v[64:67], v83 offset:16384
	v_add_u32_e32 v72, s6, v82
	ds_read_b128 v[68:71], v72
	ds_read_b128 v[72:75], v72 offset:4096
	s_waitcnt lgkmcnt(0)
	v_mfma_f32_32x32x16_bf16 v[48:63], v[64:67], v[68:71], v[48:63]
	v_mfma_f32_32x32x16_bf16 v[16:31], v[64:67], v[72:75], v[16:31]
	ds_read_b128 v[64:67], v83 offset:20480
	s_waitcnt lgkmcnt(0)
	v_mfma_f32_32x32x16_bf16 v[32:47], v[64:67], v[68:71], v[32:47]
	v_mfma_f32_32x32x16_bf16 v[0:15], v[64:67], v[72:75], v[0:15]
	ds_read_b128 v[64:67], v81 offset:16384
	v_add_u32_e32 v72, s6, v80
	ds_read_b128 v[68:71], v72
	ds_read_b128 v[72:75], v72 offset:4096
	s_waitcnt lgkmcnt(0)
	v_mfma_f32_32x32x16_bf16 v[48:63], v[64:67], v[68:71], v[48:63]
	v_mfma_f32_32x32x16_bf16 v[16:31], v[64:67], v[72:75], v[16:31]
	ds_read_b128 v[64:67], v81 offset:20480
	s_waitcnt lgkmcnt(0)
	v_mfma_f32_32x32x16_bf16 v[32:47], v[64:67], v[68:71], v[32:47]
	v_mfma_f32_32x32x16_bf16 v[0:15], v[64:67], v[72:75], v[0:15]
	ds_read_b128 v[64:67], v79 offset:16384
	v_add_u32_e32 v72, s6, v78
	ds_read_b128 v[68:71], v72
	ds_read_b128 v[72:75], v72 offset:4096
	s_waitcnt lgkmcnt(0)
	v_mfma_f32_32x32x16_bf16 v[48:63], v[64:67], v[68:71], v[48:63]
	v_mfma_f32_32x32x16_bf16 v[16:31], v[64:67], v[72:75], v[16:31]
	ds_read_b128 v[64:67], v79 offset:20480
	s_waitcnt lgkmcnt(0)
	v_mfma_f32_32x32x16_bf16 v[32:47], v[64:67], v[68:71], v[32:47]
	v_mfma_f32_32x32x16_bf16 v[0:15], v[64:67], v[72:75], v[0:15]
	ds_read_b128 v[64:67], v77 offset:16384
	v_add_u32_e32 v72, s6, v76
	ds_read_b128 v[68:71], v72
	ds_read_b128 v[72:75], v72 offset:4096
	s_mov_b64 s[6:7], 0
	s_waitcnt lgkmcnt(0)
	v_mfma_f32_32x32x16_bf16 v[48:63], v[64:67], v[68:71], v[48:63]
	v_mfma_f32_32x32x16_bf16 v[16:31], v[64:67], v[72:75], v[16:31]
	ds_read_b128 v[64:67], v77 offset:20480
	s_waitcnt vmcnt(0) lgkmcnt(0)
	s_barrier
	s_waitcnt lgkmcnt(0)
	v_mfma_f32_32x32x16_bf16 v[32:47], v[64:67], v[68:71], v[32:47]
	v_mfma_f32_32x32x16_bf16 v[0:15], v[64:67], v[72:75], v[0:15]

; DEV int stage_next(int s) { return (s == 2 * GS_STAGE) ? 0 : s + GS_STAGE; }
; template <int WAIT0>
; DEV void gk_main(f32x16 (&acc)[2][2], const GTile& t, int s0) {
;     ...
;   vm_wait_bar<WAIT0>();
;   int stc = s0, std_ = stage_next(stage_next(s0));
; #pragma nounroll
;   for (int kt = 0; kt < nk - 2; ++kt) {
;     GK_DMA(std_, kt + 2);
;     GK_COMPUTE(stc);
;     vm_wait_bar<6>();
;     stc = stage_next(stc); std_ = stage_next(std_);
;   }
.LBB0_79:
	s_add_i32 s21, s19, s20
	s_mov_b32 s98, s21
	s_mov_b64 s[100:101], s[6:7]
	v_add_u32_e32 v100, s99, v80
	s_add_i32 s21, s18, 0xc000
	s_cmp_lg_u32 s18, 0x18000
	s_cselect_b32 s18, s21, 0
	s_add_i32 s21, s20, 0xc000
	s_cmp_lg_u32 s20, 0x18000
	s_cselect_b32 s20, s21, 0
	ds_read_b128 v[236:239], v101 offset:20480
	s_waitcnt lgkmcnt(1)
	v_mfma_f32_32x32x16_bf16 v[48:63], v[84:87], v[88:91], v[48:63]
	v_mfma_f32_32x32x16_bf16 v[16:31], v[84:87], v[92:95], v[16:31]
	s_mov_b32 m0, s98
	v_lshl_add_u64 v[254:255], v[64:65], 0, s[100:101]
	global_load_lds_dwordx4 v[254:255], off
	v_add_u32_e32 v101, s99, v81
	s_add_u32 s6, s6, 0x80
	s_addc_u32 s7, s7, 0
	ds_read_b128 v[84:87], v101 offset:16384
	ds_read_b128 v[240:243], v100
	ds_read_b128 v[244:247], v100 offset:4096
	s_waitcnt lgkmcnt(3)
	v_mfma_f32_32x32x16_bf16 v[32:47], v[236:239], v[88:91], v[32:47]
	v_mfma_f32_32x32x16_bf16 v[0:15], v[236:239], v[92:95], v[0:15]
	s_add_i32 m0, s98, 0x2000
	v_lshl_add_u64 v[254:255], v[66:67], 0, s[100:101]
	global_load_lds_dwordx4 v[254:255], off
	v_add_u32_e32 v100, s99, v78
	ds_read_b128 v[236:239], v101 offset:20480
	s_waitcnt lgkmcnt(1)
	v_mfma_f32_32x32x16_bf16 v[48:63], v[84:87], v[240:243], v[48:63]
	v_mfma_f32_32x32x16_bf16 v[16:31], v[84:87], v[244:247], v[16:31]
	s_add_i32 m0, s98, 0x4000
	v_lshl_add_u64 v[254:255], v[68:69], 0, s[100:101]
	global_load_lds_dwordx4 v[254:255], off
	v_add_u32_e32 v101, s99, v79
	ds_read_b128 v[84:87], v101 offset:16384
	ds_read_b128 v[88:91], v100
	ds_read_b128 v[92:95], v100 offset:4096
	s_waitcnt lgkmcnt(3)
	v_mfma_f32_32x32x16_bf16 v[32:47], v[236:239], v[240:243], v[32:47]
	v_mfma_f32_32x32x16_bf16 v[0:15], v[236:239], v[244:247], v[0:15]
	s_add_i32 m0, s98, 0x6000
	v_lshl_add_u64 v[254:255], v[70:71], 0, s[100:101]
	global_load_lds_dwordx4 v[254:255], off
	v_add_u32_e32 v100, s99, v76
	ds_read_b128 v[236:239], v101 offset:20480
	s_waitcnt lgkmcnt(1)
	v_mfma_f32_32x32x16_bf16 v[48:63], v[84:87], v[88:91], v[48:63]
	v_mfma_f32_32x32x16_bf16 v[16:31], v[84:87], v[92:95], v[16:31]
	s_add_i32 m0, s98, 0x8000
	v_lshl_add_u64 v[254:255], v[72:73], 0, s[100:101]
	global_load_lds_dwordx4 v[254:255], off
	v_add_u32_e32 v101, s99, v77
	ds_read_b128 v[84:87], v101 offset:16384
	ds_read_b128 v[240:243], v100
	ds_read_b128 v[244:247], v100 offset:4096
	s_waitcnt lgkmcnt(3)
	v_mfma_f32_32x32x16_bf16 v[32:47], v[236:239], v[88:91], v[32:47]
	v_mfma_f32_32x32x16_bf16 v[0:15], v[236:239], v[92:95], v[0:15]
	s_add_i32 m0, s98, 0xa000
	v_lshl_add_u64 v[254:255], v[74:75], 0, s[100:101]
	global_load_lds_dwordx4 v[254:255], off
	ds_read_b128 v[236:239], v101 offset:20480
	s_waitcnt lgkmcnt(1)
	v_mfma_f32_32x32x16_bf16 v[48:63], v[84:87], v[240:243], v[48:63]
	v_mfma_f32_32x32x16_bf16 v[16:31], v[84:87], v[244:247], v[16:31]
	s_waitcnt vmcnt(6) lgkmcnt(0)
	s_barrier
	s_add_i32 s99, s18, 0
	v_add_u32_e32 v100, s99, v82
	v_add_u32_e32 v101, s99, v83
	ds_read_b128 v[84:87], v101 offset:16384
	ds_read_b128 v[88:91], v100
	ds_read_b128 v[92:95], v100 offset:4096
	s_waitcnt lgkmcnt(3)
	v_mfma_f32_32x32x16_bf16 v[32:47], v[236:239], v[240:243], v[32:47]
	v_mfma_f32_32x32x16_bf16 v[0:15], v[236:239], v[244:247], v[0:15]
	s_cmpk_lg_i32 s6, 0x700
	s_cbranch_scc1 .LBB0_79
; DEV int stage_next(int s) { return (s == 2 * GS_STAGE) ? 0 : s + GS_STAGE; }
; template <int WAIT0>
; DEV void gk_main(f32x16 (&acc)[2][2], const GTile& t, int s0) {
;     ...
;   vm_wait_bar<WAIT0>();
;   int stc = s0, std_ = stage_next(stage_next(s0));
; #pragma nounroll
;   for (int kt = 0; kt < nk - 2; ++kt) {
;     GK_DMA(std_, kt + 2);
;     GK_COMPUTE(stc);
;     vm_wait_bar<6>();
;     stc = stage_next(stc); std_ = stage_next(std_);
;   }
;   GK_COMPUTE(stc);
;   vm_wait_bar<0>();
;   stc = stage_next(stc);
;   GK_COMPUTE(stc);
;   vm_wait_bar<0>();
	s_waitcnt lgkmcnt(0)
	s_add_i32 s6, s18, 0
	v_add_u32_e32 v84, s6, v83
	ds_read_b128 v[64:67], v84 offset:16384
	v_add_u32_e32 v72, s6, v82
	ds_read_b128 v[68:71], v72
	ds_read_b128 v[72:75], v72 offset:4096
	s_waitcnt lgkmcnt(0)
	v_mfma_f32_32x32x16_bf16 v[48:63], v[64:67], v[68:71], v[48:63]
	v_mfma_f32_32x32x16_bf16 v[16:31], v[64:67], v[72:75], v[16:31]
	ds_read_b128 v[64:67], v84 offset:20480
	v_add_u32_e32 v84, s6, v81
	s_waitcnt lgkmcnt(0)
	v_mfma_f32_32x32x16_bf16 v[32:47], v[64:67], v[68:71], v[32:47]
	v_mfma_f32_32x32x16_bf16 v[0:15], v[64:67], v[72:75], v[0:15]
	ds_read_b128 v[64:67], v84 offset:16384
	v_add_u32_e32 v72, s6, v80
	ds_read_b128 v[68:71], v72
	ds_read_b128 v[72:75], v72 offset:4096
	s_waitcnt lgkmcnt(0)
	v_mfma_f32_32x32x16_bf16 v[48:63], v[64:67], v[68:71], v[48:63]
	v_mfma_f32_32x32x16_bf16 v[16:31], v[64:67], v[72:75], v[16:31]
	ds_read_b128 v[64:67], v84 offset:20480
	v_add_u32_e32 v84, s6, v79
	s_waitcnt lgkmcnt(0)
	v_mfma_f32_32x32x16_bf16 v[32:47], v[64:67], v[68:71], v[32:47]
	v_mfma_f32_32x32x16_bf16 v[0:15], v[64:67], v[72:75], v[0:15]
	ds_read_b128 v[64:67], v84 offset:16384
	v_add_u32_e32 v72, s6, v78
	ds_read_b128 v[68:71], v72
	ds_read_b128 v[72:75], v72 offset:4096
	s_waitcnt lgkmcnt(0)
	v_mfma_f32_32x32x16_bf16 v[48:63], v[64:67], v[68:71], v[48:63]
	v_mfma_f32_32x32x16_bf16 v[16:31], v[64:67], v[72:75], v[16:31]
	ds_read_b128 v[64:67], v84 offset:20480
	v_add_u32_e32 v84, s6, v77
	s_waitcnt lgkmcnt(0)
	v_mfma_f32_32x32x16_bf16 v[32:47], v[64:67], v[68:71], v[32:47]
	v_mfma_f32_32x32x16_bf16 v[0:15], v[64:67], v[72:75], v[0:15]
	ds_read_b128 v[64:67], v84 offset:16384
	v_add_u32_e32 v72, s6, v76
	ds_read_b128 v[68:71], v72
	ds_read_b128 v[72:75], v72 offset:4096
	s_add_i32 s6, s18, 0xc000
	s_cmp_lg_u32 s18, 0x18000
	s_cselect_b32 s6, s6, 0
	s_waitcnt lgkmcnt(0)
	v_mfma_f32_32x32x16_bf16 v[48:63], v[64:67], v[68:71], v[48:63]
	s_add_i32 s6, s6, 0
	v_add_u32_e32 v83, s6, v83
	v_add_u32_e32 v81, s6, v81
	v_add_u32_e32 v79, s6, v79
	v_add_u32_e32 v77, s6, v77
	v_mfma_f32_32x32x16_bf16 v[16:31], v[64:67], v[72:75], v[16:31]
	ds_read_b128 v[64:67], v84 offset:20480
	s_waitcnt vmcnt(0) lgkmcnt(0)
	s_barrier
	s_waitcnt lgkmcnt(0)
	v_mfma_f32_32x32x16_bf16 v[32:47], v[64:67], v[68:71], v[32:47]
	v_mfma_f32_32x32x16_bf16 v[0:15], v[64:67], v[72:75], v[0:15]
	ds_read_b128 v[64:67], v83 offset:16384
	v_add_u32_e32 v72, s6, v82
	ds_read_b128 v[68:71], v72
	ds_read_b128 v[72:75], v72 offset:4096
	s_waitcnt lgkmcnt(0)
	v_mfma_f32_32x32x16_bf16 v[48:63], v[64:67], v[68:71], v[48:63]
	v_mfma_f32_32x32x16_bf16 v[16:31], v[64:67], v[72:75], v[16:31]
	ds_read_b128 v[64:67], v83 offset:20480
	s_waitcnt lgkmcnt(0)
	v_mfma_f32_32x32x16_bf16 v[32:47], v[64:67], v[68:71], v[32:47]
	v_mfma_f32_32x32x16_bf16 v[0:15], v[64:67], v[72:75], v[0:15]
	ds_read_b128 v[64:67], v81 offset:16384
	v_add_u32_e32 v72, s6, v80
	ds_read_b128 v[68:71], v72
	ds_read_b128 v[72:75], v72 offset:4096
	s_waitcnt lgkmcnt(0)
	v_mfma_f32_32x32x16_bf16 v[48:63], v[64:67], v[68:71], v[48:63]
	v_mfma_f32_32x32x16_bf16 v[16:31], v[64:67], v[72:75], v[16:31]
	ds_read_b128 v[64:67], v81 offset:20480
	s_waitcnt lgkmcnt(0)
	v_mfma_f32_32x32x16_bf16 v[32:47], v[64:67], v[68:71], v[32:47]
	v_mfma_f32_32x32x16_bf16 v[0:15], v[64:67], v[72:75], v[0:15]
	ds_read_b128 v[64:67], v79 offset:16384
	v_add_u32_e32 v72, s6, v78
	ds_read_b128 v[68:71], v72
	ds_read_b128 v[72:75], v72 offset:4096
	s_waitcnt lgkmcnt(0)
	v_mfma_f32_32x32x16_bf16 v[48:63], v[64:67], v[68:71], v[48:63]
	v_mfma_f32_32x32x16_bf16 v[16:31], v[64:67], v[72:75], v[16:31]
	ds_read_b128 v[64:67], v79 offset:20480
	s_waitcnt lgkmcnt(0)
	v_mfma_f32_32x32x16_bf16 v[32:47], v[64:67], v[68:71], v[32:47]
	v_mfma_f32_32x32x16_bf16 v[0:15], v[64:67], v[72:75], v[0:15]
	ds_read_b128 v[64:67], v77 offset:16384
	v_add_u32_e32 v72, s6, v76
	ds_read_b128 v[68:71], v72
	ds_read_b128 v[72:75], v72 offset:4096
	s_waitcnt lgkmcnt(0)
	v_mfma_f32_32x32x16_bf16 v[48:63], v[64:67], v[68:71], v[48:63]
	v_mfma_f32_32x32x16_bf16 v[16:31], v[64:67], v[72:75], v[16:31]
	ds_read_b128 v[64:67], v77 offset:20480
	s_waitcnt vmcnt(0) lgkmcnt(0)
	s_barrier
	s_waitcnt lgkmcnt(0)
	v_mfma_f32_32x32x16_bf16 v[32:47], v[64:67], v[68:71], v[32:47]
	v_mfma_f32_32x32x16_bf16 v[0:15], v[64:67], v[72:75], v[0:15]

; DEV int stage_next(int s) { return (s == 2 * GS_STAGE) ? 0 : s + GS_STAGE; }
; template <int WAIT0>
; DEV void gk_main(f32x16 (&acc)[2][2], const GTile& t, int s0) {
;     ...
;   vm_wait_bar<WAIT0>();
;   int stc = s0, std_ = stage_next(stage_next(s0));
; #pragma nounroll
;   for (int kt = 0; kt < nk - 2; ++kt) {
;     GK_DMA(std_, kt + 2);
;     GK_COMPUTE(stc);
;     vm_wait_bar<6>();
;     stc = stage_next(stc); std_ = stage_next(std_);
;   }
.LBB0_87:
	s_add_i32 s21, s19, s20
	s_mov_b32 s98, s21
	s_mov_b64 s[100:101], s[6:7]
	v_add_u32_e32 v100, s99, v80
	s_add_i32 s21, s18, 0xc000
	s_cmp_lg_u32 s18, 0x18000
	s_cselect_b32 s18, s21, 0
	s_add_i32 s21, s20, 0xc000
	s_cmp_lg_u32 s20, 0x18000
	s_cselect_b32 s20, s21, 0
	ds_read_b128 v[236:239], v101 offset:20480
	s_waitcnt lgkmcnt(1)
	v_mfma_f32_32x32x16_bf16 v[48:63], v[84:87], v[88:91], v[48:63]
	v_mfma_f32_32x32x16_bf16 v[16:31], v[84:87], v[92:95], v[16:31]
	s_mov_b32 m0, s98
	v_lshl_add_u64 v[254:255], v[64:65], 0, s[100:101]
	global_load_lds_dwordx4 v[254:255], off
	v_add_u32_e32 v101, s99, v81
	s_add_u32 s6, s6, 0x80
	s_addc_u32 s7, s7, 0
	ds_read_b128 v[84:87], v101 offset:16384
	ds_read_b128 v[240:243], v100
	ds_read_b128 v[244:247], v100 offset:4096
	s_waitcnt lgkmcnt(3)
	v_mfma_f32_32x32x16_bf16 v[32:47], v[236:239], v[88:91], v[32:47]
	v_mfma_f32_32x32x16_bf16 v[0:15], v[236:239], v[92:95], v[0:15]
	s_add_i32 m0, s98, 0x2000
	v_lshl_add_u64 v[254:255], v[66:67], 0, s[100:101]
	global_load_lds_dwordx4 v[254:255], off
	v_add_u32_e32 v100, s99, v78
	ds_read_b128 v[236:239], v101 offset:20480
	s_waitcnt lgkmcnt(1)
	v_mfma_f32_32x32x16_bf16 v[48:63], v[84:87], v[240:243], v[48:63]
	v_mfma_f32_32x32x16_bf16 v[16:31], v[84:87], v[244:247], v[16:31]
	s_add_i32 m0, s98, 0x4000
	v_lshl_add_u64 v[254:255], v[68:69], 0, s[100:101]
	global_load_lds_dwordx4 v[254:255], off
	v_add_u32_e32 v101, s99, v79
	ds_read_b128 v[84:87], v101 offset:16384
	ds_read_b128 v[88:91], v100
	ds_read_b128 v[92:95], v100 offset:4096
	s_waitcnt lgkmcnt(3)
	v_mfma_f32_32x32x16_bf16 v[32:47], v[236:239], v[240:243], v[32:47]
	v_mfma_f32_32x32x16_bf16 v[0:15], v[236:239], v[244:247], v[0:15]
	s_add_i32 m0, s98, 0x6000
	v_lshl_add_u64 v[254:255], v[70:71], 0, s[100:101]
	global_load_lds_dwordx4 v[254:255], off
	v_add_u32_e32 v100, s99, v76
	ds_read_b128 v[236:239], v101 offset:20480
	s_waitcnt lgkmcnt(1)
	v_mfma_f32_32x32x16_bf16 v[48:63], v[84:87], v[88:91], v[48:63]
	v_mfma_f32_32x32x16_bf16 v[16:31], v[84:87], v[92:95], v[16:31]
	s_add_i32 m0, s98, 0x8000
	v_lshl_add_u64 v[254:255], v[72:73], 0, s[100:101]
	global_load_lds_dwordx4 v[254:255], off
	v_add_u32_e32 v101, s99, v77
	ds_read_b128 v[84:87], v101 offset:16384
	ds_read_b128 v[240:243], v100
	ds_read_b128 v[244:247], v100 offset:4096
	s_waitcnt lgkmcnt(3)
	v_mfma_f32_32x32x16_bf16 v[32:47], v[236:239], v[88:91], v[32:47]
	v_mfma_f32_32x32x16_bf16 v[0:15], v[236:239], v[92:95], v[0:15]
	s_add_i32 m0, s98, 0xa000
	v_lshl_add_u64 v[254:255], v[74:75], 0, s[100:101]
	global_load_lds_dwordx4 v[254:255], off
	ds_read_b128 v[236:239], v101 offset:20480
	s_waitcnt lgkmcnt(1)
	v_mfma_f32_32x32x16_bf16 v[48:63], v[84:87], v[240:243], v[48:63]
	v_mfma_f32_32x32x16_bf16 v[16:31], v[84:87], v[244:247], v[16:31]
	s_waitcnt vmcnt(6) lgkmcnt(0)
	s_barrier
	s_add_i32 s99, s18, 0
	v_add_u32_e32 v100, s99, v82
	v_add_u32_e32 v101, s99, v83
	ds_read_b128 v[84:87], v101 offset:16384
	ds_read_b128 v[88:91], v100
	ds_read_b128 v[92:95], v100 offset:4096
	s_waitcnt lgkmcnt(3)
	v_mfma_f32_32x32x16_bf16 v[32:47], v[236:239], v[240:243], v[32:47]
	v_mfma_f32_32x32x16_bf16 v[0:15], v[236:239], v[244:247], v[0:15]
	s_cmpk_lg_i32 s6, 0x700
	s_cbranch_scc1 .LBB0_87
; DEV int stage_next(int s) { return (s == 2 * GS_STAGE) ? 0 : s + GS_STAGE; }
; template <int WAIT0>
; DEV void gk_main(f32x16 (&acc)[2][2], const GTile& t, int s0) {
;     ...
;   vm_wait_bar<WAIT0>();
;   int stc = s0, std_ = stage_next(stage_next(s0));
; #pragma nounroll
;   for (int kt = 0; kt < nk - 2; ++kt) {
;     GK_DMA(std_, kt + 2);
;     GK_COMPUTE(stc);
;     vm_wait_bar<6>();
;     stc = stage_next(stc); std_ = stage_next(std_);
;   }
;   GK_COMPUTE(stc);
;   vm_wait_bar<0>();
;   stc = stage_next(stc);
;   GK_COMPUTE(stc);
;   vm_wait_bar<0>();
; template <int WAIT_E, int WAIT_O, class TileFn, class EpiFn>
; DEV void gemm_seq(int ntiles, TileFn tf, EpiFn epi) {
;     ...
;   for (int i = 0; i < ntiles; ++i) {
;     f32x16 acc[2][2]; acc_zero(acc);
;     if (i == 0) gk_main<6>(acc, cur, s0);
;     else if (i & 1) gk_main<WAIT_O>(acc, cur, s0);
;     else gk_main<WAIT_E>(acc, cur, s0);
;     const int sn = stage_next(s0);
;     if (i + 1 < ntiles) { cur = tf(i + 1); gk_issue2(cur, sn); }
;     epi(i, acc, s0);
;     s0 = sn;
;   }
	s_waitcnt lgkmcnt(0)
	s_add_i32 s6, s18, 0
	v_add_u32_e32 v84, s6, v83
	ds_read_b128 v[64:67], v84 offset:16384
	v_add_u32_e32 v72, s6, v82
	ds_read_b128 v[68:71], v72
	ds_read_b128 v[72:75], v72 offset:4096
	s_waitcnt lgkmcnt(0)
	v_mfma_f32_32x32x16_bf16 v[48:63], v[64:67], v[68:71], v[48:63]
	v_mfma_f32_32x32x16_bf16 v[16:31], v[64:67], v[72:75], v[16:31]
	ds_read_b128 v[64:67], v84 offset:20480
	v_add_u32_e32 v84, s6, v81
	s_waitcnt lgkmcnt(0)
	v_mfma_f32_32x32x16_bf16 v[32:47], v[64:67], v[68:71], v[32:47]
	v_mfma_f32_32x32x16_bf16 v[0:15], v[64:67], v[72:75], v[0:15]
	ds_read_b128 v[64:67], v84 offset:16384
	v_add_u32_e32 v72, s6, v80
	ds_read_b128 v[68:71], v72
	ds_read_b128 v[72:75], v72 offset:4096
	s_waitcnt lgkmcnt(0)
	v_mfma_f32_32x32x16_bf16 v[48:63], v[64:67], v[68:71], v[48:63]
	v_mfma_f32_32x32x16_bf16 v[16:31], v[64:67], v[72:75], v[16:31]
	ds_read_b128 v[64:67], v84 offset:20480
	v_add_u32_e32 v84, s6, v79
	s_waitcnt lgkmcnt(0)
	v_mfma_f32_32x32x16_bf16 v[32:47], v[64:67], v[68:71], v[32:47]
	v_mfma_f32_32x32x16_bf16 v[0:15], v[64:67], v[72:75], v[0:15]
	ds_read_b128 v[64:67], v84 offset:16384
	v_add_u32_e32 v72, s6, v78
	ds_read_b128 v[68:71], v72
	ds_read_b128 v[72:75], v72 offset:4096
	s_waitcnt lgkmcnt(0)
	v_mfma_f32_32x32x16_bf16 v[48:63], v[64:67], v[68:71], v[48:63]
	v_mfma_f32_32x32x16_bf16 v[16:31], v[64:67], v[72:75], v[16:31]
	ds_read_b128 v[64:67], v84 offset:20480
	v_add_u32_e32 v84, s6, v77
	s_waitcnt lgkmcnt(0)
	v_mfma_f32_32x32x16_bf16 v[32:47], v[64:67], v[68:71], v[32:47]
	v_mfma_f32_32x32x16_bf16 v[0:15], v[64:67], v[72:75], v[0:15]
	ds_read_b128 v[64:67], v84 offset:16384
	v_add_u32_e32 v72, s6, v76
	ds_read_b128 v[68:71], v72
	ds_read_b128 v[72:75], v72 offset:4096
	s_add_i32 s6, s18, 0xc000
	s_cmp_lg_u32 s18, 0x18000
	s_cselect_b32 s6, s6, 0
	s_waitcnt lgkmcnt(0)
	v_mfma_f32_32x32x16_bf16 v[48:63], v[64:67], v[68:71], v[48:63]
	s_add_i32 s6, s6, 0
	v_add_u32_e32 v83, s6, v83
	v_add_u32_e32 v81, s6, v81
	v_add_u32_e32 v79, s6, v79
	v_add_u32_e32 v77, s6, v77
	v_mfma_f32_32x32x16_bf16 v[16:31], v[64:67], v[72:75], v[16:31]
	ds_read_b128 v[64:67], v84 offset:20480
	s_waitcnt vmcnt(0) lgkmcnt(0)
	s_barrier
	s_waitcnt lgkmcnt(0)
	v_mfma_f32_32x32x16_bf16 v[32:47], v[64:67], v[68:71], v[32:47]
	v_mfma_f32_32x32x16_bf16 v[0:15], v[64:67], v[72:75], v[0:15]
	ds_read_b128 v[64:67], v83 offset:16384
	v_add_u32_e32 v72, s6, v82
	ds_read_b128 v[68:71], v72
	ds_read_b128 v[72:75], v72 offset:4096
	s_waitcnt lgkmcnt(0)
	v_mfma_f32_32x32x16_bf16 v[48:63], v[64:67], v[68:71], v[48:63]
	v_mfma_f32_32x32x16_bf16 v[16:31], v[64:67], v[72:75], v[16:31]
	ds_read_b128 v[64:67], v83 offset:20480
	s_waitcnt lgkmcnt(0)
	v_mfma_f32_32x32x16_bf16 v[32:47], v[64:67], v[68:71], v[32:47]
	v_mfma_f32_32x32x16_bf16 v[0:15], v[64:67], v[72:75], v[0:15]
	ds_read_b128 v[64:67], v81 offset:16384
	v_add_u32_e32 v72, s6, v80
	ds_read_b128 v[68:71], v72
	ds_read_b128 v[72:75], v72 offset:4096
	s_waitcnt lgkmcnt(0)
	v_mfma_f32_32x32x16_bf16 v[48:63], v[64:67], v[68:71], v[48:63]
	v_mfma_f32_32x32x16_bf16 v[16:31], v[64:67], v[72:75], v[16:31]
	ds_read_b128 v[64:67], v81 offset:20480
	s_waitcnt lgkmcnt(0)
	v_mfma_f32_32x32x16_bf16 v[32:47], v[64:67], v[68:71], v[32:47]
	v_mfma_f32_32x32x16_bf16 v[0:15], v[64:67], v[72:75], v[0:15]
	ds_read_b128 v[64:67], v79 offset:16384
	v_add_u32_e32 v72, s6, v78
	ds_read_b128 v[68:71], v72
	ds_read_b128 v[72:75], v72 offset:4096
	s_waitcnt lgkmcnt(0)
	v_mfma_f32_32x32x16_bf16 v[48:63], v[64:67], v[68:71], v[48:63]
	v_mfma_f32_32x32x16_bf16 v[16:31], v[64:67], v[72:75], v[16:31]
	ds_read_b128 v[64:67], v79 offset:20480
	s_waitcnt lgkmcnt(0)
	v_mfma_f32_32x32x16_bf16 v[32:47], v[64:67], v[68:71], v[32:47]
	v_mfma_f32_32x32x16_bf16 v[0:15], v[64:67], v[72:75], v[0:15]
	ds_read_b128 v[64:67], v77 offset:16384
	v_add_u32_e32 v72, s6, v76
	ds_read_b128 v[68:71], v72
	ds_read_b128 v[72:75], v72 offset:4096
	s_waitcnt lgkmcnt(0)
	v_mfma_f32_32x32x16_bf16 v[48:63], v[64:67], v[68:71], v[48:63]
	v_mfma_f32_32x32x16_bf16 v[16:31], v[64:67], v[72:75], v[16:31]
	ds_read_b128 v[64:67], v77 offset:20480
	s_waitcnt vmcnt(0) lgkmcnt(0)
	s_barrier
	s_waitcnt lgkmcnt(0)
	v_mfma_f32_32x32x16_bf16 v[32:47], v[64:67], v[68:71], v[32:47]
	v_mfma_f32_32x32x16_bf16 v[0:15], v[64:67], v[72:75], v[0:15]
	s_add_i32 s18, s17, 1
	s_cmp_eq_u32 s17, 11
	s_cbranch_scc1 .LBB0_83

; DEV bf16_t f2bf(float f) { return (bf16_t)(pk2(f, 0.f) & 0xffffu); }
; DEV int stage_next(int s) { return (s == 2 * GS_STAGE) ? 0 : s + GS_STAGE; }
; #define FOR_ACC _Pragma("unroll") for (int nb = 0; nb < 2; ++nb) _Pragma("unroll") for (int mb = 0; mb < 2; ++mb) _Pragma("unroll") for (int rq = 0; rq < 4; ++rq)
; template <int WAIT0>
; DEV void gk_main(f32x16 (&acc)[2][2], const GTile& t, int s0) {
;     ...
;   vm_wait_bar<WAIT0>();
;   int stc = s0, std_ = stage_next(stage_next(s0));
; #pragma nounroll
;   for (int kt = 0; kt < nk - 2; ++kt) {
;     GK_DMA(std_, kt + 2);
;     GK_COMPUTE(stc);
;     vm_wait_bar<6>();
;     stc = stage_next(stc); std_ = stage_next(std_);
;   }
;   GK_COMPUTE(stc);
;   vm_wait_bar<0>();
;   stc = stage_next(stc);
;   GK_COMPUTE(stc);
;   vm_wait_bar<0>();
; DEV void fold_unit(const Params& P, int u) {
;     ...
;   gemm_seq<6, 6>(1, [&](int) { return GTile{A, 2048, Bt, 256, 256}; }, [&](int, f32x16 (&acc)[2][2], int) {
;     FOR_ACC {
;       const int j = jt * 128 + 64 * wm + 32 * mb + l32, n = 64 * wn + 32 * nb + 8 * rq + 4 * hi;
; #pragma unroll
;       for (int e = 0; e < 4; ++e) wpt[((size_t)l * 2048 + hh * 256 + n + e) * 1024 + j] = f2bf(acc[nb][mb][4 * rq + e]);
;     }
.LBB0_96:
	s_add_i32 s39, s38, s24
	s_mov_b32 s98, s39
	s_mov_b64 s[100:101], s[22:23]
	v_add_u32_e32 v108, s99, v87
	v_add_u32_e32 v91, s99, v86
	s_add_i32 s39, s25, 0xc000
	s_cmp_lg_u32 s25, 0x18000
	s_cselect_b32 s25, s39, 0
	s_add_i32 s39, s24, 0xc000
	s_cmp_lg_u32 s24, 0x18000
	s_cselect_b32 s24, s39, 0
	s_add_u32 s22, s22, 0x80
	s_addc_u32 s23, s23, 0
	ds_read_b128 v[236:239], v108 offset:16384
	ds_read_b128 v[240:243], v91
	ds_read_b128 v[244:247], v91 offset:4096
	ds_read_b128 v[248:251], v108 offset:20480
	s_waitcnt lgkmcnt(4)
	v_mfma_f32_32x32x16_bf16 v[48:63], v[92:95], v[96:99], v[48:63]
	v_mfma_f32_32x32x16_bf16 v[32:47], v[92:95], v[100:103], v[32:47]
	s_mov_b32 m0, s98
	v_lshl_add_u64 v[254:255], v[64:65], 0, s[100:101]
	global_load_lds_dwordx4 v[254:255], off
	v_mfma_f32_32x32x16_bf16 v[16:31], v[104:107], v[96:99], v[16:31]
	v_mfma_f32_32x32x16_bf16 v[0:15], v[104:107], v[100:103], v[0:15]
	s_add_i32 m0, s98, 0x2000
	v_lshl_add_u64 v[254:255], v[66:67], 0, s[100:101]
	global_load_lds_dwordx4 v[254:255], off
	v_add_u32_e32 v108, s99, v85
	v_add_u32_e32 v91, s99, v84
	ds_read_b128 v[92:95], v108 offset:16384
	ds_read_b128 v[96:99], v91
	ds_read_b128 v[100:103], v91 offset:4096
	ds_read_b128 v[104:107], v108 offset:20480
	s_waitcnt lgkmcnt(4)
	v_mfma_f32_32x32x16_bf16 v[48:63], v[236:239], v[240:243], v[48:63]
	v_mfma_f32_32x32x16_bf16 v[32:47], v[236:239], v[244:247], v[32:47]
	s_add_i32 m0, s98, 0x4000
	v_lshl_add_u64 v[254:255], v[68:69], 0, s[100:101]
	global_load_lds_dwordx4 v[254:255], off
	v_mfma_f32_32x32x16_bf16 v[16:31], v[248:251], v[240:243], v[16:31]
	v_mfma_f32_32x32x16_bf16 v[0:15], v[248:251], v[244:247], v[0:15]
	s_add_i32 m0, s98, 0x6000
	v_lshl_add_u64 v[254:255], v[70:71], 0, s[100:101]
	global_load_lds_dwordx4 v[254:255], off
	v_add_u32_e32 v108, s99, v83
	v_add_u32_e32 v91, s99, v80
	ds_read_b128 v[236:239], v108 offset:16384
	ds_read_b128 v[240:243], v91
	ds_read_b128 v[244:247], v91 offset:4096
	ds_read_b128 v[248:251], v108 offset:20480
	s_waitcnt lgkmcnt(4)
	v_mfma_f32_32x32x16_bf16 v[48:63], v[92:95], v[96:99], v[48:63]
	v_mfma_f32_32x32x16_bf16 v[32:47], v[92:95], v[100:103], v[32:47]
	s_add_i32 m0, s98, 0x8000
	v_lshl_add_u64 v[254:255], v[72:73], 0, s[100:101]
	global_load_lds_dwordx4 v[254:255], off
	v_mfma_f32_32x32x16_bf16 v[16:31], v[104:107], v[96:99], v[16:31]
	v_mfma_f32_32x32x16_bf16 v[0:15], v[104:107], v[100:103], v[0:15]
	s_add_i32 m0, s98, 0xa000
	v_lshl_add_u64 v[254:255], v[74:75], 0, s[100:101]
	global_load_lds_dwordx4 v[254:255], off
	s_waitcnt vmcnt(6) lgkmcnt(0)
	s_barrier
	s_add_i32 s99, s25, 0
	v_add_u32_e32 v252, s99, v89
	v_add_u32_e32 v91, s99, v88
	ds_read_b128 v[92:95], v252 offset:16384
	ds_read_b128 v[96:99], v91
	ds_read_b128 v[100:103], v91 offset:4096
	ds_read_b128 v[104:107], v252 offset:20480
	s_waitcnt lgkmcnt(4)
	v_mfma_f32_32x32x16_bf16 v[48:63], v[236:239], v[240:243], v[48:63]
	v_mfma_f32_32x32x16_bf16 v[32:47], v[236:239], v[244:247], v[32:47]
	v_mfma_f32_32x32x16_bf16 v[16:31], v[248:251], v[240:243], v[16:31]
	v_mfma_f32_32x32x16_bf16 v[0:15], v[248:251], v[244:247], v[0:15]
	s_cmpk_lg_i32 s22, 0x100
	s_cbranch_scc1 .LBB0_96
	s_waitcnt lgkmcnt(0)
	v_add_u32_e32 v72, 0x4000, v79
	v_or_b32_e32 v64, v72, v90
	v_add_u32_e32 v73, s35, v64
	ds_read_b128 v[64:67], v73
	v_add_u32_e32 v74, s35, v88
	ds_read_b128 v[68:71], v74
	ds_read_b128 v[90:93], v74 offset:4096
	ds_read_b128 v[94:97], v73 offset:4096
	v_or_b32_e32 v73, v72, v76
	v_or_b32_e32 v74, v72, v77
	s_waitcnt lgkmcnt(0)
	v_mfma_f32_32x32x16_bf16 v[16:31], v[94:97], v[68:71], v[16:31]
	v_or_b32_e32 v76, v72, v78
	v_add_u32_e32 v72, s35, v80
	v_add_u32_e32 v76, s35, v76
	v_add_u32_e32 v88, 0, v88
	v_add_u32_e32 v154, 0, v87
	v_add_u32_e32 v80, 0, v80
	s_lshl_b64 s[20:21], s[20:21], 11
	v_mfma_f32_32x32x16_bf16 v[48:63], v[64:67], v[68:71], v[48:63]
	v_add_u32_e32 v68, s35, v74
	s_or_b64 s[20:21], s[20:21], s[8:9]
	s_add_i32 s36, s36, s86
	s_add_i32 s30, s30, s31
	s_add_i32 s33, s33, s34
	s_cmpk_gt_i32 s36, 0x7f
	v_mfma_f32_32x32x16_bf16 v[32:47], v[64:67], v[90:93], v[32:47]
	v_add_u32_e32 v64, s35, v86
	ds_read_b128 v[98:101], v64
	ds_read_b128 v[102:105], v64 offset:4096
	v_add_u32_e32 v64, s35, v73
	ds_read_b128 v[106:109], v64
	ds_read_b128 v[110:113], v64 offset:4096
	v_add_u32_e32 v64, s35, v84
	ds_read_b128 v[114:117], v64
	ds_read_b128 v[64:67], v64 offset:4096
	ds_read_b128 v[118:121], v68
	ds_read_b128 v[68:71], v68 offset:4096
	s_waitcnt lgkmcnt(0)
	v_mfma_f32_32x32x16_bf16 v[48:63], v[106:109], v[98:101], v[48:63]
	ds_read_b128 v[122:125], v72
	ds_read_b128 v[72:75], v72 offset:4096
	ds_read_b128 v[126:129], v76
	ds_read_b128 v[76:79], v76 offset:4096
	s_waitcnt vmcnt(0) lgkmcnt(0)
	s_barrier
	ds_read_b128 v[130:133], v88
	ds_read_b128 v[134:137], v88 offset:4096
	v_add_u32_e32 v88, 0, v89
	v_mfma_f32_32x32x16_bf16 v[48:63], v[118:121], v[114:117], v[48:63]
	ds_read_b128 v[138:141], v88 offset:16384
	ds_read_b128 v[142:145], v88 offset:20480
	v_add_u32_e32 v86, 0, v86
	ds_read_b128 v[146:149], v86
	ds_read_b128 v[150:153], v86 offset:4096
	ds_read_b128 v[86:89], v154 offset:16384
	ds_read_b128 v[154:157], v154 offset:20480
	v_add_u32_e32 v84, 0, v84
	ds_read_b128 v[158:161], v84
	ds_read_b128 v[162:165], v84 offset:4096
	v_add_u32_e32 v84, 0, v85
	s_waitcnt lgkmcnt(0)
	v_mfma_f32_32x32x16_bf16 v[48:63], v[126:129], v[122:125], v[48:63]
	ds_read_b128 v[166:169], v84 offset:16384
	ds_read_b128 v[170:173], v84 offset:20480
	ds_read_b128 v[182:185], v80
	ds_read_b128 v[186:189], v80 offset:4096
	v_add_u32_e32 v80, 0, v83
	ds_read_b128 v[190:193], v80 offset:16384
	ds_read_b128 v[194:197], v80 offset:20480
	v_ashrrev_i32_e32 v83, 1, v82
	v_and_b32_e32 v80, 0x5f, v82
	v_and_b32_e32 v83, 0xffffffc0, v83
	v_mfma_f32_32x32x16_bf16 v[48:63], v[138:141], v[130:133], v[48:63]
	v_lshrrev_b32_e32 v82, 3, v82
	v_and_or_b32 v84, v82, 4, v83
	v_or_b32_e32 v80, s37, v80
	v_ashrrev_i32_e32 v85, 31, v84
	v_lshlrev_b32_e32 v80, 1, v80
	v_lshl_add_u64 v[174:175], s[20:21], 0, v[84:85]
	v_lshl_add_u64 v[82:83], s[2:3], 0, v[80:81]
	v_mfma_f32_32x32x16_bf16 v[32:47], v[106:109], v[102:105], v[32:47]
	v_lshlrev_b64 v[174:175], 11, v[174:175]
	v_lshl_add_u64 v[198:199], v[82:83], 0, v[174:175]
	s_waitcnt vmcnt(0) lgkmcnt(0)
	s_barrier
; DEV bf16_t f2bf(float f) { return (bf16_t)(pk2(f, 0.f) & 0xffffu); }
; DEV int stage_next(int s) { return (s == 2 * GS_STAGE) ? 0 : s + GS_STAGE; }
; #define FOR_ACC _Pragma("unroll") for (int nb = 0; nb < 2; ++nb) _Pragma("unroll") for (int mb = 0; mb < 2; ++mb) _Pragma("unroll") for (int rq = 0; rq < 4; ++rq)
; template <int WAIT0>
; DEV void gk_main(f32x16 (&acc)[2][2], const GTile& t, int s0) {
;     ...
;   GK_COMPUTE(stc);
;   vm_wait_bar<0>();
;   stc = stage_next(stc);
;   GK_COMPUTE(stc);
;   vm_wait_bar<0>();
; DEV void fold_unit(const Params& P, int u) {
;     ...
;   gemm_seq<6, 6>(1, [&](int) { return GTile{A, 2048, Bt, 256, 256}; }, [&](int, f32x16 (&acc)[2][2], int) {
;     FOR_ACC {
;       const int j = jt * 128 + 64 * wm + 32 * mb + l32, n = 64 * wn + 32 * nb + 8 * rq + 4 * hi;
; #pragma unroll
;       for (int e = 0; e < 4; ++e) wpt[((size_t)l * 2048 + hh * 256 + n + e) * 1024 + j] = f2bf(acc[nb][mb][4 * rq + e]);
;     }
	v_mfma_f32_32x32x16_bf16 v[48:63], v[86:89], v[146:149], v[48:63]
	v_mfma_f32_32x32x16_bf16 v[32:47], v[118:121], v[64:67], v[32:47]
	s_waitcnt lgkmcnt(0)
	v_mfma_f32_32x32x16_bf16 v[48:63], v[166:169], v[158:161], v[48:63]
	v_mfma_f32_32x32x16_bf16 v[32:47], v[126:129], v[72:75], v[32:47]
	v_mfma_f32_32x32x16_bf16 v[48:63], v[190:193], v[182:185], v[48:63]
	v_mfma_f32_32x32x16_bf16 v[16:31], v[110:113], v[98:101], v[16:31]
	s_nop 10
	v_cvt_pk_bf16_f32 v48, v48, s0
	global_store_short v[198:199], v48, off
	v_cvt_pk_bf16_f32 v48, v49, s0
	global_store_short v[198:199], v48, off offset:2048
	v_or_b32_e32 v48, 0x1000, v174
	v_mov_b32_e32 v49, v175
	v_cvt_pk_bf16_f32 v50, v50, s0
	v_mfma_f32_32x32x16_bf16 v[32:47], v[138:141], v[134:137], v[32:47]
	v_or_b32_e32 v174, 0x1800, v174
	v_cvt_pk_bf16_f32 v80, v51, s0
	v_cvt_pk_bf16_f32 v52, v52, s0
	v_cvt_pk_bf16_f32 v54, v54, s0
	v_cvt_pk_bf16_f32 v56, v56, s0
	v_cvt_pk_bf16_f32 v58, v58, s0
	v_cvt_pk_bf16_f32 v60, v60, s0
	v_mfma_f32_32x32x16_bf16 v[16:31], v[68:71], v[114:117], v[16:31]
	v_cvt_pk_bf16_f32 v62, v62, s0
	v_mfma_f32_32x32x16_bf16 v[0:15], v[94:97], v[90:93], v[0:15]
	v_lshl_add_u64 v[90:91], v[82:83], 0, v[48:49]
	global_store_short v[90:91], v50, off
	v_lshl_add_u64 v[50:51], v[82:83], 0, v[174:175]
	global_store_short v[50:51], v80, off
	v_or_b32_e32 v50, 8, v84
	v_ashrrev_i32_e32 v51, 31, v50
	v_lshl_add_u64 v[50:51], s[20:21], 0, v[50:51]
	v_mfma_f32_32x32x16_bf16 v[32:47], v[86:89], v[150:153], v[32:47]
	v_lshlrev_b64 v[50:51], 11, v[50:51]
	v_lshl_add_u64 v[90:91], v[82:83], 0, v[50:51]
	global_store_short v[90:91], v52, off
	v_cvt_pk_bf16_f32 v80, v53, s0
	v_or_b32_e32 v52, 0x800, v50
	v_mov_b32_e32 v53, v51
	v_or_b32_e32 v92, 0x1000, v50
	v_mfma_f32_32x32x16_bf16 v[16:31], v[76:79], v[122:125], v[16:31]
	v_mov_b32_e32 v93, v51
	v_lshl_add_u64 v[52:53], v[82:83], 0, v[52:53]
	v_lshl_add_u64 v[92:93], v[82:83], 0, v[92:93]
	v_or_b32_e32 v50, 0x1800, v50
	global_store_short v[52:53], v80, off
	global_store_short v[92:93], v54, off
	v_cvt_pk_bf16_f32 v54, v55, s0
	v_lshl_add_u64 v[50:51], v[82:83], 0, v[50:51]
	v_mfma_f32_32x32x16_bf16 v[32:47], v[166:169], v[162:165], v[32:47]
	global_store_short v[50:51], v54, off
	v_or_b32_e32 v54, 16, v84
	v_ashrrev_i32_e32 v55, 31, v54
	v_lshl_add_u64 v[54:55], s[20:21], 0, v[54:55]
	v_lshlrev_b64 v[54:55], 11, v[54:55]
	v_lshl_add_u64 v[94:95], v[82:83], 0, v[54:55]
	global_store_short v[94:95], v56, off
	v_mfma_f32_32x32x16_bf16 v[16:31], v[142:145], v[130:133], v[16:31]
	v_cvt_pk_bf16_f32 v80, v57, s0
	v_or_b32_e32 v56, 0x800, v54
	v_mov_b32_e32 v57, v55
	v_or_b32_e32 v96, 0x1000, v54
	v_mov_b32_e32 v97, v55
	v_lshl_add_u64 v[56:57], v[82:83], 0, v[56:57]
	v_lshl_add_u64 v[96:97], v[82:83], 0, v[96:97]
	v_or_b32_e32 v54, 0x1800, v54
	global_store_short v[56:57], v80, off
	global_store_short v[96:97], v58, off
	v_cvt_pk_bf16_f32 v58, v59, s0
	v_lshl_add_u64 v[54:55], v[82:83], 0, v[54:55]
	v_mfma_f32_32x32x16_bf16 v[32:47], v[190:193], v[186:189], v[32:47]
	global_store_short v[54:55], v58, off
	v_or_b32_e32 v58, 24, v84
	v_ashrrev_i32_e32 v59, 31, v58
	v_lshl_add_u64 v[58:59], s[20:21], 0, v[58:59]
	v_lshlrev_b64 v[58:59], 11, v[58:59]
	v_lshl_add_u64 v[86:87], v[82:83], 0, v[58:59]
	global_store_short v[86:87], v60, off
	v_mfma_f32_32x32x16_bf16 v[0:15], v[110:113], v[102:105], v[0:15]
	v_cvt_pk_bf16_f32 v80, v61, s0
	v_or_b32_e32 v60, 0x800, v58
	v_mov_b32_e32 v61, v59
	v_or_b32_e32 v88, 0x1000, v58
	v_mov_b32_e32 v89, v59
	v_lshl_add_u64 v[60:61], v[82:83], 0, v[60:61]
	v_lshl_add_u64 v[88:89], v[82:83], 0, v[88:89]
	v_mfma_f32_32x32x16_bf16 v[16:31], v[154:157], v[146:149], v[16:31]
	v_or_b32_e32 v58, 0x1800, v58
	global_store_short v[60:61], v80, off
	global_store_short v[88:89], v62, off
	v_cvt_pk_bf16_f32 v62, v63, s0
	v_lshl_add_u64 v[58:59], v[82:83], 0, v[58:59]
	v_cvt_pk_bf16_f32 v32, v32, s0
	global_store_short v[58:59], v62, off
	v_lshl_add_u64 v[62:63], v[82:83], 0, 64
	global_store_short v[198:199], v32, off offset:64
	v_cvt_pk_bf16_f32 v32, v33, s0
	global_store_short v[198:199], v32, off offset:2112
	v_cvt_pk_bf16_f32 v34, v34, s0
	v_lshl_add_u64 v[32:33], v[62:63], 0, v[48:49]
	global_store_short v[32:33], v34, off
	v_cvt_pk_bf16_f32 v34, v35, s0
	v_lshl_add_u64 v[32:33], v[62:63], 0, v[174:175]
	global_store_short v[32:33], v34, off
	v_cvt_pk_bf16_f32 v32, v36, s0
	v_mfma_f32_32x32x16_bf16 v[16:31], v[170:173], v[158:161], v[16:31]
	global_store_short v[90:91], v32, off offset:64
	v_cvt_pk_bf16_f32 v32, v37, s0
	global_store_short v[52:53], v32, off offset:64
	v_cvt_pk_bf16_f32 v32, v38, s0
	global_store_short v[92:93], v32, off offset:64
	v_cvt_pk_bf16_f32 v32, v39, s0
	global_store_short v[50:51], v32, off offset:64
	v_mfma_f32_32x32x16_bf16 v[0:15], v[68:71], v[64:67], v[0:15]
	v_cvt_pk_bf16_f32 v32, v40, s0
	global_store_short v[94:95], v32, off offset:64
	v_cvt_pk_bf16_f32 v32, v41, s0
	global_store_short v[56:57], v32, off offset:64
	v_cvt_pk_bf16_f32 v32, v42, s0
	global_store_short v[96:97], v32, off offset:64
	v_cvt_pk_bf16_f32 v32, v43, s0
	global_store_short v[54:55], v32, off offset:64
; DEV bf16_t f2bf(float f) { return (bf16_t)(pk2(f, 0.f) & 0xffffu); }
; #define FOR_ACC _Pragma("unroll") for (int nb = 0; nb < 2; ++nb) _Pragma("unroll") for (int mb = 0; mb < 2; ++mb) _Pragma("unroll") for (int rq = 0; rq < 4; ++rq)
; DEV void fold_unit(const Params& P, int u) {
;     ...
;   gemm_seq<6, 6>(1, [&](int) { return GTile{A, 2048, Bt, 256, 256}; }, [&](int, f32x16 (&acc)[2][2], int) {
;     FOR_ACC {
;       const int j = jt * 128 + 64 * wm + 32 * mb + l32, n = 64 * wn + 32 * nb + 8 * rq + 4 * hi;
; #pragma unroll
;       for (int e = 0; e < 4; ++e) wpt[((size_t)l * 2048 + hh * 256 + n + e) * 1024 + j] = f2bf(acc[nb][mb][4 * rq + e]);
;     }
; __global__ void __launch_bounds__(512) mega(Params P) {
;     ...
;   for (int u = blockIdx.x; u < 128; u += gridDim.x) { asm volatile("" ::: "memory"); fold_unit(P, u); }
	v_cvt_pk_bf16_f32 v32, v44, s0
	v_mfma_f32_32x32x16_bf16 v[16:31], v[194:197], v[182:185], v[16:31]
	global_store_short v[86:87], v32, off offset:64
	v_cvt_pk_bf16_f32 v32, v45, s0
	global_store_short v[60:61], v32, off offset:64
	v_cvt_pk_bf16_f32 v32, v46, s0
	global_store_short v[88:89], v32, off offset:64
	v_cvt_pk_bf16_f32 v32, v47, s0
	global_store_short v[58:59], v32, off offset:64
	v_mfma_f32_32x32x16_bf16 v[0:15], v[76:79], v[72:75], v[0:15]
	v_or_b32_e32 v32, 32, v84
	v_ashrrev_i32_e32 v33, 31, v32
	v_lshl_add_u64 v[32:33], s[20:21], 0, v[32:33]
	v_lshlrev_b64 v[32:33], 11, v[32:33]
	v_cvt_pk_bf16_f32 v16, v16, s0
	v_lshl_add_u64 v[34:35], v[82:83], 0, v[32:33]
	global_store_short v[34:35], v16, off
	v_mfma_f32_32x32x16_bf16 v[0:15], v[142:145], v[134:137], v[0:15]
	v_cvt_pk_bf16_f32 v36, v17, s0
	v_or_b32_e32 v16, 0x800, v32
	v_mov_b32_e32 v17, v33
	v_lshl_add_u64 v[16:17], v[82:83], 0, v[16:17]
	global_store_short v[16:17], v36, off
	v_or_b32_e32 v36, 0x1000, v32
	v_mov_b32_e32 v37, v33
	v_cvt_pk_bf16_f32 v18, v18, s0
	v_lshl_add_u64 v[36:37], v[82:83], 0, v[36:37]
	v_or_b32_e32 v32, 0x1800, v32
	global_store_short v[36:37], v18, off
	v_cvt_pk_bf16_f32 v38, v19, s0
	v_lshl_add_u64 v[18:19], v[82:83], 0, v[32:33]
	v_or_b32_e32 v32, 40, v84
	v_ashrrev_i32_e32 v33, 31, v32
	v_lshl_add_u64 v[32:33], s[20:21], 0, v[32:33]
	v_mfma_f32_32x32x16_bf16 v[0:15], v[154:157], v[150:153], v[0:15]
	v_lshlrev_b64 v[32:33], 11, v[32:33]
	global_store_short v[18:19], v38, off
	v_cvt_pk_bf16_f32 v20, v20, s0
	v_lshl_add_u64 v[38:39], v[82:83], 0, v[32:33]
	global_store_short v[38:39], v20, off
	v_cvt_pk_bf16_f32 v40, v21, s0
	v_or_b32_e32 v20, 0x800, v32
	v_mov_b32_e32 v21, v33
	v_lshl_add_u64 v[20:21], v[82:83], 0, v[20:21]
	global_store_short v[20:21], v40, off
	v_or_b32_e32 v40, 0x1000, v32
	v_mov_b32_e32 v41, v33
	v_cvt_pk_bf16_f32 v22, v22, s0
	v_lshl_add_u64 v[40:41], v[82:83], 0, v[40:41]
	v_or_b32_e32 v32, 0x1800, v32
	global_store_short v[40:41], v22, off
	v_cvt_pk_bf16_f32 v42, v23, s0
	v_lshl_add_u64 v[22:23], v[82:83], 0, v[32:33]
	v_or_b32_e32 v32, 48, v84
	v_ashrrev_i32_e32 v33, 31, v32
	v_mfma_f32_32x32x16_bf16 v[0:15], v[170:173], v[162:165], v[0:15]
	v_lshl_add_u64 v[32:33], s[20:21], 0, v[32:33]
	v_lshlrev_b64 v[32:33], 11, v[32:33]
	global_store_short v[22:23], v42, off
	v_cvt_pk_bf16_f32 v24, v24, s0
	v_lshl_add_u64 v[42:43], v[82:83], 0, v[32:33]
	global_store_short v[42:43], v24, off
	v_cvt_pk_bf16_f32 v44, v25, s0
	v_or_b32_e32 v24, 0x800, v32
	v_mov_b32_e32 v25, v33
	v_lshl_add_u64 v[24:25], v[82:83], 0, v[24:25]
	global_store_short v[24:25], v44, off
	v_or_b32_e32 v44, 0x1000, v32
	v_mov_b32_e32 v45, v33
	v_cvt_pk_bf16_f32 v26, v26, s0
	v_lshl_add_u64 v[44:45], v[82:83], 0, v[44:45]
	v_or_b32_e32 v32, 0x1800, v32
	global_store_short v[44:45], v26, off
	v_cvt_pk_bf16_f32 v46, v27, s0
	v_lshl_add_u64 v[26:27], v[82:83], 0, v[32:33]
	v_or_b32_e32 v32, 56, v84
	v_mfma_f32_32x32x16_bf16 v[0:15], v[194:197], v[186:189], v[0:15]
	v_ashrrev_i32_e32 v33, 31, v32
	v_lshl_add_u64 v[32:33], s[20:21], 0, v[32:33]
	v_lshlrev_b64 v[32:33], 11, v[32:33]
	global_store_short v[26:27], v46, off
	v_cvt_pk_bf16_f32 v28, v28, s0
	v_lshl_add_u64 v[46:47], v[82:83], 0, v[32:33]
	global_store_short v[46:47], v28, off
	v_cvt_pk_bf16_f32 v48, v29, s0
	v_or_b32_e32 v28, 0x800, v32
	v_mov_b32_e32 v29, v33
	v_lshl_add_u64 v[28:29], v[82:83], 0, v[28:29]
	global_store_short v[28:29], v48, off
	v_or_b32_e32 v48, 0x1000, v32
	v_mov_b32_e32 v49, v33
	v_cvt_pk_bf16_f32 v30, v30, s0
	v_lshl_add_u64 v[48:49], v[82:83], 0, v[48:49]
	v_or_b32_e32 v32, 0x1800, v32
	global_store_short v[48:49], v30, off
	v_cvt_pk_bf16_f32 v50, v31, s0
	v_lshl_add_u64 v[30:31], v[82:83], 0, v[32:33]
	v_cvt_pk_bf16_f32 v0, v0, s0
	global_store_short v[30:31], v50, off
	global_store_short v[34:35], v0, off offset:64
	v_cvt_pk_bf16_f32 v0, v1, s0
	global_store_short v[16:17], v0, off offset:64
	v_cvt_pk_bf16_f32 v0, v2, s0
	global_store_short v[36:37], v0, off offset:64
	v_cvt_pk_bf16_f32 v0, v3, s0
	global_store_short v[18:19], v0, off offset:64
	v_cvt_pk_bf16_f32 v0, v4, s0
	global_store_short v[38:39], v0, off offset:64
	v_cvt_pk_bf16_f32 v0, v5, s0
	global_store_short v[20:21], v0, off offset:64
	v_cvt_pk_bf16_f32 v0, v6, s0
	global_store_short v[40:41], v0, off offset:64
	v_cvt_pk_bf16_f32 v0, v7, s0
	global_store_short v[22:23], v0, off offset:64
	v_cvt_pk_bf16_f32 v0, v8, s0
	global_store_short v[42:43], v0, off offset:64
	v_cvt_pk_bf16_f32 v0, v9, s0
	global_store_short v[24:25], v0, off offset:64
	v_cvt_pk_bf16_f32 v0, v10, s0
	global_store_short v[44:45], v0, off offset:64
	v_cvt_pk_bf16_f32 v0, v11, s0
	global_store_short v[26:27], v0, off offset:64
	v_cvt_pk_bf16_f32 v0, v12, s0
	global_store_short v[46:47], v0, off offset:64
	v_cvt_pk_bf16_f32 v0, v13, s0
	global_store_short v[28:29], v0, off offset:64
	v_cvt_pk_bf16_f32 v0, v14, s0
	global_store_short v[48:49], v0, off offset:64
	v_cvt_pk_bf16_f32 v0, v15, s0
	global_store_short v[30:31], v0, off offset:64
	s_waitcnt vmcnt(0)
	s_cbranch_scc0 .LBB0_95

; DEV int stage_next(int s) { return (s == 2 * GS_STAGE) ? 0 : s + GS_STAGE; }
; template <int WAIT0>
; DEV void gk_main(f32x16 (&acc)[2][2], const GTile& t, int s0) {
;     ...
;   vm_wait_bar<WAIT0>();
;   int stc = s0, std_ = stage_next(stage_next(s0));
; #pragma nounroll
;   for (int kt = 0; kt < nk - 2; ++kt) {
;     GK_DMA(std_, kt + 2);
;     GK_COMPUTE(stc);
;     vm_wait_bar<6>();
;     stc = stage_next(stc); std_ = stage_next(std_);
;   }
.LBB0_276:
	s_add_i32 s12, s10, s11
	s_mov_b32 s98, s12
	s_mov_b64 s[100:101], s[6:7]
	v_add_u32_e32 v252, s99, v80
	v_add_u32_e32 v253, s99, v81
	ds_read_b128 v[236:239], v252
	ds_read_b128 v[240:243], v252 offset:4096
	ds_read_b128 v[244:247], v253 offset:16384
	ds_read_b128 v[248:251], v253 offset:20480
	s_waitcnt lgkmcnt(4)
	v_mfma_f32_32x32x16_bf16 v[48:63], v[92:95], v[84:87], v[48:63]
	v_mfma_f32_32x32x16_bf16 v[16:31], v[92:95], v[88:91], v[16:31]
	s_mov_b32 m0, s98
	v_lshl_add_u64 v[254:255], v[74:75], 0, s[100:101]
	global_load_lds_dwordx4 v[254:255], off
	v_mfma_f32_32x32x16_bf16 v[32:47], v[96:99], v[84:87], v[32:47]
	v_mfma_f32_32x32x16_bf16 v[0:15], v[96:99], v[88:91], v[0:15]
	s_add_i32 m0, s98, 0x2000
	v_lshl_add_u64 v[254:255], v[72:73], 0, s[100:101]
	global_load_lds_dwordx4 v[254:255], off
	v_add_u32_e32 v252, s99, v78
	v_add_u32_e32 v253, s99, v79
	ds_read_b128 v[84:87], v252
	ds_read_b128 v[88:91], v252 offset:4096
	ds_read_b128 v[92:95], v253 offset:16384
	ds_read_b128 v[96:99], v253 offset:20480
	s_waitcnt lgkmcnt(4)
	v_mfma_f32_32x32x16_bf16 v[48:63], v[244:247], v[236:239], v[48:63]
	v_mfma_f32_32x32x16_bf16 v[16:31], v[244:247], v[240:243], v[16:31]
	s_add_i32 m0, s98, 0x4000
	v_lshl_add_u64 v[254:255], v[70:71], 0, s[100:101]
	global_load_lds_dwordx4 v[254:255], off
	v_mfma_f32_32x32x16_bf16 v[32:47], v[248:251], v[236:239], v[32:47]
	v_mfma_f32_32x32x16_bf16 v[0:15], v[248:251], v[240:243], v[0:15]
	s_add_i32 m0, s98, 0x6000
	v_lshl_add_u64 v[254:255], v[68:69], 0, s[100:101]
	global_load_lds_dwordx4 v[254:255], off
	v_add_u32_e32 v252, s99, v76
	v_add_u32_e32 v253, s99, v77
	ds_read_b128 v[236:239], v252
	ds_read_b128 v[240:243], v252 offset:4096
	ds_read_b128 v[244:247], v253 offset:16384
	ds_read_b128 v[248:251], v253 offset:20480
	s_waitcnt lgkmcnt(4)
	v_mfma_f32_32x32x16_bf16 v[48:63], v[92:95], v[84:87], v[48:63]
	v_mfma_f32_32x32x16_bf16 v[16:31], v[92:95], v[88:91], v[16:31]
	s_add_i32 m0, s98, 0x8000
	v_lshl_add_u64 v[254:255], v[66:67], 0, s[100:101]
	global_load_lds_dwordx4 v[254:255], off
	v_mfma_f32_32x32x16_bf16 v[32:47], v[96:99], v[84:87], v[32:47]
	v_mfma_f32_32x32x16_bf16 v[0:15], v[96:99], v[88:91], v[0:15]
	s_add_i32 m0, s98, 0xa000
	v_lshl_add_u64 v[254:255], v[64:65], 0, s[100:101]
	global_load_lds_dwordx4 v[254:255], off
	s_add_i32 s12, s3, 0xc000
	s_cmp_lg_u32 s3, 0x18000
	s_cselect_b32 s3, s12, 0
	s_waitcnt lgkmcnt(0)
	v_mfma_f32_32x32x16_bf16 v[48:63], v[244:247], v[236:239], v[48:63]
	s_add_i32 s12, s11, 0xc000
	s_cmp_lg_u32 s11, 0x18000
	s_waitcnt vmcnt(6) lgkmcnt(0)
	s_barrier
	s_cselect_b32 s11, s12, 0
	s_add_u32 s6, s6, 0x80
	s_add_i32 s99, s3, 0
	v_add_u32_e32 v252, s99, v82
	v_add_u32_e32 v253, s99, v83
	ds_read_b128 v[84:87], v252
	ds_read_b128 v[88:91], v252 offset:4096
	ds_read_b128 v[92:95], v253 offset:16384
	ds_read_b128 v[96:99], v253 offset:20480
	v_mfma_f32_32x32x16_bf16 v[16:31], v[244:247], v[240:243], v[16:31]
	s_addc_u32 s7, s7, 0
	s_cmpk_lg_i32 s6, 0x700
	v_mfma_f32_32x32x16_bf16 v[32:47], v[248:251], v[236:239], v[32:47]
	v_mfma_f32_32x32x16_bf16 v[0:15], v[248:251], v[240:243], v[0:15]
	s_cbranch_scc1 .LBB0_276
; DEV int stage_next(int s) { return (s == 2 * GS_STAGE) ? 0 : s + GS_STAGE; }
; template <int WAIT0>
; DEV void gk_main(f32x16 (&acc)[2][2], const GTile& t, int s0) {
;     ...
;   vm_wait_bar<WAIT0>();
;   int stc = s0, std_ = stage_next(stage_next(s0));
; #pragma nounroll
;   for (int kt = 0; kt < nk - 2; ++kt) {
;     GK_DMA(std_, kt + 2);
;     GK_COMPUTE(stc);
;     vm_wait_bar<6>();
;     stc = stage_next(stc); std_ = stage_next(std_);
;   }
;   GK_COMPUTE(stc);
;   vm_wait_bar<0>();
;   stc = stage_next(stc);
;   GK_COMPUTE(stc);
;   vm_wait_bar<0>();
	s_waitcnt lgkmcnt(0)
	s_add_i32 s6, s3, 0
	v_add_u32_e32 v84, s6, v83
	ds_read_b128 v[64:67], v84 offset:16384
	v_add_u32_e32 v72, s6, v82
	ds_read_b128 v[68:71], v72
	ds_read_b128 v[72:75], v72 offset:4096
	s_waitcnt lgkmcnt(0)
	v_mfma_f32_32x32x16_bf16 v[48:63], v[64:67], v[68:71], v[48:63]
	v_mfma_f32_32x32x16_bf16 v[16:31], v[64:67], v[72:75], v[16:31]
	ds_read_b128 v[64:67], v84 offset:20480
	v_add_u32_e32 v84, s6, v81
	s_waitcnt lgkmcnt(0)
	v_mfma_f32_32x32x16_bf16 v[32:47], v[64:67], v[68:71], v[32:47]
	v_mfma_f32_32x32x16_bf16 v[0:15], v[64:67], v[72:75], v[0:15]
	ds_read_b128 v[64:67], v84 offset:16384
	v_add_u32_e32 v72, s6, v80
	ds_read_b128 v[68:71], v72
	ds_read_b128 v[72:75], v72 offset:4096
	s_waitcnt lgkmcnt(0)
	v_mfma_f32_32x32x16_bf16 v[48:63], v[64:67], v[68:71], v[48:63]
	v_mfma_f32_32x32x16_bf16 v[16:31], v[64:67], v[72:75], v[16:31]
	ds_read_b128 v[64:67], v84 offset:20480
	v_add_u32_e32 v84, s6, v79
	s_waitcnt lgkmcnt(0)
	v_mfma_f32_32x32x16_bf16 v[32:47], v[64:67], v[68:71], v[32:47]
	v_mfma_f32_32x32x16_bf16 v[0:15], v[64:67], v[72:75], v[0:15]
	ds_read_b128 v[64:67], v84 offset:16384
	v_add_u32_e32 v72, s6, v78
	ds_read_b128 v[68:71], v72
	ds_read_b128 v[72:75], v72 offset:4096
	s_waitcnt lgkmcnt(0)
	v_mfma_f32_32x32x16_bf16 v[48:63], v[64:67], v[68:71], v[48:63]
	v_mfma_f32_32x32x16_bf16 v[16:31], v[64:67], v[72:75], v[16:31]
	ds_read_b128 v[64:67], v84 offset:20480
	v_add_u32_e32 v84, s6, v77
	s_waitcnt lgkmcnt(0)
	v_mfma_f32_32x32x16_bf16 v[32:47], v[64:67], v[68:71], v[32:47]
	v_mfma_f32_32x32x16_bf16 v[0:15], v[64:67], v[72:75], v[0:15]
	ds_read_b128 v[64:67], v84 offset:16384
	v_add_u32_e32 v72, s6, v76
	ds_read_b128 v[68:71], v72
	ds_read_b128 v[72:75], v72 offset:4096
	s_add_i32 s6, s3, 0xc000
	s_cmp_lg_u32 s3, 0x18000
	s_cselect_b32 s3, s6, 0
	s_waitcnt lgkmcnt(0)
	v_mfma_f32_32x32x16_bf16 v[48:63], v[64:67], v[68:71], v[48:63]
	s_add_i32 s3, s3, 0
	v_add_u32_e32 v83, s3, v83
	v_add_u32_e32 v81, s3, v81
	v_add_u32_e32 v79, s3, v79
	v_add_u32_e32 v77, s3, v77
	s_mov_b64 s[6:7], 0
	v_mfma_f32_32x32x16_bf16 v[16:31], v[64:67], v[72:75], v[16:31]
	ds_read_b128 v[64:67], v84 offset:20480
	s_waitcnt vmcnt(0) lgkmcnt(0)
	s_barrier
	s_waitcnt lgkmcnt(0)
	v_mfma_f32_32x32x16_bf16 v[32:47], v[64:67], v[68:71], v[32:47]
	v_mfma_f32_32x32x16_bf16 v[0:15], v[64:67], v[72:75], v[0:15]
	ds_read_b128 v[64:67], v83 offset:16384
	v_add_u32_e32 v72, s3, v82
	ds_read_b128 v[68:71], v72
	ds_read_b128 v[72:75], v72 offset:4096
	s_waitcnt lgkmcnt(0)
	v_mfma_f32_32x32x16_bf16 v[48:63], v[64:67], v[68:71], v[48:63]
	v_mfma_f32_32x32x16_bf16 v[16:31], v[64:67], v[72:75], v[16:31]
	ds_read_b128 v[64:67], v83 offset:20480
	s_waitcnt lgkmcnt(0)
	v_mfma_f32_32x32x16_bf16 v[32:47], v[64:67], v[68:71], v[32:47]
	v_mfma_f32_32x32x16_bf16 v[0:15], v[64:67], v[72:75], v[0:15]
	ds_read_b128 v[64:67], v81 offset:16384
	v_add_u32_e32 v72, s3, v80
	ds_read_b128 v[68:71], v72
	ds_read_b128 v[72:75], v72 offset:4096
	s_waitcnt lgkmcnt(0)
	v_mfma_f32_32x32x16_bf16 v[48:63], v[64:67], v[68:71], v[48:63]
	v_mfma_f32_32x32x16_bf16 v[16:31], v[64:67], v[72:75], v[16:31]
	ds_read_b128 v[64:67], v81 offset:20480
	s_waitcnt lgkmcnt(0)
	v_mfma_f32_32x32x16_bf16 v[32:47], v[64:67], v[68:71], v[32:47]
	v_mfma_f32_32x32x16_bf16 v[0:15], v[64:67], v[72:75], v[0:15]
	ds_read_b128 v[64:67], v79 offset:16384
	v_add_u32_e32 v72, s3, v78
	ds_read_b128 v[68:71], v72
	ds_read_b128 v[72:75], v72 offset:4096
	s_waitcnt lgkmcnt(0)
	v_mfma_f32_32x32x16_bf16 v[48:63], v[64:67], v[68:71], v[48:63]
	v_mfma_f32_32x32x16_bf16 v[16:31], v[64:67], v[72:75], v[16:31]
	ds_read_b128 v[64:67], v79 offset:20480
	s_waitcnt lgkmcnt(0)
	v_mfma_f32_32x32x16_bf16 v[32:47], v[64:67], v[68:71], v[32:47]
	v_mfma_f32_32x32x16_bf16 v[0:15], v[64:67], v[72:75], v[0:15]
	ds_read_b128 v[64:67], v77 offset:16384
	v_add_u32_e32 v72, s3, v76
	ds_read_b128 v[68:71], v72
	ds_read_b128 v[72:75], v72 offset:4096
	s_waitcnt lgkmcnt(0)
	v_mfma_f32_32x32x16_bf16 v[48:63], v[64:67], v[68:71], v[48:63]
	v_mfma_f32_32x32x16_bf16 v[16:31], v[64:67], v[72:75], v[16:31]
	ds_read_b128 v[64:67], v77 offset:20480
	s_waitcnt vmcnt(0) lgkmcnt(0)
	s_barrier
	s_waitcnt lgkmcnt(0)
	v_mfma_f32_32x32x16_bf16 v[32:47], v[64:67], v[68:71], v[32:47]
	v_mfma_f32_32x32x16_bf16 v[0:15], v[64:67], v[72:75], v[0:15]

; DEV int stage_next(int s) { return (s == 2 * GS_STAGE) ? 0 : s + GS_STAGE; }
; template <int WAIT0>
; DEV void gk_main(f32x16 (&acc)[2][2], const GTile& t, int s0) {
;     ...
;   vm_wait_bar<WAIT0>();
;   int stc = s0, std_ = stage_next(stage_next(s0));
; #pragma nounroll
;   for (int kt = 0; kt < nk - 2; ++kt) {
;     GK_DMA(std_, kt + 2);
;     GK_COMPUTE(stc);
;     vm_wait_bar<6>();
;     stc = stage_next(stc); std_ = stage_next(std_);
;   }
.LBB0_280:
	s_add_i32 s12, s10, s11
	s_mov_b32 s98, s12
	s_mov_b64 s[100:101], s[6:7]
	v_add_u32_e32 v252, s99, v80
	v_add_u32_e32 v253, s99, v81
	ds_read_b128 v[236:239], v252
	ds_read_b128 v[240:243], v252 offset:4096
	ds_read_b128 v[244:247], v253 offset:16384
	ds_read_b128 v[248:251], v253 offset:20480
	s_waitcnt lgkmcnt(4)
	v_mfma_f32_32x32x16_bf16 v[48:63], v[92:95], v[84:87], v[48:63]
	v_mfma_f32_32x32x16_bf16 v[16:31], v[92:95], v[88:91], v[16:31]
	s_mov_b32 m0, s98
	v_lshl_add_u64 v[254:255], v[74:75], 0, s[100:101]
	global_load_lds_dwordx4 v[254:255], off
	v_mfma_f32_32x32x16_bf16 v[32:47], v[96:99], v[84:87], v[32:47]
	v_mfma_f32_32x32x16_bf16 v[0:15], v[96:99], v[88:91], v[0:15]
	s_add_i32 m0, s98, 0x2000
	v_lshl_add_u64 v[254:255], v[72:73], 0, s[100:101]
	global_load_lds_dwordx4 v[254:255], off
	v_add_u32_e32 v252, s99, v78
	v_add_u32_e32 v253, s99, v79
	ds_read_b128 v[84:87], v252
	ds_read_b128 v[88:91], v252 offset:4096
	ds_read_b128 v[92:95], v253 offset:16384
	ds_read_b128 v[96:99], v253 offset:20480
	s_waitcnt lgkmcnt(4)
	v_mfma_f32_32x32x16_bf16 v[48:63], v[244:247], v[236:239], v[48:63]
	v_mfma_f32_32x32x16_bf16 v[16:31], v[244:247], v[240:243], v[16:31]
	s_add_i32 m0, s98, 0x4000
	v_lshl_add_u64 v[254:255], v[70:71], 0, s[100:101]
	global_load_lds_dwordx4 v[254:255], off
	v_mfma_f32_32x32x16_bf16 v[32:47], v[248:251], v[236:239], v[32:47]
	v_mfma_f32_32x32x16_bf16 v[0:15], v[248:251], v[240:243], v[0:15]
	s_add_i32 m0, s98, 0x6000
	v_lshl_add_u64 v[254:255], v[68:69], 0, s[100:101]
	global_load_lds_dwordx4 v[254:255], off
	v_add_u32_e32 v252, s99, v76
	v_add_u32_e32 v253, s99, v77
	ds_read_b128 v[236:239], v252
	ds_read_b128 v[240:243], v252 offset:4096
	ds_read_b128 v[244:247], v253 offset:16384
	ds_read_b128 v[248:251], v253 offset:20480
	s_waitcnt lgkmcnt(4)
	v_mfma_f32_32x32x16_bf16 v[48:63], v[92:95], v[84:87], v[48:63]
	v_mfma_f32_32x32x16_bf16 v[16:31], v[92:95], v[88:91], v[16:31]
	s_add_i32 m0, s98, 0x8000
	v_lshl_add_u64 v[254:255], v[66:67], 0, s[100:101]
	global_load_lds_dwordx4 v[254:255], off
	v_mfma_f32_32x32x16_bf16 v[32:47], v[96:99], v[84:87], v[32:47]
	v_mfma_f32_32x32x16_bf16 v[0:15], v[96:99], v[88:91], v[0:15]
	s_add_i32 m0, s98, 0xa000
	v_lshl_add_u64 v[254:255], v[64:65], 0, s[100:101]
	global_load_lds_dwordx4 v[254:255], off
	s_add_i32 s12, s3, 0xc000
	s_cmp_lg_u32 s3, 0x18000
	s_cselect_b32 s3, s12, 0
	s_waitcnt lgkmcnt(0)
	v_mfma_f32_32x32x16_bf16 v[48:63], v[244:247], v[236:239], v[48:63]
	s_add_i32 s12, s11, 0xc000
	s_cmp_lg_u32 s11, 0x18000
	s_waitcnt vmcnt(6) lgkmcnt(0)
	s_barrier
	s_cselect_b32 s11, s12, 0
	s_add_u32 s6, s6, 0x80
	s_add_i32 s99, s3, 0
	v_add_u32_e32 v252, s99, v82
	v_add_u32_e32 v253, s99, v83
	ds_read_b128 v[84:87], v252
	ds_read_b128 v[88:91], v252 offset:4096
	ds_read_b128 v[92:95], v253 offset:16384
	ds_read_b128 v[96:99], v253 offset:20480
	v_mfma_f32_32x32x16_bf16 v[16:31], v[244:247], v[240:243], v[16:31]
	s_addc_u32 s7, s7, 0
	s_cmpk_lg_i32 s6, 0x700
	v_mfma_f32_32x32x16_bf16 v[32:47], v[248:251], v[236:239], v[32:47]
	v_mfma_f32_32x32x16_bf16 v[0:15], v[248:251], v[240:243], v[0:15]
	s_cbranch_scc1 .LBB0_280
; DEV int stage_next(int s) { return (s == 2 * GS_STAGE) ? 0 : s + GS_STAGE; }
; template <int WAIT0>
; DEV void gk_main(f32x16 (&acc)[2][2], const GTile& t, int s0) {
;     ...
;   vm_wait_bar<WAIT0>();
;   int stc = s0, std_ = stage_next(stage_next(s0));
; #pragma nounroll
;   for (int kt = 0; kt < nk - 2; ++kt) {
;     GK_DMA(std_, kt + 2);
;     GK_COMPUTE(stc);
;     vm_wait_bar<6>();
;     stc = stage_next(stc); std_ = stage_next(std_);
;   }
;   GK_COMPUTE(stc);
;   vm_wait_bar<0>();
;   stc = stage_next(stc);
;   GK_COMPUTE(stc);
;   vm_wait_bar<0>();
	s_waitcnt lgkmcnt(0)
	s_add_i32 s6, s3, 0
	v_add_u32_e32 v84, s6, v83
	ds_read_b128 v[64:67], v84 offset:16384
	v_add_u32_e32 v72, s6, v82
	ds_read_b128 v[68:71], v72
	ds_read_b128 v[72:75], v72 offset:4096
	s_waitcnt lgkmcnt(0)
	v_mfma_f32_32x32x16_bf16 v[48:63], v[64:67], v[68:71], v[48:63]
	v_mfma_f32_32x32x16_bf16 v[16:31], v[64:67], v[72:75], v[16:31]
	ds_read_b128 v[64:67], v84 offset:20480
	v_add_u32_e32 v84, s6, v81
	s_waitcnt lgkmcnt(0)
	v_mfma_f32_32x32x16_bf16 v[32:47], v[64:67], v[68:71], v[32:47]
	v_mfma_f32_32x32x16_bf16 v[0:15], v[64:67], v[72:75], v[0:15]
	ds_read_b128 v[64:67], v84 offset:16384
	v_add_u32_e32 v72, s6, v80
	ds_read_b128 v[68:71], v72
	ds_read_b128 v[72:75], v72 offset:4096
	s_waitcnt lgkmcnt(0)
	v_mfma_f32_32x32x16_bf16 v[48:63], v[64:67], v[68:71], v[48:63]
	v_mfma_f32_32x32x16_bf16 v[16:31], v[64:67], v[72:75], v[16:31]
	ds_read_b128 v[64:67], v84 offset:20480
	v_add_u32_e32 v84, s6, v79
	s_waitcnt lgkmcnt(0)
	v_mfma_f32_32x32x16_bf16 v[32:47], v[64:67], v[68:71], v[32:47]
	v_mfma_f32_32x32x16_bf16 v[0:15], v[64:67], v[72:75], v[0:15]
	ds_read_b128 v[64:67], v84 offset:16384
	v_add_u32_e32 v72, s6, v78
	ds_read_b128 v[68:71], v72
	ds_read_b128 v[72:75], v72 offset:4096
	s_waitcnt lgkmcnt(0)
	v_mfma_f32_32x32x16_bf16 v[48:63], v[64:67], v[68:71], v[48:63]
	v_mfma_f32_32x32x16_bf16 v[16:31], v[64:67], v[72:75], v[16:31]
	ds_read_b128 v[64:67], v84 offset:20480
	v_add_u32_e32 v84, s6, v77
	s_waitcnt lgkmcnt(0)
	v_mfma_f32_32x32x16_bf16 v[32:47], v[64:67], v[68:71], v[32:47]
	v_mfma_f32_32x32x16_bf16 v[0:15], v[64:67], v[72:75], v[0:15]
	ds_read_b128 v[64:67], v84 offset:16384
	v_add_u32_e32 v72, s6, v76
	ds_read_b128 v[68:71], v72
	ds_read_b128 v[72:75], v72 offset:4096
	s_add_i32 s6, s3, 0xc000
	s_cmp_lg_u32 s3, 0x18000
	s_cselect_b32 s3, s6, 0
	s_waitcnt lgkmcnt(0)
	v_mfma_f32_32x32x16_bf16 v[48:63], v[64:67], v[68:71], v[48:63]
	s_add_i32 s3, s3, 0
	v_add_u32_e32 v83, s3, v83
	v_add_u32_e32 v81, s3, v81
	v_add_u32_e32 v79, s3, v79
	v_add_u32_e32 v77, s3, v77
	v_mfma_f32_32x32x16_bf16 v[16:31], v[64:67], v[72:75], v[16:31]
	ds_read_b128 v[64:67], v84 offset:20480
	s_waitcnt vmcnt(0) lgkmcnt(0)
	s_barrier
	s_waitcnt lgkmcnt(0)
	v_mfma_f32_32x32x16_bf16 v[32:47], v[64:67], v[68:71], v[32:47]
	v_mfma_f32_32x32x16_bf16 v[0:15], v[64:67], v[72:75], v[0:15]
	ds_read_b128 v[64:67], v83 offset:16384
	v_add_u32_e32 v72, s3, v82
	ds_read_b128 v[68:71], v72
	ds_read_b128 v[72:75], v72 offset:4096
	s_waitcnt lgkmcnt(0)
	v_mfma_f32_32x32x16_bf16 v[48:63], v[64:67], v[68:71], v[48:63]
	v_mfma_f32_32x32x16_bf16 v[16:31], v[64:67], v[72:75], v[16:31]
	ds_read_b128 v[64:67], v83 offset:20480
	s_waitcnt lgkmcnt(0)
	v_mfma_f32_32x32x16_bf16 v[32:47], v[64:67], v[68:71], v[32:47]
	v_mfma_f32_32x32x16_bf16 v[0:15], v[64:67], v[72:75], v[0:15]
	ds_read_b128 v[64:67], v81 offset:16384
	v_add_u32_e32 v72, s3, v80
	ds_read_b128 v[68:71], v72
	ds_read_b128 v[72:75], v72 offset:4096
	s_waitcnt lgkmcnt(0)
	v_mfma_f32_32x32x16_bf16 v[48:63], v[64:67], v[68:71], v[48:63]
	v_mfma_f32_32x32x16_bf16 v[16:31], v[64:67], v[72:75], v[16:31]
	ds_read_b128 v[64:67], v81 offset:20480
	s_waitcnt lgkmcnt(0)
	v_mfma_f32_32x32x16_bf16 v[32:47], v[64:67], v[68:71], v[32:47]
	v_mfma_f32_32x32x16_bf16 v[0:15], v[64:67], v[72:75], v[0:15]
	ds_read_b128 v[64:67], v79 offset:16384
	v_add_u32_e32 v72, s3, v78
	ds_read_b128 v[68:71], v72
	ds_read_b128 v[72:75], v72 offset:4096
	s_waitcnt lgkmcnt(0)
	v_mfma_f32_32x32x16_bf16 v[48:63], v[64:67], v[68:71], v[48:63]
	v_mfma_f32_32x32x16_bf16 v[16:31], v[64:67], v[72:75], v[16:31]
	ds_read_b128 v[64:67], v79 offset:20480
	s_waitcnt lgkmcnt(0)
	v_mfma_f32_32x32x16_bf16 v[32:47], v[64:67], v[68:71], v[32:47]
	v_mfma_f32_32x32x16_bf16 v[0:15], v[64:67], v[72:75], v[0:15]
	ds_read_b128 v[64:67], v77 offset:16384
	v_add_u32_e32 v72, s3, v76
	ds_read_b128 v[68:71], v72
	ds_read_b128 v[72:75], v72 offset:4096
	s_waitcnt lgkmcnt(0)
	v_mfma_f32_32x32x16_bf16 v[48:63], v[64:67], v[68:71], v[48:63]
	v_mfma_f32_32x32x16_bf16 v[16:31], v[64:67], v[72:75], v[16:31]
	ds_read_b128 v[64:67], v77 offset:20480
	s_waitcnt vmcnt(0) lgkmcnt(0)
	s_barrier
	s_waitcnt lgkmcnt(0)
	v_mfma_f32_32x32x16_bf16 v[32:47], v[64:67], v[68:71], v[32:47]
	v_mfma_f32_32x32x16_bf16 v[0:15], v[64:67], v[72:75], v[0:15]

; DEV int stage_next(int s) { return (s == 2 * GS_STAGE) ? 0 : s + GS_STAGE; }
; template <int WAIT0>
; DEV void gk_main(f32x16 (&acc)[2][2], const GTile& t, int s0) {
;     ...
;   vm_wait_bar<WAIT0>();
;   int stc = s0, std_ = stage_next(stage_next(s0));
; #pragma nounroll
;   for (int kt = 0; kt < nk - 2; ++kt) {
;     GK_DMA(std_, kt + 2);
;     GK_COMPUTE(stc);
;     vm_wait_bar<6>();
;     stc = stage_next(stc); std_ = stage_next(std_);
;   }
.LBB0_286:
	s_add_i32 s12, s10, s11
	s_mov_b32 s98, s12
	s_mov_b64 s[100:101], s[6:7]
	v_add_u32_e32 v252, s99, v80
	v_add_u32_e32 v253, s99, v81
	ds_read_b128 v[236:239], v252
	ds_read_b128 v[240:243], v252 offset:4096
	ds_read_b128 v[244:247], v253 offset:16384
	ds_read_b128 v[248:251], v253 offset:20480
	s_waitcnt lgkmcnt(4)
	v_mfma_f32_32x32x16_bf16 v[48:63], v[92:95], v[84:87], v[48:63]
	v_mfma_f32_32x32x16_bf16 v[16:31], v[92:95], v[88:91], v[16:31]
	s_mov_b32 m0, s98
	v_lshl_add_u64 v[254:255], v[74:75], 0, s[100:101]
	global_load_lds_dwordx4 v[254:255], off
	v_mfma_f32_32x32x16_bf16 v[32:47], v[96:99], v[84:87], v[32:47]
	v_mfma_f32_32x32x16_bf16 v[0:15], v[96:99], v[88:91], v[0:15]
	s_add_i32 m0, s98, 0x2000
	v_lshl_add_u64 v[254:255], v[72:73], 0, s[100:101]
	global_load_lds_dwordx4 v[254:255], off
	v_add_u32_e32 v252, s99, v78
	v_add_u32_e32 v253, s99, v79
	ds_read_b128 v[84:87], v252
	ds_read_b128 v[88:91], v252 offset:4096
	ds_read_b128 v[92:95], v253 offset:16384
	ds_read_b128 v[96:99], v253 offset:20480
	s_waitcnt lgkmcnt(4)
	v_mfma_f32_32x32x16_bf16 v[48:63], v[244:247], v[236:239], v[48:63]
	v_mfma_f32_32x32x16_bf16 v[16:31], v[244:247], v[240:243], v[16:31]
	s_add_i32 m0, s98, 0x4000
	v_lshl_add_u64 v[254:255], v[70:71], 0, s[100:101]
	global_load_lds_dwordx4 v[254:255], off
	v_mfma_f32_32x32x16_bf16 v[32:47], v[248:251], v[236:239], v[32:47]
	v_mfma_f32_32x32x16_bf16 v[0:15], v[248:251], v[240:243], v[0:15]
	s_add_i32 m0, s98, 0x6000
	v_lshl_add_u64 v[254:255], v[68:69], 0, s[100:101]
	global_load_lds_dwordx4 v[254:255], off
	v_add_u32_e32 v252, s99, v76
	v_add_u32_e32 v253, s99, v77
	ds_read_b128 v[236:239], v252
	ds_read_b128 v[240:243], v252 offset:4096
	ds_read_b128 v[244:247], v253 offset:16384
	ds_read_b128 v[248:251], v253 offset:20480
	s_waitcnt lgkmcnt(4)
	v_mfma_f32_32x32x16_bf16 v[48:63], v[92:95], v[84:87], v[48:63]
	v_mfma_f32_32x32x16_bf16 v[16:31], v[92:95], v[88:91], v[16:31]
	s_add_i32 m0, s98, 0x8000
	v_lshl_add_u64 v[254:255], v[66:67], 0, s[100:101]
	global_load_lds_dwordx4 v[254:255], off
	v_mfma_f32_32x32x16_bf16 v[32:47], v[96:99], v[84:87], v[32:47]
	v_mfma_f32_32x32x16_bf16 v[0:15], v[96:99], v[88:91], v[0:15]
	s_add_i32 m0, s98, 0xa000
	v_lshl_add_u64 v[254:255], v[64:65], 0, s[100:101]
	global_load_lds_dwordx4 v[254:255], off
	s_add_i32 s12, s3, 0xc000
	s_cmp_lg_u32 s3, 0x18000
	s_cselect_b32 s3, s12, 0
	s_waitcnt lgkmcnt(0)
	v_mfma_f32_32x32x16_bf16 v[48:63], v[244:247], v[236:239], v[48:63]
	s_add_i32 s12, s11, 0xc000
	s_cmp_lg_u32 s11, 0x18000
	s_waitcnt vmcnt(6) lgkmcnt(0)
	s_barrier
	s_cselect_b32 s11, s12, 0
	s_add_u32 s6, s6, 0x80
	s_add_i32 s99, s3, 0
	v_add_u32_e32 v252, s99, v82
	v_add_u32_e32 v253, s99, v83
	ds_read_b128 v[84:87], v252
	ds_read_b128 v[88:91], v252 offset:4096
	ds_read_b128 v[92:95], v253 offset:16384
	ds_read_b128 v[96:99], v253 offset:20480
	v_mfma_f32_32x32x16_bf16 v[16:31], v[244:247], v[240:243], v[16:31]
	s_addc_u32 s7, s7, 0
	s_cmpk_lg_i32 s6, 0x700
	v_mfma_f32_32x32x16_bf16 v[32:47], v[248:251], v[236:239], v[32:47]
	v_mfma_f32_32x32x16_bf16 v[0:15], v[248:251], v[240:243], v[0:15]
	s_cbranch_scc1 .LBB0_286
; DEV int stage_next(int s) { return (s == 2 * GS_STAGE) ? 0 : s + GS_STAGE; }
; template <int WAIT0>
; DEV void gk_main(f32x16 (&acc)[2][2], const GTile& t, int s0) {
;     ...
;   vm_wait_bar<WAIT0>();
;   int stc = s0, std_ = stage_next(stage_next(s0));
; #pragma nounroll
;   for (int kt = 0; kt < nk - 2; ++kt) {
;     GK_DMA(std_, kt + 2);
;     GK_COMPUTE(stc);
;     vm_wait_bar<6>();
;     stc = stage_next(stc); std_ = stage_next(std_);
;   }
;   GK_COMPUTE(stc);
;   vm_wait_bar<0>();
;   stc = stage_next(stc);
;   GK_COMPUTE(stc);
;   vm_wait_bar<0>();
; template <int WAIT_E, int WAIT_O, class TileFn, class EpiFn>
; DEV void gemm_seq(int ntiles, TileFn tf, EpiFn epi) {
;     ...
;   for (int i = 0; i < ntiles; ++i) {
;     f32x16 acc[2][2]; acc_zero(acc);
;     if (i == 0) gk_main<6>(acc, cur, s0);
;     else if (i & 1) gk_main<WAIT_O>(acc, cur, s0);
;     else gk_main<WAIT_E>(acc, cur, s0);
;     const int sn = stage_next(s0);
;     if (i + 1 < ntiles) { cur = tf(i + 1); gk_issue2(cur, sn); }
;     epi(i, acc, s0);
;     s0 = sn;
;   }
	s_waitcnt lgkmcnt(0)
	s_add_i32 s6, s3, 0
	v_add_u32_e32 v84, s6, v83
	ds_read_b128 v[64:67], v84 offset:16384
	v_add_u32_e32 v72, s6, v82
	ds_read_b128 v[68:71], v72
	ds_read_b128 v[72:75], v72 offset:4096
	s_waitcnt lgkmcnt(0)
	v_mfma_f32_32x32x16_bf16 v[48:63], v[64:67], v[68:71], v[48:63]
	v_mfma_f32_32x32x16_bf16 v[16:31], v[64:67], v[72:75], v[16:31]
	ds_read_b128 v[64:67], v84 offset:20480
	v_add_u32_e32 v84, s6, v81
	s_waitcnt lgkmcnt(0)
	v_mfma_f32_32x32x16_bf16 v[32:47], v[64:67], v[68:71], v[32:47]
	v_mfma_f32_32x32x16_bf16 v[0:15], v[64:67], v[72:75], v[0:15]
	ds_read_b128 v[64:67], v84 offset:16384
	v_add_u32_e32 v72, s6, v80
	ds_read_b128 v[68:71], v72
	ds_read_b128 v[72:75], v72 offset:4096
	s_waitcnt lgkmcnt(0)
	v_mfma_f32_32x32x16_bf16 v[48:63], v[64:67], v[68:71], v[48:63]
	v_mfma_f32_32x32x16_bf16 v[16:31], v[64:67], v[72:75], v[16:31]
	ds_read_b128 v[64:67], v84 offset:20480
	v_add_u32_e32 v84, s6, v79
	s_waitcnt lgkmcnt(0)
	v_mfma_f32_32x32x16_bf16 v[32:47], v[64:67], v[68:71], v[32:47]
	v_mfma_f32_32x32x16_bf16 v[0:15], v[64:67], v[72:75], v[0:15]
	ds_read_b128 v[64:67], v84 offset:16384
	v_add_u32_e32 v72, s6, v78
	ds_read_b128 v[68:71], v72
	ds_read_b128 v[72:75], v72 offset:4096
	s_waitcnt lgkmcnt(0)
	v_mfma_f32_32x32x16_bf16 v[48:63], v[64:67], v[68:71], v[48:63]
	v_mfma_f32_32x32x16_bf16 v[16:31], v[64:67], v[72:75], v[16:31]
	ds_read_b128 v[64:67], v84 offset:20480
	v_add_u32_e32 v84, s6, v77
	s_waitcnt lgkmcnt(0)
	v_mfma_f32_32x32x16_bf16 v[32:47], v[64:67], v[68:71], v[32:47]
	v_mfma_f32_32x32x16_bf16 v[0:15], v[64:67], v[72:75], v[0:15]
	ds_read_b128 v[64:67], v84 offset:16384
	v_add_u32_e32 v72, s6, v76
	ds_read_b128 v[68:71], v72
	ds_read_b128 v[72:75], v72 offset:4096
	s_add_i32 s6, s3, 0xc000
	s_cmp_lg_u32 s3, 0x18000
	s_cselect_b32 s3, s6, 0
	s_waitcnt lgkmcnt(0)
	v_mfma_f32_32x32x16_bf16 v[48:63], v[64:67], v[68:71], v[48:63]
	s_add_i32 s3, s3, 0
	v_add_u32_e32 v83, s3, v83
	v_add_u32_e32 v81, s3, v81
	v_add_u32_e32 v79, s3, v79
	v_add_u32_e32 v77, s3, v77
	v_mfma_f32_32x32x16_bf16 v[16:31], v[64:67], v[72:75], v[16:31]
	ds_read_b128 v[64:67], v84 offset:20480
	s_waitcnt vmcnt(0) lgkmcnt(0)
	s_barrier
	s_waitcnt lgkmcnt(0)
	v_mfma_f32_32x32x16_bf16 v[32:47], v[64:67], v[68:71], v[32:47]
	v_mfma_f32_32x32x16_bf16 v[0:15], v[64:67], v[72:75], v[0:15]
	ds_read_b128 v[64:67], v83 offset:16384
	v_add_u32_e32 v72, s3, v82
	ds_read_b128 v[68:71], v72
	ds_read_b128 v[72:75], v72 offset:4096
	s_waitcnt lgkmcnt(0)
	v_mfma_f32_32x32x16_bf16 v[48:63], v[64:67], v[68:71], v[48:63]
	v_mfma_f32_32x32x16_bf16 v[16:31], v[64:67], v[72:75], v[16:31]
	ds_read_b128 v[64:67], v83 offset:20480
	s_waitcnt lgkmcnt(0)
	v_mfma_f32_32x32x16_bf16 v[32:47], v[64:67], v[68:71], v[32:47]
	v_mfma_f32_32x32x16_bf16 v[0:15], v[64:67], v[72:75], v[0:15]
	ds_read_b128 v[64:67], v81 offset:16384
	v_add_u32_e32 v72, s3, v80
	ds_read_b128 v[68:71], v72
	ds_read_b128 v[72:75], v72 offset:4096
	s_waitcnt lgkmcnt(0)
	v_mfma_f32_32x32x16_bf16 v[48:63], v[64:67], v[68:71], v[48:63]
	v_mfma_f32_32x32x16_bf16 v[16:31], v[64:67], v[72:75], v[16:31]
	ds_read_b128 v[64:67], v81 offset:20480
	s_waitcnt lgkmcnt(0)
	v_mfma_f32_32x32x16_bf16 v[32:47], v[64:67], v[68:71], v[32:47]
	v_mfma_f32_32x32x16_bf16 v[0:15], v[64:67], v[72:75], v[0:15]
	ds_read_b128 v[64:67], v79 offset:16384
	v_add_u32_e32 v72, s3, v78
	ds_read_b128 v[68:71], v72
	ds_read_b128 v[72:75], v72 offset:4096
	s_waitcnt lgkmcnt(0)
	v_mfma_f32_32x32x16_bf16 v[48:63], v[64:67], v[68:71], v[48:63]
	v_mfma_f32_32x32x16_bf16 v[16:31], v[64:67], v[72:75], v[16:31]
	ds_read_b128 v[64:67], v79 offset:20480
	s_waitcnt lgkmcnt(0)
	v_mfma_f32_32x32x16_bf16 v[32:47], v[64:67], v[68:71], v[32:47]
	v_mfma_f32_32x32x16_bf16 v[0:15], v[64:67], v[72:75], v[0:15]
	ds_read_b128 v[64:67], v77 offset:16384
	v_add_u32_e32 v72, s3, v76
	ds_read_b128 v[68:71], v72
	ds_read_b128 v[72:75], v72 offset:4096
	s_waitcnt lgkmcnt(0)
	v_mfma_f32_32x32x16_bf16 v[48:63], v[64:67], v[68:71], v[48:63]
	v_mfma_f32_32x32x16_bf16 v[16:31], v[64:67], v[72:75], v[16:31]
	ds_read_b128 v[64:67], v77 offset:20480
	s_waitcnt vmcnt(0) lgkmcnt(0)
	s_barrier
	s_waitcnt lgkmcnt(0)
	v_mfma_f32_32x32x16_bf16 v[32:47], v[64:67], v[68:71], v[32:47]
	v_mfma_f32_32x32x16_bf16 v[0:15], v[64:67], v[72:75], v[0:15]
	s_add_i32 s3, s2, 1
	s_cmp_eq_u32 s2, 3
	s_cbranch_scc1 .LBB0_272

; DEV int stage_next(int s) { return (s == 2 * GS_STAGE) ? 0 : s + GS_STAGE; }
; template <int WAIT0>
; DEV void gk_main(f32x16 (&acc)[2][2], const GTile& t, int s0) {
;     ...
;   vm_wait_bar<WAIT0>();
;   int stc = s0, std_ = stage_next(stage_next(s0));
; #pragma nounroll
;   for (int kt = 0; kt < nk - 2; ++kt) {
;     GK_DMA(std_, kt + 2);
;     GK_COMPUTE(stc);
;     vm_wait_bar<6>();
;     stc = stage_next(stc); std_ = stage_next(std_);
;   }
.LBB0_403:
	s_add_i32 s10, s3, s8
	s_mov_b32 s98, s10
	v_add_u32_e32 v252, s99, v80
	v_add_u32_e32 v253, s99, v81
	ds_read_b128 v[236:239], v252
	ds_read_b128 v[240:243], v252 offset:4096
	ds_read_b128 v[244:247], v253 offset:16384
	ds_read_b128 v[248:251], v253 offset:20480
	s_waitcnt lgkmcnt(4)
	v_mfma_f32_32x32x16_bf16 v[48:63], v[92:95], v[84:87], v[48:63]
	v_mfma_f32_32x32x16_bf16 v[32:47], v[92:95], v[88:91], v[32:47]
	s_mov_b32 m0, s98
	v_lshl_add_u64 v[254:255], v[74:75], 0, v[120:121]
	global_load_lds_dwordx4 v[254:255], off
	v_lshl_add_u64 v[74:75], v[74:75], 0, s[96:97]
	v_mfma_f32_32x32x16_bf16 v[16:31], v[96:99], v[84:87], v[16:31]
	v_mfma_f32_32x32x16_bf16 v[0:15], v[96:99], v[88:91], v[0:15]
	s_add_i32 m0, s98, 0x2000
	v_lshl_add_u64 v[254:255], v[72:73], 0, v[120:121]
	global_load_lds_dwordx4 v[254:255], off
	v_lshl_add_u64 v[72:73], v[72:73], 0, s[96:97]
	v_add_u32_e32 v252, s99, v78
	v_add_u32_e32 v253, s99, v79
	ds_read_b128 v[84:87], v252
	ds_read_b128 v[88:91], v252 offset:4096
	ds_read_b128 v[92:95], v253 offset:16384
	ds_read_b128 v[96:99], v253 offset:20480
	s_waitcnt lgkmcnt(4)
	v_mfma_f32_32x32x16_bf16 v[48:63], v[244:247], v[236:239], v[48:63]
	v_mfma_f32_32x32x16_bf16 v[32:47], v[244:247], v[240:243], v[32:47]
	s_add_i32 m0, s98, 0x4000
	v_lshl_add_u64 v[254:255], v[70:71], 0, v[120:121]
	global_load_lds_dwordx4 v[254:255], off
	v_lshl_add_u64 v[70:71], v[70:71], 0, s[96:97]
	v_mfma_f32_32x32x16_bf16 v[16:31], v[248:251], v[236:239], v[16:31]
	v_mfma_f32_32x32x16_bf16 v[0:15], v[248:251], v[240:243], v[0:15]
	s_add_i32 m0, s98, 0x6000
	v_lshl_add_u64 v[254:255], v[68:69], 0, v[120:121]
	global_load_lds_dwordx4 v[254:255], off
	v_lshl_add_u64 v[68:69], v[68:69], 0, s[96:97]
	v_add_u32_e32 v252, s99, v76
	v_add_u32_e32 v253, s99, v77
	ds_read_b128 v[236:239], v252
	ds_read_b128 v[240:243], v252 offset:4096
	ds_read_b128 v[244:247], v253 offset:16384
	ds_read_b128 v[248:251], v253 offset:20480
	s_waitcnt lgkmcnt(4)
	v_mfma_f32_32x32x16_bf16 v[48:63], v[92:95], v[84:87], v[48:63]
	v_mfma_f32_32x32x16_bf16 v[32:47], v[92:95], v[88:91], v[32:47]
	s_add_i32 m0, s98, 0x8000
	v_lshl_add_u64 v[254:255], v[66:67], 0, v[120:121]
	global_load_lds_dwordx4 v[254:255], off
	v_lshl_add_u64 v[66:67], v[66:67], 0, s[96:97]
	v_mfma_f32_32x32x16_bf16 v[16:31], v[96:99], v[84:87], v[16:31]
	v_mfma_f32_32x32x16_bf16 v[0:15], v[96:99], v[88:91], v[0:15]
	s_add_i32 m0, s98, 0xa000
	v_lshl_add_u64 v[254:255], v[64:65], 0, v[120:121]
	global_load_lds_dwordx4 v[254:255], off
	v_lshl_add_u64 v[64:65], v[64:65], 0, s[96:97]
	s_add_i32 s10, s2, 0xc000
	s_cmp_lg_u32 s2, 0x18000
	s_cselect_b32 s2, s10, 0
	s_waitcnt lgkmcnt(0)
	v_mfma_f32_32x32x16_bf16 v[48:63], v[244:247], v[236:239], v[48:63]
	s_add_i32 s10, s8, 0xc000
	s_waitcnt vmcnt(6) lgkmcnt(0)
	s_barrier
	s_cmp_lg_u32 s8, 0x18000
	s_cselect_b32 s8, s10, 0
	s_add_i32 s9, s9, -1
	s_add_i32 s99, s2, 0
	v_add_u32_e32 v252, s99, v82
	v_add_u32_e32 v253, s99, v83
	ds_read_b128 v[84:87], v252
	ds_read_b128 v[88:91], v252 offset:4096
	ds_read_b128 v[92:95], v253 offset:16384
	ds_read_b128 v[96:99], v253 offset:20480
	v_mfma_f32_32x32x16_bf16 v[32:47], v[244:247], v[240:243], v[32:47]
	s_cmp_lg_u32 s9, 0
	v_mfma_f32_32x32x16_bf16 v[16:31], v[248:251], v[236:239], v[16:31]
	v_mfma_f32_32x32x16_bf16 v[0:15], v[248:251], v[240:243], v[0:15]
	s_cbranch_scc1 .LBB0_403
; DEV int stage_next(int s) { return (s == 2 * GS_STAGE) ? 0 : s + GS_STAGE; }
; template <int WAIT0>
; DEV void gk_main(f32x16 (&acc)[2][2], const GTile& t, int s0) {
;     ...
;   vm_wait_bar<WAIT0>();
;   int stc = s0, std_ = stage_next(stage_next(s0));
; #pragma nounroll
;   for (int kt = 0; kt < nk - 2; ++kt) {
;     GK_DMA(std_, kt + 2);
;     GK_COMPUTE(stc);
;     vm_wait_bar<6>();
;     stc = stage_next(stc); std_ = stage_next(std_);
;   }
;   GK_COMPUTE(stc);
;   vm_wait_bar<0>();
;   stc = stage_next(stc);
;   GK_COMPUTE(stc);
;   vm_wait_bar<0>();
	s_waitcnt lgkmcnt(0)
	s_add_i32 s3, s2, 0
	v_add_u32_e32 v84, s3, v83
	ds_read_b128 v[64:67], v84 offset:16384
	v_add_u32_e32 v72, s3, v82
	ds_read_b128 v[68:71], v72
	ds_read_b128 v[72:75], v72 offset:4096
	s_mov_b64 s[8:9], 0
	s_waitcnt lgkmcnt(0)
	v_mfma_f32_32x32x16_bf16 v[48:63], v[64:67], v[68:71], v[48:63]
	v_mfma_f32_32x32x16_bf16 v[32:47], v[64:67], v[72:75], v[32:47]
	ds_read_b128 v[64:67], v84 offset:20480
	v_add_u32_e32 v84, s3, v81
	s_waitcnt lgkmcnt(0)
	v_mfma_f32_32x32x16_bf16 v[16:31], v[64:67], v[68:71], v[16:31]
	v_mfma_f32_32x32x16_bf16 v[0:15], v[64:67], v[72:75], v[0:15]
	ds_read_b128 v[64:67], v84 offset:16384
	v_add_u32_e32 v72, s3, v80
	ds_read_b128 v[68:71], v72
	ds_read_b128 v[72:75], v72 offset:4096
	s_waitcnt lgkmcnt(0)
	v_mfma_f32_32x32x16_bf16 v[48:63], v[64:67], v[68:71], v[48:63]
	v_mfma_f32_32x32x16_bf16 v[32:47], v[64:67], v[72:75], v[32:47]
	ds_read_b128 v[64:67], v84 offset:20480
	v_add_u32_e32 v84, s3, v79
	s_waitcnt lgkmcnt(0)
	v_mfma_f32_32x32x16_bf16 v[16:31], v[64:67], v[68:71], v[16:31]
	v_mfma_f32_32x32x16_bf16 v[0:15], v[64:67], v[72:75], v[0:15]
	ds_read_b128 v[64:67], v84 offset:16384
	v_add_u32_e32 v72, s3, v78
	ds_read_b128 v[68:71], v72
	ds_read_b128 v[72:75], v72 offset:4096
	s_waitcnt lgkmcnt(0)
	v_mfma_f32_32x32x16_bf16 v[48:63], v[64:67], v[68:71], v[48:63]
	v_mfma_f32_32x32x16_bf16 v[32:47], v[64:67], v[72:75], v[32:47]
	ds_read_b128 v[64:67], v84 offset:20480
	v_add_u32_e32 v84, s3, v77
	s_waitcnt lgkmcnt(0)
	v_mfma_f32_32x32x16_bf16 v[16:31], v[64:67], v[68:71], v[16:31]
	v_mfma_f32_32x32x16_bf16 v[0:15], v[64:67], v[72:75], v[0:15]
	ds_read_b128 v[64:67], v84 offset:16384
	v_add_u32_e32 v72, s3, v76
	ds_read_b128 v[68:71], v72
	ds_read_b128 v[72:75], v72 offset:4096
	s_add_i32 s3, s2, 0xc000
	s_cmp_lg_u32 s2, 0x18000
	s_cselect_b32 s2, s3, 0
	s_waitcnt lgkmcnt(0)
	v_mfma_f32_32x32x16_bf16 v[48:63], v[64:67], v[68:71], v[48:63]
	s_add_i32 s2, s2, 0
	v_add_u32_e32 v83, s2, v83
	v_add_u32_e32 v81, s2, v81
	v_add_u32_e32 v79, s2, v79
	v_add_u32_e32 v77, s2, v77
	v_mfma_f32_32x32x16_bf16 v[32:47], v[64:67], v[72:75], v[32:47]
	ds_read_b128 v[64:67], v84 offset:20480
	s_waitcnt vmcnt(0) lgkmcnt(0)
	s_barrier
	s_waitcnt lgkmcnt(0)
	v_mfma_f32_32x32x16_bf16 v[16:31], v[64:67], v[68:71], v[16:31]
	v_mfma_f32_32x32x16_bf16 v[0:15], v[64:67], v[72:75], v[0:15]
	ds_read_b128 v[64:67], v83 offset:16384
	v_add_u32_e32 v72, s2, v82
	ds_read_b128 v[68:71], v72
	ds_read_b128 v[72:75], v72 offset:4096
	s_waitcnt lgkmcnt(0)
	v_mfma_f32_32x32x16_bf16 v[48:63], v[64:67], v[68:71], v[48:63]
	v_mfma_f32_32x32x16_bf16 v[32:47], v[64:67], v[72:75], v[32:47]
	ds_read_b128 v[64:67], v83 offset:20480
	s_waitcnt lgkmcnt(0)
	v_mfma_f32_32x32x16_bf16 v[16:31], v[64:67], v[68:71], v[16:31]
	v_mfma_f32_32x32x16_bf16 v[0:15], v[64:67], v[72:75], v[0:15]
	ds_read_b128 v[64:67], v81 offset:16384
	v_add_u32_e32 v72, s2, v80
	ds_read_b128 v[68:71], v72
	ds_read_b128 v[72:75], v72 offset:4096
	s_waitcnt lgkmcnt(0)
	v_mfma_f32_32x32x16_bf16 v[48:63], v[64:67], v[68:71], v[48:63]
	v_mfma_f32_32x32x16_bf16 v[32:47], v[64:67], v[72:75], v[32:47]
	ds_read_b128 v[64:67], v81 offset:20480
	s_waitcnt lgkmcnt(0)
	v_mfma_f32_32x32x16_bf16 v[16:31], v[64:67], v[68:71], v[16:31]
	v_mfma_f32_32x32x16_bf16 v[0:15], v[64:67], v[72:75], v[0:15]
	ds_read_b128 v[64:67], v79 offset:16384
	v_add_u32_e32 v72, s2, v78
	ds_read_b128 v[68:71], v72
	ds_read_b128 v[72:75], v72 offset:4096
	s_waitcnt lgkmcnt(0)
	v_mfma_f32_32x32x16_bf16 v[48:63], v[64:67], v[68:71], v[48:63]
	v_mfma_f32_32x32x16_bf16 v[32:47], v[64:67], v[72:75], v[32:47]
	ds_read_b128 v[64:67], v79 offset:20480
	s_waitcnt lgkmcnt(0)
	v_mfma_f32_32x32x16_bf16 v[16:31], v[64:67], v[68:71], v[16:31]
	v_mfma_f32_32x32x16_bf16 v[0:15], v[64:67], v[72:75], v[0:15]
	ds_read_b128 v[64:67], v77 offset:16384
	v_add_u32_e32 v72, s2, v76
	ds_read_b128 v[68:71], v72
	ds_read_b128 v[72:75], v72 offset:4096
	s_waitcnt lgkmcnt(0)
	v_mfma_f32_32x32x16_bf16 v[48:63], v[64:67], v[68:71], v[48:63]
	v_mfma_f32_32x32x16_bf16 v[32:47], v[64:67], v[72:75], v[32:47]
	ds_read_b128 v[64:67], v77 offset:20480
	s_waitcnt vmcnt(0) lgkmcnt(0)
	s_barrier
	s_waitcnt lgkmcnt(0)
	v_mfma_f32_32x32x16_bf16 v[16:31], v[64:67], v[68:71], v[16:31]
	v_mfma_f32_32x32x16_bf16 v[0:15], v[64:67], v[72:75], v[0:15]

; DEV int stage_next(int s) { return (s == 2 * GS_STAGE) ? 0 : s + GS_STAGE; }
; template <int WAIT0>
; DEV void gk_main(f32x16 (&acc)[2][2], const GTile& t, int s0) {
;     ...
;   vm_wait_bar<WAIT0>();
;   int stc = s0, std_ = stage_next(stage_next(s0));
; #pragma nounroll
;   for (int kt = 0; kt < nk - 2; ++kt) {
;     GK_DMA(std_, kt + 2);
;     GK_COMPUTE(stc);
;     vm_wait_bar<6>();
;     stc = stage_next(stc); std_ = stage_next(std_);
;   }
.LBB0_407:
	s_add_i32 s10, s3, s8
	s_mov_b32 s98, s10
	v_add_u32_e32 v252, s99, v80
	v_add_u32_e32 v253, s99, v81
	ds_read_b128 v[236:239], v252
	ds_read_b128 v[240:243], v252 offset:4096
	ds_read_b128 v[244:247], v253 offset:16384
	ds_read_b128 v[248:251], v253 offset:20480
	s_waitcnt lgkmcnt(4)
	v_mfma_f32_32x32x16_bf16 v[48:63], v[92:95], v[84:87], v[48:63]
	v_mfma_f32_32x32x16_bf16 v[32:47], v[92:95], v[88:91], v[32:47]
	s_mov_b32 m0, s98
	v_lshl_add_u64 v[254:255], v[74:75], 0, v[120:121]
	global_load_lds_dwordx4 v[254:255], off
	v_lshl_add_u64 v[74:75], v[74:75], 0, s[96:97]
	v_mfma_f32_32x32x16_bf16 v[16:31], v[96:99], v[84:87], v[16:31]
	v_mfma_f32_32x32x16_bf16 v[0:15], v[96:99], v[88:91], v[0:15]
	s_add_i32 m0, s98, 0x2000
	v_lshl_add_u64 v[254:255], v[72:73], 0, v[120:121]
	global_load_lds_dwordx4 v[254:255], off
	v_lshl_add_u64 v[72:73], v[72:73], 0, s[96:97]
	v_add_u32_e32 v252, s99, v78
	v_add_u32_e32 v253, s99, v79
	ds_read_b128 v[84:87], v252
	ds_read_b128 v[88:91], v252 offset:4096
	ds_read_b128 v[92:95], v253 offset:16384
	ds_read_b128 v[96:99], v253 offset:20480
	s_waitcnt lgkmcnt(4)
	v_mfma_f32_32x32x16_bf16 v[48:63], v[244:247], v[236:239], v[48:63]
	v_mfma_f32_32x32x16_bf16 v[32:47], v[244:247], v[240:243], v[32:47]
	s_add_i32 m0, s98, 0x4000
	v_lshl_add_u64 v[254:255], v[70:71], 0, v[120:121]
	global_load_lds_dwordx4 v[254:255], off
	v_lshl_add_u64 v[70:71], v[70:71], 0, s[96:97]
	v_mfma_f32_32x32x16_bf16 v[16:31], v[248:251], v[236:239], v[16:31]
	v_mfma_f32_32x32x16_bf16 v[0:15], v[248:251], v[240:243], v[0:15]
	s_add_i32 m0, s98, 0x6000
	v_lshl_add_u64 v[254:255], v[68:69], 0, v[120:121]
	global_load_lds_dwordx4 v[254:255], off
	v_lshl_add_u64 v[68:69], v[68:69], 0, s[96:97]
	v_add_u32_e32 v252, s99, v76
	v_add_u32_e32 v253, s99, v77
	ds_read_b128 v[236:239], v252
	ds_read_b128 v[240:243], v252 offset:4096
	ds_read_b128 v[244:247], v253 offset:16384
	ds_read_b128 v[248:251], v253 offset:20480
	s_waitcnt lgkmcnt(4)
	v_mfma_f32_32x32x16_bf16 v[48:63], v[92:95], v[84:87], v[48:63]
	v_mfma_f32_32x32x16_bf16 v[32:47], v[92:95], v[88:91], v[32:47]
	s_add_i32 m0, s98, 0x8000
	v_lshl_add_u64 v[254:255], v[66:67], 0, v[120:121]
	global_load_lds_dwordx4 v[254:255], off
	v_lshl_add_u64 v[66:67], v[66:67], 0, s[96:97]
	v_mfma_f32_32x32x16_bf16 v[16:31], v[96:99], v[84:87], v[16:31]
	v_mfma_f32_32x32x16_bf16 v[0:15], v[96:99], v[88:91], v[0:15]
	s_add_i32 m0, s98, 0xa000
	v_lshl_add_u64 v[254:255], v[64:65], 0, v[120:121]
	global_load_lds_dwordx4 v[254:255], off
	v_lshl_add_u64 v[64:65], v[64:65], 0, s[96:97]
	s_add_i32 s10, s2, 0xc000
	s_cmp_lg_u32 s2, 0x18000
	s_cselect_b32 s2, s10, 0
	s_waitcnt lgkmcnt(0)
	v_mfma_f32_32x32x16_bf16 v[48:63], v[244:247], v[236:239], v[48:63]
	s_add_i32 s10, s8, 0xc000
	s_waitcnt vmcnt(6) lgkmcnt(0)
	s_barrier
	s_cmp_lg_u32 s8, 0x18000
	s_cselect_b32 s8, s10, 0
	s_add_i32 s9, s9, -1
	s_add_i32 s99, s2, 0
	v_add_u32_e32 v252, s99, v82
	v_add_u32_e32 v253, s99, v83
	ds_read_b128 v[84:87], v252
	ds_read_b128 v[88:91], v252 offset:4096
	ds_read_b128 v[92:95], v253 offset:16384
	ds_read_b128 v[96:99], v253 offset:20480
	v_mfma_f32_32x32x16_bf16 v[32:47], v[244:247], v[240:243], v[32:47]
	s_cmp_lg_u32 s9, 0
	v_mfma_f32_32x32x16_bf16 v[16:31], v[248:251], v[236:239], v[16:31]
	v_mfma_f32_32x32x16_bf16 v[0:15], v[248:251], v[240:243], v[0:15]
	s_cbranch_scc1 .LBB0_407
; DEV int stage_next(int s) { return (s == 2 * GS_STAGE) ? 0 : s + GS_STAGE; }
; template <int WAIT0>
; DEV void gk_main(f32x16 (&acc)[2][2], const GTile& t, int s0) {
;     ...
;   vm_wait_bar<WAIT0>();
;   int stc = s0, std_ = stage_next(stage_next(s0));
; #pragma nounroll
;   for (int kt = 0; kt < nk - 2; ++kt) {
;     GK_DMA(std_, kt + 2);
;     GK_COMPUTE(stc);
;     vm_wait_bar<6>();
;     stc = stage_next(stc); std_ = stage_next(std_);
;   }
;   GK_COMPUTE(stc);
;   vm_wait_bar<0>();
;   stc = stage_next(stc);
;   GK_COMPUTE(stc);
;   vm_wait_bar<0>();
	s_waitcnt lgkmcnt(0)
	s_add_i32 s3, s2, 0
	v_add_u32_e32 v84, s3, v83
	ds_read_b128 v[64:67], v84 offset:16384
	v_add_u32_e32 v72, s3, v82
	ds_read_b128 v[68:71], v72
	ds_read_b128 v[72:75], v72 offset:4096
	s_waitcnt lgkmcnt(0)
	v_mfma_f32_32x32x16_bf16 v[48:63], v[64:67], v[68:71], v[48:63]
	v_mfma_f32_32x32x16_bf16 v[32:47], v[64:67], v[72:75], v[32:47]
	ds_read_b128 v[64:67], v84 offset:20480
	v_add_u32_e32 v84, s3, v81
	s_waitcnt lgkmcnt(0)
	v_mfma_f32_32x32x16_bf16 v[16:31], v[64:67], v[68:71], v[16:31]
	v_mfma_f32_32x32x16_bf16 v[0:15], v[64:67], v[72:75], v[0:15]
	ds_read_b128 v[64:67], v84 offset:16384
	v_add_u32_e32 v72, s3, v80
	ds_read_b128 v[68:71], v72
	ds_read_b128 v[72:75], v72 offset:4096
	s_waitcnt lgkmcnt(0)
	v_mfma_f32_32x32x16_bf16 v[48:63], v[64:67], v[68:71], v[48:63]
	v_mfma_f32_32x32x16_bf16 v[32:47], v[64:67], v[72:75], v[32:47]
	ds_read_b128 v[64:67], v84 offset:20480
	v_add_u32_e32 v84, s3, v79
	s_waitcnt lgkmcnt(0)
	v_mfma_f32_32x32x16_bf16 v[16:31], v[64:67], v[68:71], v[16:31]
	v_mfma_f32_32x32x16_bf16 v[0:15], v[64:67], v[72:75], v[0:15]
	ds_read_b128 v[64:67], v84 offset:16384
	v_add_u32_e32 v72, s3, v78
	ds_read_b128 v[68:71], v72
	ds_read_b128 v[72:75], v72 offset:4096
	s_waitcnt lgkmcnt(0)
	v_mfma_f32_32x32x16_bf16 v[48:63], v[64:67], v[68:71], v[48:63]
	v_mfma_f32_32x32x16_bf16 v[32:47], v[64:67], v[72:75], v[32:47]
	ds_read_b128 v[64:67], v84 offset:20480
	v_add_u32_e32 v84, s3, v77
	s_waitcnt lgkmcnt(0)
	v_mfma_f32_32x32x16_bf16 v[16:31], v[64:67], v[68:71], v[16:31]
	v_mfma_f32_32x32x16_bf16 v[0:15], v[64:67], v[72:75], v[0:15]
	ds_read_b128 v[64:67], v84 offset:16384
	v_add_u32_e32 v72, s3, v76
	ds_read_b128 v[68:71], v72
	ds_read_b128 v[72:75], v72 offset:4096
	s_add_i32 s3, s2, 0xc000
	s_cmp_lg_u32 s2, 0x18000
	s_cselect_b32 s2, s3, 0
	s_waitcnt lgkmcnt(0)
	v_mfma_f32_32x32x16_bf16 v[48:63], v[64:67], v[68:71], v[48:63]
	s_add_i32 s2, s2, 0
	v_add_u32_e32 v83, s2, v83
	v_add_u32_e32 v81, s2, v81
	v_add_u32_e32 v79, s2, v79
	v_add_u32_e32 v77, s2, v77
	v_mfma_f32_32x32x16_bf16 v[32:47], v[64:67], v[72:75], v[32:47]
	ds_read_b128 v[64:67], v84 offset:20480
	s_waitcnt vmcnt(0) lgkmcnt(0)
	s_barrier
	s_waitcnt lgkmcnt(0)
	v_mfma_f32_32x32x16_bf16 v[16:31], v[64:67], v[68:71], v[16:31]
	v_mfma_f32_32x32x16_bf16 v[0:15], v[64:67], v[72:75], v[0:15]
	ds_read_b128 v[64:67], v83 offset:16384
	v_add_u32_e32 v72, s2, v82
	ds_read_b128 v[68:71], v72
	ds_read_b128 v[72:75], v72 offset:4096
	s_waitcnt lgkmcnt(0)
	v_mfma_f32_32x32x16_bf16 v[48:63], v[64:67], v[68:71], v[48:63]
	v_mfma_f32_32x32x16_bf16 v[32:47], v[64:67], v[72:75], v[32:47]
	ds_read_b128 v[64:67], v83 offset:20480
	s_waitcnt lgkmcnt(0)
	v_mfma_f32_32x32x16_bf16 v[16:31], v[64:67], v[68:71], v[16:31]
	v_mfma_f32_32x32x16_bf16 v[0:15], v[64:67], v[72:75], v[0:15]
	ds_read_b128 v[64:67], v81 offset:16384
	v_add_u32_e32 v72, s2, v80
	ds_read_b128 v[68:71], v72
	ds_read_b128 v[72:75], v72 offset:4096
	s_waitcnt lgkmcnt(0)
	v_mfma_f32_32x32x16_bf16 v[48:63], v[64:67], v[68:71], v[48:63]
	v_mfma_f32_32x32x16_bf16 v[32:47], v[64:67], v[72:75], v[32:47]
	ds_read_b128 v[64:67], v81 offset:20480
	s_waitcnt lgkmcnt(0)
	v_mfma_f32_32x32x16_bf16 v[16:31], v[64:67], v[68:71], v[16:31]
	v_mfma_f32_32x32x16_bf16 v[0:15], v[64:67], v[72:75], v[0:15]
	ds_read_b128 v[64:67], v79 offset:16384
	v_add_u32_e32 v72, s2, v78
	ds_read_b128 v[68:71], v72
	ds_read_b128 v[72:75], v72 offset:4096
	s_waitcnt lgkmcnt(0)
	v_mfma_f32_32x32x16_bf16 v[48:63], v[64:67], v[68:71], v[48:63]
	v_mfma_f32_32x32x16_bf16 v[32:47], v[64:67], v[72:75], v[32:47]
	ds_read_b128 v[64:67], v79 offset:20480
	s_waitcnt lgkmcnt(0)
	v_mfma_f32_32x32x16_bf16 v[16:31], v[64:67], v[68:71], v[16:31]
	v_mfma_f32_32x32x16_bf16 v[0:15], v[64:67], v[72:75], v[0:15]
	ds_read_b128 v[64:67], v77 offset:16384
	v_add_u32_e32 v72, s2, v76
	ds_read_b128 v[68:71], v72
	ds_read_b128 v[72:75], v72 offset:4096
	s_waitcnt lgkmcnt(0)
	v_mfma_f32_32x32x16_bf16 v[48:63], v[64:67], v[68:71], v[48:63]
	v_mfma_f32_32x32x16_bf16 v[32:47], v[64:67], v[72:75], v[32:47]
	ds_read_b128 v[64:67], v77 offset:20480
	s_waitcnt vmcnt(0) lgkmcnt(0)
	s_barrier
	s_waitcnt lgkmcnt(0)
	v_mfma_f32_32x32x16_bf16 v[16:31], v[64:67], v[68:71], v[16:31]
	v_mfma_f32_32x32x16_bf16 v[0:15], v[64:67], v[72:75], v[0:15]

; DEV int stage_next(int s) { return (s == 2 * GS_STAGE) ? 0 : s + GS_STAGE; }
; template <int WAIT0>
; DEV void gk_main(f32x16 (&acc)[2][2], const GTile& t, int s0) {
;     ...
;   vm_wait_bar<WAIT0>();
;   int stc = s0, std_ = stage_next(stage_next(s0));
; #pragma nounroll
;   for (int kt = 0; kt < nk - 2; ++kt) {
;     GK_DMA(std_, kt + 2);
;     GK_COMPUTE(stc);
;     vm_wait_bar<6>();
;     stc = stage_next(stc); std_ = stage_next(std_);
;   }
.LBB0_415:
	s_add_i32 s10, s3, s8
	s_mov_b32 s98, s10
	v_add_u32_e32 v252, s99, v80
	v_add_u32_e32 v253, s99, v81
	ds_read_b128 v[236:239], v252
	ds_read_b128 v[240:243], v252 offset:4096
	ds_read_b128 v[244:247], v253 offset:16384
	ds_read_b128 v[248:251], v253 offset:20480
	s_waitcnt lgkmcnt(4)
	v_mfma_f32_32x32x16_bf16 v[48:63], v[92:95], v[84:87], v[48:63]
	v_mfma_f32_32x32x16_bf16 v[32:47], v[92:95], v[88:91], v[32:47]
	s_mov_b32 m0, s98
	v_lshl_add_u64 v[254:255], v[74:75], 0, v[120:121]
	global_load_lds_dwordx4 v[254:255], off
	v_lshl_add_u64 v[74:75], v[74:75], 0, s[96:97]
	v_mfma_f32_32x32x16_bf16 v[16:31], v[96:99], v[84:87], v[16:31]
	v_mfma_f32_32x32x16_bf16 v[0:15], v[96:99], v[88:91], v[0:15]
	s_add_i32 m0, s98, 0x2000
	v_lshl_add_u64 v[254:255], v[72:73], 0, v[120:121]
	global_load_lds_dwordx4 v[254:255], off
	v_lshl_add_u64 v[72:73], v[72:73], 0, s[96:97]
	v_add_u32_e32 v252, s99, v78
	v_add_u32_e32 v253, s99, v79
	ds_read_b128 v[84:87], v252
	ds_read_b128 v[88:91], v252 offset:4096
	ds_read_b128 v[92:95], v253 offset:16384
	ds_read_b128 v[96:99], v253 offset:20480
	s_waitcnt lgkmcnt(4)
	v_mfma_f32_32x32x16_bf16 v[48:63], v[244:247], v[236:239], v[48:63]
	v_mfma_f32_32x32x16_bf16 v[32:47], v[244:247], v[240:243], v[32:47]
	s_add_i32 m0, s98, 0x4000
	v_lshl_add_u64 v[254:255], v[70:71], 0, v[120:121]
	global_load_lds_dwordx4 v[254:255], off
	v_lshl_add_u64 v[70:71], v[70:71], 0, s[96:97]
	v_mfma_f32_32x32x16_bf16 v[16:31], v[248:251], v[236:239], v[16:31]
	v_mfma_f32_32x32x16_bf16 v[0:15], v[248:251], v[240:243], v[0:15]
	s_add_i32 m0, s98, 0x6000
	v_lshl_add_u64 v[254:255], v[68:69], 0, v[120:121]
	global_load_lds_dwordx4 v[254:255], off
	v_lshl_add_u64 v[68:69], v[68:69], 0, s[96:97]
	v_add_u32_e32 v252, s99, v76
	v_add_u32_e32 v253, s99, v77
	ds_read_b128 v[236:239], v252
	ds_read_b128 v[240:243], v252 offset:4096
	ds_read_b128 v[244:247], v253 offset:16384
	ds_read_b128 v[248:251], v253 offset:20480
	s_waitcnt lgkmcnt(4)
	v_mfma_f32_32x32x16_bf16 v[48:63], v[92:95], v[84:87], v[48:63]
	v_mfma_f32_32x32x16_bf16 v[32:47], v[92:95], v[88:91], v[32:47]
	s_add_i32 m0, s98, 0x8000
	v_lshl_add_u64 v[254:255], v[66:67], 0, v[120:121]
	global_load_lds_dwordx4 v[254:255], off
	v_lshl_add_u64 v[66:67], v[66:67], 0, s[96:97]
	v_mfma_f32_32x32x16_bf16 v[16:31], v[96:99], v[84:87], v[16:31]
	v_mfma_f32_32x32x16_bf16 v[0:15], v[96:99], v[88:91], v[0:15]
	s_add_i32 m0, s98, 0xa000
	v_lshl_add_u64 v[254:255], v[64:65], 0, v[120:121]
	global_load_lds_dwordx4 v[254:255], off
	v_lshl_add_u64 v[64:65], v[64:65], 0, s[96:97]
	s_add_i32 s10, s2, 0xc000
	s_cmp_lg_u32 s2, 0x18000
	s_cselect_b32 s2, s10, 0
	s_waitcnt lgkmcnt(0)
	v_mfma_f32_32x32x16_bf16 v[48:63], v[244:247], v[236:239], v[48:63]
	s_add_i32 s10, s8, 0xc000
	s_waitcnt vmcnt(6) lgkmcnt(0)
	s_barrier
	s_cmp_lg_u32 s8, 0x18000
	s_cselect_b32 s8, s10, 0
	s_add_i32 s9, s9, -1
	s_add_i32 s99, s2, 0
	v_add_u32_e32 v252, s99, v82
	v_add_u32_e32 v253, s99, v83
	ds_read_b128 v[84:87], v252
	ds_read_b128 v[88:91], v252 offset:4096
	ds_read_b128 v[92:95], v253 offset:16384
	ds_read_b128 v[96:99], v253 offset:20480
	v_mfma_f32_32x32x16_bf16 v[32:47], v[244:247], v[240:243], v[32:47]
	s_cmp_lg_u32 s9, 0
	v_mfma_f32_32x32x16_bf16 v[16:31], v[248:251], v[236:239], v[16:31]
	v_mfma_f32_32x32x16_bf16 v[0:15], v[248:251], v[240:243], v[0:15]
	s_cbranch_scc1 .LBB0_415
; DEV int stage_next(int s) { return (s == 2 * GS_STAGE) ? 0 : s + GS_STAGE; }
; template <int WAIT0>
; DEV void gk_main(f32x16 (&acc)[2][2], const GTile& t, int s0) {
;     ...
;   vm_wait_bar<WAIT0>();
;   int stc = s0, std_ = stage_next(stage_next(s0));
; #pragma nounroll
;   for (int kt = 0; kt < nk - 2; ++kt) {
;     GK_DMA(std_, kt + 2);
;     GK_COMPUTE(stc);
;     vm_wait_bar<6>();
;     stc = stage_next(stc); std_ = stage_next(std_);
;   }
;   GK_COMPUTE(stc);
;   vm_wait_bar<0>();
;   stc = stage_next(stc);
;   GK_COMPUTE(stc);
;   vm_wait_bar<0>();
; template <int WAIT_E, int WAIT_O, class TileFn, class EpiFn>
; DEV void gemm_seq(int ntiles, TileFn tf, EpiFn epi) {
;     ...
;   for (int i = 0; i < ntiles; ++i) {
;     f32x16 acc[2][2]; acc_zero(acc);
;     if (i == 0) gk_main<6>(acc, cur, s0);
;     else if (i & 1) gk_main<WAIT_O>(acc, cur, s0);
;     else gk_main<WAIT_E>(acc, cur, s0);
;     const int sn = stage_next(s0);
;     if (i + 1 < ntiles) { cur = tf(i + 1); gk_issue2(cur, sn); }
;     epi(i, acc, s0);
;     s0 = sn;
;   }
	s_waitcnt lgkmcnt(0)
	s_add_i32 s3, s2, 0
	v_add_u32_e32 v84, s3, v83
	ds_read_b128 v[64:67], v84 offset:16384
	v_add_u32_e32 v72, s3, v82
	ds_read_b128 v[68:71], v72
	ds_read_b128 v[72:75], v72 offset:4096
	s_waitcnt lgkmcnt(0)
	v_mfma_f32_32x32x16_bf16 v[48:63], v[64:67], v[68:71], v[48:63]
	v_mfma_f32_32x32x16_bf16 v[32:47], v[64:67], v[72:75], v[32:47]
	ds_read_b128 v[64:67], v84 offset:20480
	v_add_u32_e32 v84, s3, v81
	s_waitcnt lgkmcnt(0)
	v_mfma_f32_32x32x16_bf16 v[16:31], v[64:67], v[68:71], v[16:31]
	v_mfma_f32_32x32x16_bf16 v[0:15], v[64:67], v[72:75], v[0:15]
	ds_read_b128 v[64:67], v84 offset:16384
	v_add_u32_e32 v72, s3, v80
	ds_read_b128 v[68:71], v72
	ds_read_b128 v[72:75], v72 offset:4096
	s_waitcnt lgkmcnt(0)
	v_mfma_f32_32x32x16_bf16 v[48:63], v[64:67], v[68:71], v[48:63]
	v_mfma_f32_32x32x16_bf16 v[32:47], v[64:67], v[72:75], v[32:47]
	ds_read_b128 v[64:67], v84 offset:20480
	v_add_u32_e32 v84, s3, v79
	s_waitcnt lgkmcnt(0)
	v_mfma_f32_32x32x16_bf16 v[16:31], v[64:67], v[68:71], v[16:31]
	v_mfma_f32_32x32x16_bf16 v[0:15], v[64:67], v[72:75], v[0:15]
	ds_read_b128 v[64:67], v84 offset:16384
	v_add_u32_e32 v72, s3, v78
	ds_read_b128 v[68:71], v72
	ds_read_b128 v[72:75], v72 offset:4096
	s_waitcnt lgkmcnt(0)
	v_mfma_f32_32x32x16_bf16 v[48:63], v[64:67], v[68:71], v[48:63]
	v_mfma_f32_32x32x16_bf16 v[32:47], v[64:67], v[72:75], v[32:47]
	ds_read_b128 v[64:67], v84 offset:20480
	v_add_u32_e32 v84, s3, v77
	s_waitcnt lgkmcnt(0)
	v_mfma_f32_32x32x16_bf16 v[16:31], v[64:67], v[68:71], v[16:31]
	v_mfma_f32_32x32x16_bf16 v[0:15], v[64:67], v[72:75], v[0:15]
	ds_read_b128 v[64:67], v84 offset:16384
	v_add_u32_e32 v72, s3, v76
	ds_read_b128 v[68:71], v72
	ds_read_b128 v[72:75], v72 offset:4096
	s_add_i32 s3, s2, 0xc000
	s_cmp_lg_u32 s2, 0x18000
	s_cselect_b32 s2, s3, 0
	s_waitcnt lgkmcnt(0)
	v_mfma_f32_32x32x16_bf16 v[48:63], v[64:67], v[68:71], v[48:63]
	s_add_i32 s2, s2, 0
	v_add_u32_e32 v83, s2, v83
	v_add_u32_e32 v81, s2, v81
	v_add_u32_e32 v79, s2, v79
	v_add_u32_e32 v77, s2, v77
	v_mfma_f32_32x32x16_bf16 v[32:47], v[64:67], v[72:75], v[32:47]
	ds_read_b128 v[64:67], v84 offset:20480
	s_waitcnt vmcnt(0) lgkmcnt(0)
	s_barrier
	s_waitcnt lgkmcnt(0)
	v_mfma_f32_32x32x16_bf16 v[16:31], v[64:67], v[68:71], v[16:31]
	v_mfma_f32_32x32x16_bf16 v[0:15], v[64:67], v[72:75], v[0:15]
	ds_read_b128 v[64:67], v83 offset:16384
	v_add_u32_e32 v72, s2, v82
	ds_read_b128 v[68:71], v72
	ds_read_b128 v[72:75], v72 offset:4096
	s_waitcnt lgkmcnt(0)
	v_mfma_f32_32x32x16_bf16 v[48:63], v[64:67], v[68:71], v[48:63]
	v_mfma_f32_32x32x16_bf16 v[32:47], v[64:67], v[72:75], v[32:47]
	ds_read_b128 v[64:67], v83 offset:20480
	s_waitcnt lgkmcnt(0)
	v_mfma_f32_32x32x16_bf16 v[16:31], v[64:67], v[68:71], v[16:31]
	v_mfma_f32_32x32x16_bf16 v[0:15], v[64:67], v[72:75], v[0:15]
	ds_read_b128 v[64:67], v81 offset:16384
	v_add_u32_e32 v72, s2, v80
	ds_read_b128 v[68:71], v72
	ds_read_b128 v[72:75], v72 offset:4096
	s_waitcnt lgkmcnt(0)
	v_mfma_f32_32x32x16_bf16 v[48:63], v[64:67], v[68:71], v[48:63]
	v_mfma_f32_32x32x16_bf16 v[32:47], v[64:67], v[72:75], v[32:47]
	ds_read_b128 v[64:67], v81 offset:20480
	s_waitcnt lgkmcnt(0)
	v_mfma_f32_32x32x16_bf16 v[16:31], v[64:67], v[68:71], v[16:31]
	v_mfma_f32_32x32x16_bf16 v[0:15], v[64:67], v[72:75], v[0:15]
	ds_read_b128 v[64:67], v79 offset:16384
	v_add_u32_e32 v72, s2, v78
	ds_read_b128 v[68:71], v72
	ds_read_b128 v[72:75], v72 offset:4096
	s_waitcnt lgkmcnt(0)
	v_mfma_f32_32x32x16_bf16 v[48:63], v[64:67], v[68:71], v[48:63]
	v_mfma_f32_32x32x16_bf16 v[32:47], v[64:67], v[72:75], v[32:47]
	ds_read_b128 v[64:67], v79 offset:20480
	s_waitcnt lgkmcnt(0)
	v_mfma_f32_32x32x16_bf16 v[16:31], v[64:67], v[68:71], v[16:31]
	v_mfma_f32_32x32x16_bf16 v[0:15], v[64:67], v[72:75], v[0:15]
	ds_read_b128 v[64:67], v77 offset:16384
	v_add_u32_e32 v72, s2, v76
	ds_read_b128 v[68:71], v72
	ds_read_b128 v[72:75], v72 offset:4096
	s_waitcnt lgkmcnt(0)
	v_mfma_f32_32x32x16_bf16 v[48:63], v[64:67], v[68:71], v[48:63]
	v_mfma_f32_32x32x16_bf16 v[32:47], v[64:67], v[72:75], v[32:47]
	ds_read_b128 v[64:67], v77 offset:20480
	s_waitcnt vmcnt(0) lgkmcnt(0)
	s_barrier
	s_waitcnt lgkmcnt(0)
	v_mfma_f32_32x32x16_bf16 v[16:31], v[64:67], v[68:71], v[16:31]
	v_mfma_f32_32x32x16_bf16 v[0:15], v[64:67], v[72:75], v[0:15]
	s_add_i32 s2, s19, 1
	s_cmp_eq_u32 s19, 7
	s_mov_b64 s[8:9], 0
	s_cbranch_scc1 .LBB0_411

; DEV int stage_next(int s) { return (s == 2 * GS_STAGE) ? 0 : s + GS_STAGE; }
; template <int WAIT0>
; DEV void gk_main(f32x16 (&acc)[2][2], const GTile& t, int s0) {
;     ...
;   vm_wait_bar<WAIT0>();
;   int stc = s0, std_ = stage_next(stage_next(s0));
; #pragma nounroll
;   for (int kt = 0; kt < nk - 2; ++kt) {
;     GK_DMA(std_, kt + 2);
;     GK_COMPUTE(stc);
;     vm_wait_bar<6>();
;     stc = stage_next(stc); std_ = stage_next(std_);
;   }
.LBB0_437:
	s_add_i32 s12, s10, s11
	s_mov_b32 s98, s12
	s_mov_b64 s[100:101], s[6:7]
	v_add_u32_e32 v252, s99, v80
	v_add_u32_e32 v253, s99, v81
	ds_read_b128 v[236:239], v252
	ds_read_b128 v[240:243], v252 offset:4096
	ds_read_b128 v[244:247], v253 offset:16384
	ds_read_b128 v[248:251], v253 offset:20480
	s_waitcnt lgkmcnt(4)
	v_mfma_f32_32x32x16_bf16 v[48:63], v[92:95], v[84:87], v[48:63]
	v_mfma_f32_32x32x16_bf16 v[16:31], v[92:95], v[88:91], v[16:31]
	s_mov_b32 m0, s98
	v_lshl_add_u64 v[254:255], v[74:75], 0, s[100:101]
	global_load_lds_dwordx4 v[254:255], off
	v_mfma_f32_32x32x16_bf16 v[32:47], v[96:99], v[84:87], v[32:47]
	v_mfma_f32_32x32x16_bf16 v[0:15], v[96:99], v[88:91], v[0:15]
	s_add_i32 m0, s98, 0x2000
	v_lshl_add_u64 v[254:255], v[72:73], 0, s[100:101]
	global_load_lds_dwordx4 v[254:255], off
	v_add_u32_e32 v252, s99, v78
	v_add_u32_e32 v253, s99, v79
	ds_read_b128 v[84:87], v252
	ds_read_b128 v[88:91], v252 offset:4096
	ds_read_b128 v[92:95], v253 offset:16384
	ds_read_b128 v[96:99], v253 offset:20480
	s_waitcnt lgkmcnt(4)
	v_mfma_f32_32x32x16_bf16 v[48:63], v[244:247], v[236:239], v[48:63]
	v_mfma_f32_32x32x16_bf16 v[16:31], v[244:247], v[240:243], v[16:31]
	s_add_i32 m0, s98, 0x4000
	v_lshl_add_u64 v[254:255], v[70:71], 0, s[100:101]
	global_load_lds_dwordx4 v[254:255], off
	v_mfma_f32_32x32x16_bf16 v[32:47], v[248:251], v[236:239], v[32:47]
	v_mfma_f32_32x32x16_bf16 v[0:15], v[248:251], v[240:243], v[0:15]
	s_add_i32 m0, s98, 0x6000
	v_lshl_add_u64 v[254:255], v[68:69], 0, s[100:101]
	global_load_lds_dwordx4 v[254:255], off
	v_add_u32_e32 v252, s99, v76
	v_add_u32_e32 v253, s99, v77
	ds_read_b128 v[236:239], v252
	ds_read_b128 v[240:243], v252 offset:4096
	ds_read_b128 v[244:247], v253 offset:16384
	ds_read_b128 v[248:251], v253 offset:20480
	s_waitcnt lgkmcnt(4)
	v_mfma_f32_32x32x16_bf16 v[48:63], v[92:95], v[84:87], v[48:63]
	v_mfma_f32_32x32x16_bf16 v[16:31], v[92:95], v[88:91], v[16:31]
	s_add_i32 m0, s98, 0x8000
	v_lshl_add_u64 v[254:255], v[66:67], 0, s[100:101]
	global_load_lds_dwordx4 v[254:255], off
	v_mfma_f32_32x32x16_bf16 v[32:47], v[96:99], v[84:87], v[32:47]
	v_mfma_f32_32x32x16_bf16 v[0:15], v[96:99], v[88:91], v[0:15]
	s_add_i32 m0, s98, 0xa000
	v_lshl_add_u64 v[254:255], v[64:65], 0, s[100:101]
	global_load_lds_dwordx4 v[254:255], off
	s_add_i32 s12, s3, 0xc000
	s_cmp_lg_u32 s3, 0x18000
	s_cselect_b32 s3, s12, 0
	s_waitcnt lgkmcnt(0)
	v_mfma_f32_32x32x16_bf16 v[48:63], v[244:247], v[236:239], v[48:63]
	s_add_i32 s12, s11, 0xc000
	s_cmp_lg_u32 s11, 0x18000
	s_waitcnt vmcnt(6) lgkmcnt(0)
	s_barrier
	s_cselect_b32 s11, s12, 0
	s_add_u32 s6, s6, 0x80
	s_add_i32 s99, s3, 0
	v_add_u32_e32 v252, s99, v82
	v_add_u32_e32 v253, s99, v83
	ds_read_b128 v[84:87], v252
	ds_read_b128 v[88:91], v252 offset:4096
	ds_read_b128 v[92:95], v253 offset:16384
	ds_read_b128 v[96:99], v253 offset:20480
	v_mfma_f32_32x32x16_bf16 v[16:31], v[244:247], v[240:243], v[16:31]
	s_addc_u32 s7, s7, 0
	s_cmpk_lg_i32 s6, 0x700
	v_mfma_f32_32x32x16_bf16 v[32:47], v[248:251], v[236:239], v[32:47]
	v_mfma_f32_32x32x16_bf16 v[0:15], v[248:251], v[240:243], v[0:15]
	s_cbranch_scc1 .LBB0_437
; DEV int stage_next(int s) { return (s == 2 * GS_STAGE) ? 0 : s + GS_STAGE; }
; template <int WAIT0>
; DEV void gk_main(f32x16 (&acc)[2][2], const GTile& t, int s0) {
;     ...
;   vm_wait_bar<WAIT0>();
;   int stc = s0, std_ = stage_next(stage_next(s0));
; #pragma nounroll
;   for (int kt = 0; kt < nk - 2; ++kt) {
;     GK_DMA(std_, kt + 2);
;     GK_COMPUTE(stc);
;     vm_wait_bar<6>();
;     stc = stage_next(stc); std_ = stage_next(std_);
;   }
;   GK_COMPUTE(stc);
;   vm_wait_bar<0>();
;   stc = stage_next(stc);
;   GK_COMPUTE(stc);
;   vm_wait_bar<0>();
	s_waitcnt lgkmcnt(0)
	s_add_i32 s6, s3, 0
	v_add_u32_e32 v84, s6, v83
	ds_read_b128 v[64:67], v84 offset:16384
	v_add_u32_e32 v72, s6, v82
	ds_read_b128 v[68:71], v72
	ds_read_b128 v[72:75], v72 offset:4096
	s_waitcnt lgkmcnt(0)
	v_mfma_f32_32x32x16_bf16 v[48:63], v[64:67], v[68:71], v[48:63]
	v_mfma_f32_32x32x16_bf16 v[16:31], v[64:67], v[72:75], v[16:31]
	ds_read_b128 v[64:67], v84 offset:20480
	v_add_u32_e32 v84, s6, v81
	s_waitcnt lgkmcnt(0)
	v_mfma_f32_32x32x16_bf16 v[32:47], v[64:67], v[68:71], v[32:47]
	v_mfma_f32_32x32x16_bf16 v[0:15], v[64:67], v[72:75], v[0:15]
	ds_read_b128 v[64:67], v84 offset:16384
	v_add_u32_e32 v72, s6, v80
	ds_read_b128 v[68:71], v72
	ds_read_b128 v[72:75], v72 offset:4096
	s_waitcnt lgkmcnt(0)
	v_mfma_f32_32x32x16_bf16 v[48:63], v[64:67], v[68:71], v[48:63]
	v_mfma_f32_32x32x16_bf16 v[16:31], v[64:67], v[72:75], v[16:31]
	ds_read_b128 v[64:67], v84 offset:20480
	v_add_u32_e32 v84, s6, v79
	s_waitcnt lgkmcnt(0)
	v_mfma_f32_32x32x16_bf16 v[32:47], v[64:67], v[68:71], v[32:47]
	v_mfma_f32_32x32x16_bf16 v[0:15], v[64:67], v[72:75], v[0:15]
	ds_read_b128 v[64:67], v84 offset:16384
	v_add_u32_e32 v72, s6, v78
	ds_read_b128 v[68:71], v72
	ds_read_b128 v[72:75], v72 offset:4096
	s_waitcnt lgkmcnt(0)
	v_mfma_f32_32x32x16_bf16 v[48:63], v[64:67], v[68:71], v[48:63]
	v_mfma_f32_32x32x16_bf16 v[16:31], v[64:67], v[72:75], v[16:31]
	ds_read_b128 v[64:67], v84 offset:20480
	v_add_u32_e32 v84, s6, v77
	s_waitcnt lgkmcnt(0)
	v_mfma_f32_32x32x16_bf16 v[32:47], v[64:67], v[68:71], v[32:47]
	v_mfma_f32_32x32x16_bf16 v[0:15], v[64:67], v[72:75], v[0:15]
	ds_read_b128 v[64:67], v84 offset:16384
	v_add_u32_e32 v72, s6, v76
	ds_read_b128 v[68:71], v72
	ds_read_b128 v[72:75], v72 offset:4096
	s_add_i32 s6, s3, 0xc000
	s_cmp_lg_u32 s3, 0x18000
	s_cselect_b32 s3, s6, 0
	s_waitcnt lgkmcnt(0)
	v_mfma_f32_32x32x16_bf16 v[48:63], v[64:67], v[68:71], v[48:63]
	s_add_i32 s3, s3, 0
	v_add_u32_e32 v83, s3, v83
	v_add_u32_e32 v81, s3, v81
	v_add_u32_e32 v79, s3, v79
	v_add_u32_e32 v77, s3, v77
	v_mfma_f32_32x32x16_bf16 v[16:31], v[64:67], v[72:75], v[16:31]
	ds_read_b128 v[64:67], v84 offset:20480
	s_waitcnt vmcnt(0) lgkmcnt(0)
	s_barrier
	s_waitcnt lgkmcnt(0)
	v_mfma_f32_32x32x16_bf16 v[32:47], v[64:67], v[68:71], v[32:47]
	v_mfma_f32_32x32x16_bf16 v[0:15], v[64:67], v[72:75], v[0:15]
	ds_read_b128 v[64:67], v83 offset:16384
	v_add_u32_e32 v72, s3, v82
	ds_read_b128 v[68:71], v72
	ds_read_b128 v[72:75], v72 offset:4096
	s_waitcnt lgkmcnt(0)
	v_mfma_f32_32x32x16_bf16 v[48:63], v[64:67], v[68:71], v[48:63]
	v_mfma_f32_32x32x16_bf16 v[16:31], v[64:67], v[72:75], v[16:31]
	ds_read_b128 v[64:67], v83 offset:20480
	s_waitcnt lgkmcnt(0)
	v_mfma_f32_32x32x16_bf16 v[32:47], v[64:67], v[68:71], v[32:47]
	v_mfma_f32_32x32x16_bf16 v[0:15], v[64:67], v[72:75], v[0:15]
	ds_read_b128 v[64:67], v81 offset:16384
	v_add_u32_e32 v72, s3, v80
	ds_read_b128 v[68:71], v72
	ds_read_b128 v[72:75], v72 offset:4096
	s_waitcnt lgkmcnt(0)
	v_mfma_f32_32x32x16_bf16 v[48:63], v[64:67], v[68:71], v[48:63]
	v_mfma_f32_32x32x16_bf16 v[16:31], v[64:67], v[72:75], v[16:31]
	ds_read_b128 v[64:67], v81 offset:20480
	s_waitcnt lgkmcnt(0)
	v_mfma_f32_32x32x16_bf16 v[32:47], v[64:67], v[68:71], v[32:47]
	v_mfma_f32_32x32x16_bf16 v[0:15], v[64:67], v[72:75], v[0:15]
	ds_read_b128 v[64:67], v79 offset:16384
	v_add_u32_e32 v72, s3, v78
	ds_read_b128 v[68:71], v72
	ds_read_b128 v[72:75], v72 offset:4096
	s_waitcnt lgkmcnt(0)
	v_mfma_f32_32x32x16_bf16 v[48:63], v[64:67], v[68:71], v[48:63]
	v_mfma_f32_32x32x16_bf16 v[16:31], v[64:67], v[72:75], v[16:31]
	ds_read_b128 v[64:67], v79 offset:20480
	s_waitcnt lgkmcnt(0)
	v_mfma_f32_32x32x16_bf16 v[32:47], v[64:67], v[68:71], v[32:47]
	v_mfma_f32_32x32x16_bf16 v[0:15], v[64:67], v[72:75], v[0:15]
	ds_read_b128 v[64:67], v77 offset:16384
	v_add_u32_e32 v72, s3, v76
	ds_read_b128 v[68:71], v72
	ds_read_b128 v[72:75], v72 offset:4096
	s_waitcnt lgkmcnt(0)
	v_mfma_f32_32x32x16_bf16 v[48:63], v[64:67], v[68:71], v[48:63]
	v_mfma_f32_32x32x16_bf16 v[16:31], v[64:67], v[72:75], v[16:31]
	ds_read_b128 v[64:67], v77 offset:20480
	s_waitcnt vmcnt(0) lgkmcnt(0)
	s_barrier
	s_waitcnt lgkmcnt(0)
	v_mfma_f32_32x32x16_bf16 v[32:47], v[64:67], v[68:71], v[32:47]
	v_mfma_f32_32x32x16_bf16 v[0:15], v[64:67], v[72:75], v[0:15]
	s_add_i32 s3, s2, 1
	s_cmp_eq_u32 s2, 7
	s_cbranch_scc1 .LBB0_423

; DEV int stage_next(int s) { return (s == 2 * GS_STAGE) ? 0 : s + GS_STAGE; }
; template <int WAIT0>
; DEV void gk_main(f32x16 (&acc)[2][2], const GTile& t, int s0) {
;     ...
;   vm_wait_bar<WAIT0>();
;   int stc = s0, std_ = stage_next(stage_next(s0));
; #pragma nounroll
;   for (int kt = 0; kt < nk - 2; ++kt) {
;     GK_DMA(std_, kt + 2);
;     GK_COMPUTE(stc);
;     vm_wait_bar<6>();
;     stc = stage_next(stc); std_ = stage_next(std_);
;   }
.LBB0_715:
	s_add_i32 s14, s3, s13
	s_mov_b32 s98, s14
	s_mov_b64 s[100:101], s[6:7]
	v_add_u32_e32 v101, s99, v82
	v_add_u32_e32 v100, s99, v79
	s_add_i32 s14, s2, 0xc000
	s_cmp_lg_u32 s2, 0x18000
	s_cselect_b32 s2, s14, 0
	s_add_i32 s14, s13, 0xc000
	s_cmp_lg_u32 s13, 0x18000
	s_cselect_b32 s13, s14, 0
	s_add_u32 s6, s6, 0x80
	s_addc_u32 s7, s7, 0
	ds_read_b128 v[236:239], v101 offset:16384
	ds_read_b128 v[240:243], v100
	ds_read_b128 v[244:247], v100 offset:4096
	ds_read_b128 v[248:251], v101 offset:20480
	s_waitcnt lgkmcnt(4)
	v_mfma_f32_32x32x16_bf16 v[48:63], v[84:87], v[88:91], v[48:63]
	v_mfma_f32_32x32x16_bf16 v[16:31], v[84:87], v[92:95], v[16:31]
	s_mov_b32 m0, s98
	v_lshl_add_u64 v[254:255], v[74:75], 0, s[100:101]
	global_load_lds_dwordx4 v[254:255], off
	v_mfma_f32_32x32x16_bf16 v[32:47], v[96:99], v[88:91], v[32:47]
	v_mfma_f32_32x32x16_bf16 v[0:15], v[96:99], v[92:95], v[0:15]
	s_add_i32 m0, s98, 0x2000
	v_lshl_add_u64 v[254:255], v[72:73], 0, s[100:101]
	global_load_lds_dwordx4 v[254:255], off
	v_add_u32_e32 v101, s99, v80
	v_add_u32_e32 v100, s99, v77
	ds_read_b128 v[84:87], v101 offset:16384
	ds_read_b128 v[88:91], v100
	ds_read_b128 v[92:95], v100 offset:4096
	ds_read_b128 v[96:99], v101 offset:20480
	s_waitcnt lgkmcnt(4)
	v_mfma_f32_32x32x16_bf16 v[48:63], v[236:239], v[240:243], v[48:63]
	v_mfma_f32_32x32x16_bf16 v[16:31], v[236:239], v[244:247], v[16:31]
	s_add_i32 m0, s98, 0x4000
	v_lshl_add_u64 v[254:255], v[70:71], 0, s[100:101]
	global_load_lds_dwordx4 v[254:255], off
	v_mfma_f32_32x32x16_bf16 v[32:47], v[248:251], v[240:243], v[32:47]
	v_mfma_f32_32x32x16_bf16 v[0:15], v[248:251], v[244:247], v[0:15]
	s_add_i32 m0, s98, 0x6000
	v_lshl_add_u64 v[254:255], v[68:69], 0, s[100:101]
	global_load_lds_dwordx4 v[254:255], off
	v_add_u32_e32 v101, s99, v78
	v_add_u32_e32 v100, s99, v76
	ds_read_b128 v[236:239], v101 offset:16384
	ds_read_b128 v[240:243], v100
	ds_read_b128 v[244:247], v100 offset:4096
	ds_read_b128 v[248:251], v101 offset:20480
	s_waitcnt lgkmcnt(4)
	v_mfma_f32_32x32x16_bf16 v[48:63], v[84:87], v[88:91], v[48:63]
	v_mfma_f32_32x32x16_bf16 v[16:31], v[84:87], v[92:95], v[16:31]
	s_add_i32 m0, s98, 0x8000
	v_lshl_add_u64 v[254:255], v[66:67], 0, s[100:101]
	global_load_lds_dwordx4 v[254:255], off
	v_mfma_f32_32x32x16_bf16 v[32:47], v[96:99], v[88:91], v[32:47]
	v_mfma_f32_32x32x16_bf16 v[0:15], v[96:99], v[92:95], v[0:15]
	s_add_i32 m0, s98, 0xa000
	v_lshl_add_u64 v[254:255], v[64:65], 0, s[100:101]
	global_load_lds_dwordx4 v[254:255], off
	s_waitcnt vmcnt(6) lgkmcnt(0)
	s_barrier
	s_add_i32 s99, s2, 0
	v_add_u32_e32 v253, s99, v81
	v_add_u32_e32 v252, s99, v83
	ds_read_b128 v[84:87], v252 offset:16384
	ds_read_b128 v[88:91], v253
	ds_read_b128 v[92:95], v253 offset:4096
	ds_read_b128 v[96:99], v252 offset:20480
	s_waitcnt lgkmcnt(4)
	v_mfma_f32_32x32x16_bf16 v[48:63], v[236:239], v[240:243], v[48:63]
	v_mfma_f32_32x32x16_bf16 v[16:31], v[236:239], v[244:247], v[16:31]
	v_mfma_f32_32x32x16_bf16 v[32:47], v[248:251], v[240:243], v[32:47]
	v_mfma_f32_32x32x16_bf16 v[0:15], v[248:251], v[244:247], v[0:15]
	s_cmpk_lg_i32 s6, 0x700
	s_cbranch_scc1 .LBB0_715
; DEV int stage_next(int s) { return (s == 2 * GS_STAGE) ? 0 : s + GS_STAGE; }
; template <int WAIT0>
; DEV void gk_main(f32x16 (&acc)[2][2], const GTile& t, int s0) {
;     ...
;   vm_wait_bar<WAIT0>();
;   int stc = s0, std_ = stage_next(stage_next(s0));
; #pragma nounroll
;   for (int kt = 0; kt < nk - 2; ++kt) {
;     GK_DMA(std_, kt + 2);
;     GK_COMPUTE(stc);
;     vm_wait_bar<6>();
;     stc = stage_next(stc); std_ = stage_next(std_);
;   }
;   GK_COMPUTE(stc);
;   vm_wait_bar<0>();
;   stc = stage_next(stc);
;   GK_COMPUTE(stc);
;   vm_wait_bar<0>();
	s_waitcnt lgkmcnt(0)
	s_add_i32 s3, s2, 0
	v_add_u32_e32 v84, s3, v83
	ds_read_b128 v[64:67], v84 offset:16384
	v_add_u32_e32 v72, s3, v81
	ds_read_b128 v[68:71], v72
	ds_read_b128 v[72:75], v72 offset:4096
	ds_read_b128 v[84:87], v84 offset:20480
	s_mov_b64 s[6:7], 0
	s_waitcnt lgkmcnt(0)
	v_mfma_f32_32x32x16_bf16 v[32:47], v[84:87], v[68:71], v[32:47]
	v_mfma_f32_32x32x16_bf16 v[0:15], v[84:87], v[72:75], v[0:15]
	v_add_u32_e32 v84, s3, v82
	v_mfma_f32_32x32x16_bf16 v[48:63], v[64:67], v[68:71], v[48:63]
	v_mfma_f32_32x32x16_bf16 v[16:31], v[64:67], v[72:75], v[16:31]
	ds_read_b128 v[64:67], v84 offset:16384
	v_add_u32_e32 v72, s3, v79
	ds_read_b128 v[68:71], v72
	ds_read_b128 v[72:75], v72 offset:4096
	ds_read_b128 v[84:87], v84 offset:20480
	s_waitcnt lgkmcnt(0)
	v_mfma_f32_32x32x16_bf16 v[32:47], v[84:87], v[68:71], v[32:47]
	v_mfma_f32_32x32x16_bf16 v[0:15], v[84:87], v[72:75], v[0:15]
	v_add_u32_e32 v84, s3, v80
	v_mfma_f32_32x32x16_bf16 v[48:63], v[64:67], v[68:71], v[48:63]
	v_mfma_f32_32x32x16_bf16 v[16:31], v[64:67], v[72:75], v[16:31]
	ds_read_b128 v[64:67], v84 offset:16384
	v_add_u32_e32 v72, s3, v77
	ds_read_b128 v[68:71], v72
	ds_read_b128 v[72:75], v72 offset:4096
	ds_read_b128 v[84:87], v84 offset:20480
	s_waitcnt lgkmcnt(0)
	v_mfma_f32_32x32x16_bf16 v[32:47], v[84:87], v[68:71], v[32:47]
	v_mfma_f32_32x32x16_bf16 v[0:15], v[84:87], v[72:75], v[0:15]
	v_add_u32_e32 v84, s3, v78
	v_mfma_f32_32x32x16_bf16 v[48:63], v[64:67], v[68:71], v[48:63]
	v_mfma_f32_32x32x16_bf16 v[16:31], v[64:67], v[72:75], v[16:31]
	ds_read_b128 v[64:67], v84 offset:16384
	v_add_u32_e32 v72, s3, v76
	s_add_i32 s3, s2, 0xc000
	ds_read_b128 v[68:71], v72
	ds_read_b128 v[72:75], v72 offset:4096
	ds_read_b128 v[84:87], v84 offset:20480
	s_cmp_lg_u32 s2, 0x18000
	s_cselect_b32 s2, s3, 0
	s_add_i32 s2, s2, 0
	s_waitcnt vmcnt(0) lgkmcnt(0)
	s_barrier
	v_add_u32_e32 v83, s2, v83
	s_waitcnt lgkmcnt(0)
	v_mfma_f32_32x32x16_bf16 v[48:63], v[64:67], v[68:71], v[48:63]
	v_mfma_f32_32x32x16_bf16 v[16:31], v[64:67], v[72:75], v[16:31]
	ds_read_b128 v[64:67], v83 offset:16384
	v_mfma_f32_32x32x16_bf16 v[32:47], v[84:87], v[68:71], v[32:47]
	v_mfma_f32_32x32x16_bf16 v[0:15], v[84:87], v[72:75], v[0:15]
	v_add_u32_e32 v72, s2, v81
	ds_read_b128 v[68:71], v72
	ds_read_b128 v[72:75], v72 offset:4096
	ds_read_b128 v[84:87], v83 offset:20480
	v_add_u32_e32 v81, s2, v82
	s_waitcnt lgkmcnt(0)
	v_mfma_f32_32x32x16_bf16 v[48:63], v[64:67], v[68:71], v[48:63]
	v_mfma_f32_32x32x16_bf16 v[16:31], v[64:67], v[72:75], v[16:31]
	ds_read_b128 v[64:67], v81 offset:16384
	v_mfma_f32_32x32x16_bf16 v[32:47], v[84:87], v[68:71], v[32:47]
	v_mfma_f32_32x32x16_bf16 v[0:15], v[84:87], v[72:75], v[0:15]
	v_add_u32_e32 v72, s2, v79
	ds_read_b128 v[68:71], v72
	ds_read_b128 v[72:75], v72 offset:4096
	ds_read_b128 v[82:85], v81 offset:20480
	v_add_u32_e32 v79, s2, v80
	s_waitcnt lgkmcnt(0)
	v_mfma_f32_32x32x16_bf16 v[48:63], v[64:67], v[68:71], v[48:63]
	v_mfma_f32_32x32x16_bf16 v[16:31], v[64:67], v[72:75], v[16:31]
	ds_read_b128 v[64:67], v79 offset:16384
	v_mfma_f32_32x32x16_bf16 v[32:47], v[82:85], v[68:71], v[32:47]
	v_mfma_f32_32x32x16_bf16 v[0:15], v[82:85], v[72:75], v[0:15]
	v_add_u32_e32 v72, s2, v77
	ds_read_b128 v[68:71], v72
	ds_read_b128 v[72:75], v72 offset:4096
	ds_read_b128 v[80:83], v79 offset:20480
	v_add_u32_e32 v77, s2, v78
	s_waitcnt lgkmcnt(0)
	v_mfma_f32_32x32x16_bf16 v[48:63], v[64:67], v[68:71], v[48:63]
	v_mfma_f32_32x32x16_bf16 v[16:31], v[64:67], v[72:75], v[16:31]
	ds_read_b128 v[64:67], v77 offset:16384
	v_mfma_f32_32x32x16_bf16 v[32:47], v[80:83], v[68:71], v[32:47]
	v_mfma_f32_32x32x16_bf16 v[0:15], v[80:83], v[72:75], v[0:15]
	v_add_u32_e32 v72, s2, v76
	ds_read_b128 v[68:71], v72
	ds_read_b128 v[72:75], v72 offset:4096
	ds_read_b128 v[76:79], v77 offset:20480
	s_waitcnt vmcnt(0) lgkmcnt(0)
	s_barrier
	s_waitcnt lgkmcnt(0)
	v_mfma_f32_32x32x16_bf16 v[48:63], v[64:67], v[68:71], v[48:63]
	v_mfma_f32_32x32x16_bf16 v[16:31], v[64:67], v[72:75], v[16:31]
	v_mfma_f32_32x32x16_bf16 v[32:47], v[76:79], v[68:71], v[32:47]
	v_mfma_f32_32x32x16_bf16 v[0:15], v[76:79], v[72:75], v[0:15]

; DEV int stage_next(int s) { return (s == 2 * GS_STAGE) ? 0 : s + GS_STAGE; }
; template <int WAIT0>
; DEV void gk_main(f32x16 (&acc)[2][2], const GTile& t, int s0) {
;     ...
;   vm_wait_bar<WAIT0>();
;   int stc = s0, std_ = stage_next(stage_next(s0));
; #pragma nounroll
;   for (int kt = 0; kt < nk - 2; ++kt) {
;     GK_DMA(std_, kt + 2);
;     GK_COMPUTE(stc);
;     vm_wait_bar<6>();
;     stc = stage_next(stc); std_ = stage_next(std_);
;   }
.LBB0_719:
	s_add_i32 s14, s3, s13
	s_mov_b32 s98, s14
	s_mov_b64 s[100:101], s[6:7]
	v_add_u32_e32 v101, s99, v82
	v_add_u32_e32 v100, s99, v79
	s_add_i32 s14, s2, 0xc000
	s_cmp_lg_u32 s2, 0x18000
	s_cselect_b32 s2, s14, 0
	s_add_i32 s14, s13, 0xc000
	s_cmp_lg_u32 s13, 0x18000
	s_cselect_b32 s13, s14, 0
	s_add_u32 s6, s6, 0x80
	s_addc_u32 s7, s7, 0
	ds_read_b128 v[236:239], v101 offset:16384
	ds_read_b128 v[240:243], v100
	ds_read_b128 v[244:247], v100 offset:4096
	ds_read_b128 v[248:251], v101 offset:20480
	s_waitcnt lgkmcnt(4)
	v_mfma_f32_32x32x16_bf16 v[48:63], v[84:87], v[88:91], v[48:63]
	v_mfma_f32_32x32x16_bf16 v[16:31], v[84:87], v[92:95], v[16:31]
	s_mov_b32 m0, s98
	v_lshl_add_u64 v[254:255], v[74:75], 0, s[100:101]
	global_load_lds_dwordx4 v[254:255], off
	v_mfma_f32_32x32x16_bf16 v[32:47], v[96:99], v[88:91], v[32:47]
	v_mfma_f32_32x32x16_bf16 v[0:15], v[96:99], v[92:95], v[0:15]
	s_add_i32 m0, s98, 0x2000
	v_lshl_add_u64 v[254:255], v[72:73], 0, s[100:101]
	global_load_lds_dwordx4 v[254:255], off
	v_add_u32_e32 v101, s99, v80
	v_add_u32_e32 v100, s99, v77
	ds_read_b128 v[84:87], v101 offset:16384
	ds_read_b128 v[88:91], v100
	ds_read_b128 v[92:95], v100 offset:4096
	ds_read_b128 v[96:99], v101 offset:20480
	s_waitcnt lgkmcnt(4)
	v_mfma_f32_32x32x16_bf16 v[48:63], v[236:239], v[240:243], v[48:63]
	v_mfma_f32_32x32x16_bf16 v[16:31], v[236:239], v[244:247], v[16:31]
	s_add_i32 m0, s98, 0x4000
	v_lshl_add_u64 v[254:255], v[70:71], 0, s[100:101]
	global_load_lds_dwordx4 v[254:255], off
	v_mfma_f32_32x32x16_bf16 v[32:47], v[248:251], v[240:243], v[32:47]
	v_mfma_f32_32x32x16_bf16 v[0:15], v[248:251], v[244:247], v[0:15]
	s_add_i32 m0, s98, 0x6000
	v_lshl_add_u64 v[254:255], v[68:69], 0, s[100:101]
	global_load_lds_dwordx4 v[254:255], off
	v_add_u32_e32 v101, s99, v78
	v_add_u32_e32 v100, s99, v76
	ds_read_b128 v[236:239], v101 offset:16384
	ds_read_b128 v[240:243], v100
	ds_read_b128 v[244:247], v100 offset:4096
	ds_read_b128 v[248:251], v101 offset:20480
	s_waitcnt lgkmcnt(4)
	v_mfma_f32_32x32x16_bf16 v[48:63], v[84:87], v[88:91], v[48:63]
	v_mfma_f32_32x32x16_bf16 v[16:31], v[84:87], v[92:95], v[16:31]
	s_add_i32 m0, s98, 0x8000
	v_lshl_add_u64 v[254:255], v[66:67], 0, s[100:101]
	global_load_lds_dwordx4 v[254:255], off
	v_mfma_f32_32x32x16_bf16 v[32:47], v[96:99], v[88:91], v[32:47]
	v_mfma_f32_32x32x16_bf16 v[0:15], v[96:99], v[92:95], v[0:15]
	s_add_i32 m0, s98, 0xa000
	v_lshl_add_u64 v[254:255], v[64:65], 0, s[100:101]
	global_load_lds_dwordx4 v[254:255], off
	s_waitcnt vmcnt(6) lgkmcnt(0)
	s_barrier
	s_add_i32 s99, s2, 0
	v_add_u32_e32 v253, s99, v81
	v_add_u32_e32 v252, s99, v83
	ds_read_b128 v[84:87], v252 offset:16384
	ds_read_b128 v[88:91], v253
	ds_read_b128 v[92:95], v253 offset:4096
	ds_read_b128 v[96:99], v252 offset:20480
	s_waitcnt lgkmcnt(4)
	v_mfma_f32_32x32x16_bf16 v[48:63], v[236:239], v[240:243], v[48:63]
	v_mfma_f32_32x32x16_bf16 v[16:31], v[236:239], v[244:247], v[16:31]
	v_mfma_f32_32x32x16_bf16 v[32:47], v[248:251], v[240:243], v[32:47]
	v_mfma_f32_32x32x16_bf16 v[0:15], v[248:251], v[244:247], v[0:15]
	s_cmpk_lg_i32 s6, 0x700
	s_cbranch_scc1 .LBB0_719
; DEV int stage_next(int s) { return (s == 2 * GS_STAGE) ? 0 : s + GS_STAGE; }
; template <int WAIT0>
; DEV void gk_main(f32x16 (&acc)[2][2], const GTile& t, int s0) {
;     ...
;   vm_wait_bar<WAIT0>();
;   int stc = s0, std_ = stage_next(stage_next(s0));
; #pragma nounroll
;   for (int kt = 0; kt < nk - 2; ++kt) {
;     GK_DMA(std_, kt + 2);
;     GK_COMPUTE(stc);
;     vm_wait_bar<6>();
;     stc = stage_next(stc); std_ = stage_next(std_);
;   }
;   GK_COMPUTE(stc);
;   vm_wait_bar<0>();
;   stc = stage_next(stc);
;   GK_COMPUTE(stc);
;   vm_wait_bar<0>();
	s_waitcnt lgkmcnt(0)
	s_add_i32 s3, s2, 0
	v_add_u32_e32 v84, s3, v83
	ds_read_b128 v[64:67], v84 offset:16384
	v_add_u32_e32 v72, s3, v81
	ds_read_b128 v[68:71], v72
	ds_read_b128 v[72:75], v72 offset:4096
	ds_read_b128 v[84:87], v84 offset:20480
	s_waitcnt lgkmcnt(0)
	v_mfma_f32_32x32x16_bf16 v[32:47], v[84:87], v[68:71], v[32:47]
	v_mfma_f32_32x32x16_bf16 v[0:15], v[84:87], v[72:75], v[0:15]
	v_add_u32_e32 v84, s3, v82
	v_mfma_f32_32x32x16_bf16 v[48:63], v[64:67], v[68:71], v[48:63]
	v_mfma_f32_32x32x16_bf16 v[16:31], v[64:67], v[72:75], v[16:31]
	ds_read_b128 v[64:67], v84 offset:16384
	v_add_u32_e32 v72, s3, v79
	ds_read_b128 v[68:71], v72
	ds_read_b128 v[72:75], v72 offset:4096
	ds_read_b128 v[84:87], v84 offset:20480
	s_waitcnt lgkmcnt(0)
	v_mfma_f32_32x32x16_bf16 v[32:47], v[84:87], v[68:71], v[32:47]
	v_mfma_f32_32x32x16_bf16 v[0:15], v[84:87], v[72:75], v[0:15]
	v_add_u32_e32 v84, s3, v80
	v_mfma_f32_32x32x16_bf16 v[48:63], v[64:67], v[68:71], v[48:63]
	v_mfma_f32_32x32x16_bf16 v[16:31], v[64:67], v[72:75], v[16:31]
	ds_read_b128 v[64:67], v84 offset:16384
	v_add_u32_e32 v72, s3, v77
	ds_read_b128 v[68:71], v72
	ds_read_b128 v[72:75], v72 offset:4096
	ds_read_b128 v[84:87], v84 offset:20480
	s_waitcnt lgkmcnt(0)
	v_mfma_f32_32x32x16_bf16 v[32:47], v[84:87], v[68:71], v[32:47]
	v_mfma_f32_32x32x16_bf16 v[0:15], v[84:87], v[72:75], v[0:15]
	v_add_u32_e32 v84, s3, v78
	v_mfma_f32_32x32x16_bf16 v[48:63], v[64:67], v[68:71], v[48:63]
	v_mfma_f32_32x32x16_bf16 v[16:31], v[64:67], v[72:75], v[16:31]
	ds_read_b128 v[64:67], v84 offset:16384
	v_add_u32_e32 v72, s3, v76
	s_add_i32 s3, s2, 0xc000
	ds_read_b128 v[68:71], v72
	ds_read_b128 v[72:75], v72 offset:4096
	ds_read_b128 v[84:87], v84 offset:20480
	s_cmp_lg_u32 s2, 0x18000
	s_cselect_b32 s2, s3, 0
	s_add_i32 s2, s2, 0
	s_waitcnt vmcnt(0) lgkmcnt(0)
	s_barrier
	v_add_u32_e32 v83, s2, v83
	s_waitcnt lgkmcnt(0)
	v_mfma_f32_32x32x16_bf16 v[48:63], v[64:67], v[68:71], v[48:63]
	v_mfma_f32_32x32x16_bf16 v[16:31], v[64:67], v[72:75], v[16:31]
	ds_read_b128 v[64:67], v83 offset:16384
	v_mfma_f32_32x32x16_bf16 v[32:47], v[84:87], v[68:71], v[32:47]
	v_mfma_f32_32x32x16_bf16 v[0:15], v[84:87], v[72:75], v[0:15]
	v_add_u32_e32 v72, s2, v81
	ds_read_b128 v[68:71], v72
	ds_read_b128 v[72:75], v72 offset:4096
	ds_read_b128 v[84:87], v83 offset:20480
	v_add_u32_e32 v81, s2, v82
	s_waitcnt lgkmcnt(0)
	v_mfma_f32_32x32x16_bf16 v[48:63], v[64:67], v[68:71], v[48:63]
	v_mfma_f32_32x32x16_bf16 v[16:31], v[64:67], v[72:75], v[16:31]
	ds_read_b128 v[64:67], v81 offset:16384
	v_mfma_f32_32x32x16_bf16 v[32:47], v[84:87], v[68:71], v[32:47]
	v_mfma_f32_32x32x16_bf16 v[0:15], v[84:87], v[72:75], v[0:15]
	v_add_u32_e32 v72, s2, v79
	ds_read_b128 v[68:71], v72
	ds_read_b128 v[72:75], v72 offset:4096
	ds_read_b128 v[82:85], v81 offset:20480
	v_add_u32_e32 v79, s2, v80
	s_waitcnt lgkmcnt(0)
	v_mfma_f32_32x32x16_bf16 v[48:63], v[64:67], v[68:71], v[48:63]
	v_mfma_f32_32x32x16_bf16 v[16:31], v[64:67], v[72:75], v[16:31]
	ds_read_b128 v[64:67], v79 offset:16384
	v_mfma_f32_32x32x16_bf16 v[32:47], v[82:85], v[68:71], v[32:47]
	v_mfma_f32_32x32x16_bf16 v[0:15], v[82:85], v[72:75], v[0:15]
	v_add_u32_e32 v72, s2, v77
	ds_read_b128 v[68:71], v72
	ds_read_b128 v[72:75], v72 offset:4096
	ds_read_b128 v[80:83], v79 offset:20480
	v_add_u32_e32 v77, s2, v78
	s_waitcnt lgkmcnt(0)
	v_mfma_f32_32x32x16_bf16 v[48:63], v[64:67], v[68:71], v[48:63]
	v_mfma_f32_32x32x16_bf16 v[16:31], v[64:67], v[72:75], v[16:31]
	ds_read_b128 v[64:67], v77 offset:16384
	v_mfma_f32_32x32x16_bf16 v[32:47], v[80:83], v[68:71], v[32:47]
	v_mfma_f32_32x32x16_bf16 v[0:15], v[80:83], v[72:75], v[0:15]
	v_add_u32_e32 v72, s2, v76
	ds_read_b128 v[68:71], v72
	ds_read_b128 v[72:75], v72 offset:4096
	ds_read_b128 v[76:79], v77 offset:20480
	s_waitcnt vmcnt(0) lgkmcnt(0)
	s_barrier
	s_waitcnt lgkmcnt(0)
	v_mfma_f32_32x32x16_bf16 v[48:63], v[64:67], v[68:71], v[48:63]
	v_mfma_f32_32x32x16_bf16 v[16:31], v[64:67], v[72:75], v[16:31]
	v_mfma_f32_32x32x16_bf16 v[32:47], v[76:79], v[68:71], v[32:47]
	v_mfma_f32_32x32x16_bf16 v[0:15], v[76:79], v[72:75], v[0:15]

; DEV int stage_next(int s) { return (s == 2 * GS_STAGE) ? 0 : s + GS_STAGE; }
; template <int WAIT0>
; DEV void gk_main(f32x16 (&acc)[2][2], const GTile& t, int s0) {
;     ...
;   vm_wait_bar<WAIT0>();
;   int stc = s0, std_ = stage_next(stage_next(s0));
; #pragma nounroll
;   for (int kt = 0; kt < nk - 2; ++kt) {
;     GK_DMA(std_, kt + 2);
;     GK_COMPUTE(stc);
;     vm_wait_bar<6>();
;     stc = stage_next(stc); std_ = stage_next(std_);
;   }
.LBB0_725:
	s_add_i32 s14, s3, s13
	s_mov_b32 s98, s14
	s_mov_b64 s[100:101], s[6:7]
	v_add_u32_e32 v101, s99, v82
	v_add_u32_e32 v100, s99, v79
	s_add_i32 s14, s2, 0xc000
	s_cmp_lg_u32 s2, 0x18000
	s_cselect_b32 s2, s14, 0
	s_add_i32 s14, s13, 0xc000
	s_cmp_lg_u32 s13, 0x18000
	s_cselect_b32 s13, s14, 0
	s_add_u32 s6, s6, 0x80
	s_addc_u32 s7, s7, 0
	ds_read_b128 v[236:239], v101 offset:16384
	ds_read_b128 v[240:243], v100
	ds_read_b128 v[244:247], v100 offset:4096
	ds_read_b128 v[248:251], v101 offset:20480
	s_waitcnt lgkmcnt(4)
	v_mfma_f32_32x32x16_bf16 v[48:63], v[84:87], v[88:91], v[48:63]
	v_mfma_f32_32x32x16_bf16 v[16:31], v[84:87], v[92:95], v[16:31]
	s_mov_b32 m0, s98
	v_lshl_add_u64 v[254:255], v[74:75], 0, s[100:101]
	global_load_lds_dwordx4 v[254:255], off
	v_mfma_f32_32x32x16_bf16 v[32:47], v[96:99], v[88:91], v[32:47]
	v_mfma_f32_32x32x16_bf16 v[0:15], v[96:99], v[92:95], v[0:15]
	s_add_i32 m0, s98, 0x2000
	v_lshl_add_u64 v[254:255], v[72:73], 0, s[100:101]
	global_load_lds_dwordx4 v[254:255], off
	v_add_u32_e32 v101, s99, v80
	v_add_u32_e32 v100, s99, v77
	ds_read_b128 v[84:87], v101 offset:16384
	ds_read_b128 v[88:91], v100
	ds_read_b128 v[92:95], v100 offset:4096
	ds_read_b128 v[96:99], v101 offset:20480
	s_waitcnt lgkmcnt(4)
	v_mfma_f32_32x32x16_bf16 v[48:63], v[236:239], v[240:243], v[48:63]
	v_mfma_f32_32x32x16_bf16 v[16:31], v[236:239], v[244:247], v[16:31]
	s_add_i32 m0, s98, 0x4000
	v_lshl_add_u64 v[254:255], v[70:71], 0, s[100:101]
	global_load_lds_dwordx4 v[254:255], off
	v_mfma_f32_32x32x16_bf16 v[32:47], v[248:251], v[240:243], v[32:47]
	v_mfma_f32_32x32x16_bf16 v[0:15], v[248:251], v[244:247], v[0:15]
	s_add_i32 m0, s98, 0x6000
	v_lshl_add_u64 v[254:255], v[68:69], 0, s[100:101]
	global_load_lds_dwordx4 v[254:255], off
	v_add_u32_e32 v101, s99, v78
	v_add_u32_e32 v100, s99, v76
	ds_read_b128 v[236:239], v101 offset:16384
	ds_read_b128 v[240:243], v100
	ds_read_b128 v[244:247], v100 offset:4096
	ds_read_b128 v[248:251], v101 offset:20480
	s_waitcnt lgkmcnt(4)
	v_mfma_f32_32x32x16_bf16 v[48:63], v[84:87], v[88:91], v[48:63]
	v_mfma_f32_32x32x16_bf16 v[16:31], v[84:87], v[92:95], v[16:31]
	s_add_i32 m0, s98, 0x8000
	v_lshl_add_u64 v[254:255], v[66:67], 0, s[100:101]
	global_load_lds_dwordx4 v[254:255], off
	v_mfma_f32_32x32x16_bf16 v[32:47], v[96:99], v[88:91], v[32:47]
	v_mfma_f32_32x32x16_bf16 v[0:15], v[96:99], v[92:95], v[0:15]
	s_add_i32 m0, s98, 0xa000
	v_lshl_add_u64 v[254:255], v[64:65], 0, s[100:101]
	global_load_lds_dwordx4 v[254:255], off
	s_waitcnt vmcnt(6) lgkmcnt(0)
	s_barrier
	s_add_i32 s99, s2, 0
	v_add_u32_e32 v253, s99, v81
	v_add_u32_e32 v252, s99, v83
	ds_read_b128 v[84:87], v252 offset:16384
	ds_read_b128 v[88:91], v253
	ds_read_b128 v[92:95], v253 offset:4096
	ds_read_b128 v[96:99], v252 offset:20480
	s_waitcnt lgkmcnt(4)
	v_mfma_f32_32x32x16_bf16 v[48:63], v[236:239], v[240:243], v[48:63]
	v_mfma_f32_32x32x16_bf16 v[16:31], v[236:239], v[244:247], v[16:31]
	v_mfma_f32_32x32x16_bf16 v[32:47], v[248:251], v[240:243], v[32:47]
	v_mfma_f32_32x32x16_bf16 v[0:15], v[248:251], v[244:247], v[0:15]
	s_cmpk_lg_i32 s6, 0x700
	s_cbranch_scc1 .LBB0_725
; DEV int stage_next(int s) { return (s == 2 * GS_STAGE) ? 0 : s + GS_STAGE; }
; template <int WAIT0>
; DEV void gk_main(f32x16 (&acc)[2][2], const GTile& t, int s0) {
;     ...
;   vm_wait_bar<WAIT0>();
;   int stc = s0, std_ = stage_next(stage_next(s0));
; #pragma nounroll
;   for (int kt = 0; kt < nk - 2; ++kt) {
;     GK_DMA(std_, kt + 2);
;     GK_COMPUTE(stc);
;     vm_wait_bar<6>();
;     stc = stage_next(stc); std_ = stage_next(std_);
;   }
;   GK_COMPUTE(stc);
;   vm_wait_bar<0>();
;   stc = stage_next(stc);
;   GK_COMPUTE(stc);
;   vm_wait_bar<0>();
	s_waitcnt lgkmcnt(0)
	s_add_i32 s3, s2, 0
	v_add_u32_e32 v84, s3, v83
	ds_read_b128 v[64:67], v84 offset:16384
	v_add_u32_e32 v72, s3, v81
	ds_read_b128 v[68:71], v72
	ds_read_b128 v[72:75], v72 offset:4096
	ds_read_b128 v[84:87], v84 offset:20480
	s_waitcnt lgkmcnt(0)
	v_mfma_f32_32x32x16_bf16 v[32:47], v[84:87], v[68:71], v[32:47]
	v_mfma_f32_32x32x16_bf16 v[0:15], v[84:87], v[72:75], v[0:15]
	v_add_u32_e32 v84, s3, v82
	v_mfma_f32_32x32x16_bf16 v[48:63], v[64:67], v[68:71], v[48:63]
	v_mfma_f32_32x32x16_bf16 v[16:31], v[64:67], v[72:75], v[16:31]
	ds_read_b128 v[64:67], v84 offset:16384
	v_add_u32_e32 v72, s3, v79
	ds_read_b128 v[68:71], v72
	ds_read_b128 v[72:75], v72 offset:4096
	ds_read_b128 v[84:87], v84 offset:20480
	s_waitcnt lgkmcnt(0)
	v_mfma_f32_32x32x16_bf16 v[32:47], v[84:87], v[68:71], v[32:47]
	v_mfma_f32_32x32x16_bf16 v[0:15], v[84:87], v[72:75], v[0:15]
	v_add_u32_e32 v84, s3, v80
	v_mfma_f32_32x32x16_bf16 v[48:63], v[64:67], v[68:71], v[48:63]
	v_mfma_f32_32x32x16_bf16 v[16:31], v[64:67], v[72:75], v[16:31]
	ds_read_b128 v[64:67], v84 offset:16384
	v_add_u32_e32 v72, s3, v77
	ds_read_b128 v[68:71], v72
	ds_read_b128 v[72:75], v72 offset:4096
	ds_read_b128 v[84:87], v84 offset:20480
	s_waitcnt lgkmcnt(0)
	v_mfma_f32_32x32x16_bf16 v[32:47], v[84:87], v[68:71], v[32:47]
	v_mfma_f32_32x32x16_bf16 v[0:15], v[84:87], v[72:75], v[0:15]
	v_add_u32_e32 v84, s3, v78
	v_mfma_f32_32x32x16_bf16 v[48:63], v[64:67], v[68:71], v[48:63]
	v_mfma_f32_32x32x16_bf16 v[16:31], v[64:67], v[72:75], v[16:31]
	ds_read_b128 v[64:67], v84 offset:16384
	v_add_u32_e32 v72, s3, v76
	s_add_i32 s3, s2, 0xc000
	ds_read_b128 v[68:71], v72
	ds_read_b128 v[72:75], v72 offset:4096
	ds_read_b128 v[84:87], v84 offset:20480
	s_cmp_lg_u32 s2, 0x18000
	s_cselect_b32 s2, s3, 0
	s_add_i32 s2, s2, 0
	s_waitcnt vmcnt(0) lgkmcnt(0)
	s_barrier
	v_add_u32_e32 v83, s2, v83
	s_waitcnt lgkmcnt(0)
	v_mfma_f32_32x32x16_bf16 v[48:63], v[64:67], v[68:71], v[48:63]
	v_mfma_f32_32x32x16_bf16 v[16:31], v[64:67], v[72:75], v[16:31]
	ds_read_b128 v[64:67], v83 offset:16384
	v_mfma_f32_32x32x16_bf16 v[32:47], v[84:87], v[68:71], v[32:47]
	v_mfma_f32_32x32x16_bf16 v[0:15], v[84:87], v[72:75], v[0:15]
	v_add_u32_e32 v72, s2, v81
	ds_read_b128 v[68:71], v72
	ds_read_b128 v[72:75], v72 offset:4096
	ds_read_b128 v[84:87], v83 offset:20480
	v_add_u32_e32 v81, s2, v82
	s_waitcnt lgkmcnt(0)
	v_mfma_f32_32x32x16_bf16 v[48:63], v[64:67], v[68:71], v[48:63]
	v_mfma_f32_32x32x16_bf16 v[16:31], v[64:67], v[72:75], v[16:31]
	ds_read_b128 v[64:67], v81 offset:16384
	v_mfma_f32_32x32x16_bf16 v[32:47], v[84:87], v[68:71], v[32:47]
	v_mfma_f32_32x32x16_bf16 v[0:15], v[84:87], v[72:75], v[0:15]
	v_add_u32_e32 v72, s2, v79
	ds_read_b128 v[68:71], v72
	ds_read_b128 v[72:75], v72 offset:4096
	ds_read_b128 v[82:85], v81 offset:20480
	v_add_u32_e32 v79, s2, v80
	s_waitcnt lgkmcnt(0)
	v_mfma_f32_32x32x16_bf16 v[48:63], v[64:67], v[68:71], v[48:63]
	v_mfma_f32_32x32x16_bf16 v[16:31], v[64:67], v[72:75], v[16:31]
	ds_read_b128 v[64:67], v79 offset:16384
	v_mfma_f32_32x32x16_bf16 v[32:47], v[82:85], v[68:71], v[32:47]
	v_mfma_f32_32x32x16_bf16 v[0:15], v[82:85], v[72:75], v[0:15]
	v_add_u32_e32 v72, s2, v77
	ds_read_b128 v[68:71], v72
	ds_read_b128 v[72:75], v72 offset:4096
	ds_read_b128 v[80:83], v79 offset:20480
	v_add_u32_e32 v77, s2, v78
	s_waitcnt lgkmcnt(0)
	v_mfma_f32_32x32x16_bf16 v[48:63], v[64:67], v[68:71], v[48:63]
	v_mfma_f32_32x32x16_bf16 v[16:31], v[64:67], v[72:75], v[16:31]
	ds_read_b128 v[64:67], v77 offset:16384
	v_mfma_f32_32x32x16_bf16 v[32:47], v[80:83], v[68:71], v[32:47]
	v_mfma_f32_32x32x16_bf16 v[0:15], v[80:83], v[72:75], v[0:15]
	v_add_u32_e32 v72, s2, v76
	ds_read_b128 v[68:71], v72
	ds_read_b128 v[72:75], v72 offset:4096
	ds_read_b128 v[76:79], v77 offset:20480
	s_waitcnt vmcnt(0) lgkmcnt(0)
	s_barrier
	s_waitcnt lgkmcnt(0)
	v_mfma_f32_32x32x16_bf16 v[48:63], v[64:67], v[68:71], v[48:63]
	v_mfma_f32_32x32x16_bf16 v[16:31], v[64:67], v[72:75], v[16:31]
	v_mfma_f32_32x32x16_bf16 v[32:47], v[76:79], v[68:71], v[32:47]
	v_mfma_f32_32x32x16_bf16 v[0:15], v[76:79], v[72:75], v[0:15]
	s_add_i32 s2, s12, 1
	s_cmp_eq_u32 s12, 3
	s_cbranch_scc1 .LBB0_711

; DEV int stage_next(int s) { return (s == 2 * GS_STAGE) ? 0 : s + GS_STAGE; }
; template <int WAIT0>
; DEV void gk_main(f32x16 (&acc)[2][2], const GTile& t, int s0) {
;     ...
;   vm_wait_bar<WAIT0>();
;   int stc = s0, std_ = stage_next(stage_next(s0));
; #pragma nounroll
;   for (int kt = 0; kt < nk - 2; ++kt) {
;     GK_DMA(std_, kt + 2);
;     GK_COMPUTE(stc);
;     vm_wait_bar<6>();
;     stc = stage_next(stc); std_ = stage_next(std_);
;   }
.LBB0_737:
	s_add_i32 s20, s3, s19
	s_mov_b32 s98, s20
	s_mov_b64 s[100:101], s[10:11]
	v_add_u32_e32 v104, s99, v85
	v_add_u32_e32 v87, s99, v82
	s_add_i32 s20, s2, 0xc000
	s_cmp_lg_u32 s2, 0x18000
	s_cselect_b32 s2, s20, 0
	s_add_i32 s20, s19, 0xc000
	s_cmp_lg_u32 s19, 0x18000
	s_cselect_b32 s19, s20, 0
	s_add_u32 s10, s10, 0x80
	s_addc_u32 s11, s11, 0
	ds_read_b128 v[236:239], v104 offset:16384
	ds_read_b128 v[240:243], v87
	ds_read_b128 v[244:247], v87 offset:4096
	ds_read_b128 v[248:251], v104 offset:20480
	s_waitcnt lgkmcnt(4)
	v_mfma_f32_32x32x16_bf16 v[48:63], v[88:91], v[92:95], v[48:63]
	v_mfma_f32_32x32x16_bf16 v[32:47], v[88:91], v[96:99], v[32:47]
	s_mov_b32 m0, s98
	v_lshl_add_u64 v[254:255], v[76:77], 0, s[100:101]
	global_load_lds_dwordx4 v[254:255], off
	v_mfma_f32_32x32x16_bf16 v[16:31], v[100:103], v[92:95], v[16:31]
	v_mfma_f32_32x32x16_bf16 v[0:15], v[100:103], v[96:99], v[0:15]
	s_add_i32 m0, s98, 0x2000
	v_lshl_add_u64 v[254:255], v[74:75], 0, s[100:101]
	global_load_lds_dwordx4 v[254:255], off
	v_add_u32_e32 v104, s99, v83
	v_add_u32_e32 v87, s99, v80
	ds_read_b128 v[88:91], v104 offset:16384
	ds_read_b128 v[92:95], v87
	ds_read_b128 v[96:99], v87 offset:4096
	ds_read_b128 v[100:103], v104 offset:20480
	s_waitcnt lgkmcnt(4)
	v_mfma_f32_32x32x16_bf16 v[48:63], v[236:239], v[240:243], v[48:63]
	v_mfma_f32_32x32x16_bf16 v[32:47], v[236:239], v[244:247], v[32:47]
	s_add_i32 m0, s98, 0x4000
	v_lshl_add_u64 v[254:255], v[72:73], 0, s[100:101]
	global_load_lds_dwordx4 v[254:255], off
	v_mfma_f32_32x32x16_bf16 v[16:31], v[248:251], v[240:243], v[16:31]
	v_mfma_f32_32x32x16_bf16 v[0:15], v[248:251], v[244:247], v[0:15]
	s_add_i32 m0, s98, 0x6000
	v_lshl_add_u64 v[254:255], v[70:71], 0, s[100:101]
	global_load_lds_dwordx4 v[254:255], off
	v_add_u32_e32 v104, s99, v81
	v_add_u32_e32 v87, s99, v79
	ds_read_b128 v[236:239], v104 offset:16384
	ds_read_b128 v[240:243], v87
	ds_read_b128 v[244:247], v87 offset:4096
	ds_read_b128 v[248:251], v104 offset:20480
	s_waitcnt lgkmcnt(4)
	v_mfma_f32_32x32x16_bf16 v[48:63], v[88:91], v[92:95], v[48:63]
	v_mfma_f32_32x32x16_bf16 v[32:47], v[88:91], v[96:99], v[32:47]
	s_add_i32 m0, s98, 0x8000
	v_lshl_add_u64 v[254:255], v[68:69], 0, s[100:101]
	global_load_lds_dwordx4 v[254:255], off
	v_mfma_f32_32x32x16_bf16 v[16:31], v[100:103], v[92:95], v[16:31]
	v_mfma_f32_32x32x16_bf16 v[0:15], v[100:103], v[96:99], v[0:15]
	s_add_i32 m0, s98, 0xa000
	v_lshl_add_u64 v[254:255], v[66:67], 0, s[100:101]
	global_load_lds_dwordx4 v[254:255], off
	s_waitcnt vmcnt(6) lgkmcnt(0)
	s_barrier
	s_add_i32 s99, s2, 0
	v_add_u32_e32 v252, s99, v86
	v_add_u32_e32 v87, s99, v84
	ds_read_b128 v[88:91], v252 offset:16384
	ds_read_b128 v[92:95], v87
	ds_read_b128 v[96:99], v87 offset:4096
	ds_read_b128 v[100:103], v252 offset:20480
	s_waitcnt lgkmcnt(4)
	v_mfma_f32_32x32x16_bf16 v[48:63], v[236:239], v[240:243], v[48:63]
	v_mfma_f32_32x32x16_bf16 v[32:47], v[236:239], v[244:247], v[32:47]
	v_mfma_f32_32x32x16_bf16 v[16:31], v[248:251], v[240:243], v[16:31]
	v_mfma_f32_32x32x16_bf16 v[0:15], v[248:251], v[244:247], v[0:15]
	s_cmpk_lg_i32 s10, 0x700
	s_cbranch_scc1 .LBB0_737
; DEV int stage_next(int s) { return (s == 2 * GS_STAGE) ? 0 : s + GS_STAGE; }
; template <int WAIT0>
; DEV void gk_main(f32x16 (&acc)[2][2], const GTile& t, int s0) {
;     ...
;   vm_wait_bar<WAIT0>();
;   int stc = s0, std_ = stage_next(stage_next(s0));
; #pragma nounroll
;   for (int kt = 0; kt < nk - 2; ++kt) {
;     GK_DMA(std_, kt + 2);
;     GK_COMPUTE(stc);
;     vm_wait_bar<6>();
;     stc = stage_next(stc); std_ = stage_next(std_);
;   }
;   GK_COMPUTE(stc);
;   vm_wait_bar<0>();
;   stc = stage_next(stc);
;   GK_COMPUTE(stc);
;   vm_wait_bar<0>();
	s_waitcnt lgkmcnt(0)
	s_add_i32 s3, s2, 0
	v_add_u32_e32 v87, s3, v86
	ds_read_b128 v[66:69], v87 offset:16384
	v_add_u32_e32 v74, s3, v84
	ds_read_b128 v[70:73], v74
	ds_read_b128 v[74:77], v74 offset:4096
	ds_read_b128 v[88:91], v87 offset:20480
	v_add_u32_e32 v87, s3, v85
	s_mov_b64 s[10:11], 0
	s_waitcnt lgkmcnt(0)
	v_mfma_f32_32x32x16_bf16 v[0:15], v[88:91], v[74:77], v[0:15]
	v_mfma_f32_32x32x16_bf16 v[48:63], v[66:69], v[70:73], v[48:63]
	v_mfma_f32_32x32x16_bf16 v[32:47], v[66:69], v[74:77], v[32:47]
	ds_read_b128 v[66:69], v87 offset:16384
	v_add_u32_e32 v74, s3, v82
	v_mfma_f32_32x32x16_bf16 v[16:31], v[88:91], v[70:73], v[16:31]
	ds_read_b128 v[70:73], v74
	ds_read_b128 v[74:77], v74 offset:4096
	ds_read_b128 v[88:91], v87 offset:20480
	v_add_u32_e32 v87, s3, v83
	s_waitcnt lgkmcnt(0)
	v_mfma_f32_32x32x16_bf16 v[48:63], v[66:69], v[70:73], v[48:63]
	v_mfma_f32_32x32x16_bf16 v[32:47], v[66:69], v[74:77], v[32:47]
	ds_read_b128 v[66:69], v87 offset:16384
	v_mfma_f32_32x32x16_bf16 v[0:15], v[88:91], v[74:77], v[0:15]
	v_add_u32_e32 v74, s3, v80
	v_mfma_f32_32x32x16_bf16 v[16:31], v[88:91], v[70:73], v[16:31]
	ds_read_b128 v[70:73], v74
	ds_read_b128 v[74:77], v74 offset:4096
	ds_read_b128 v[88:91], v87 offset:20480
	v_add_u32_e32 v87, s3, v81
	s_waitcnt lgkmcnt(0)
	v_mfma_f32_32x32x16_bf16 v[48:63], v[66:69], v[70:73], v[48:63]
	v_mfma_f32_32x32x16_bf16 v[32:47], v[66:69], v[74:77], v[32:47]
	ds_read_b128 v[66:69], v87 offset:16384
	v_mfma_f32_32x32x16_bf16 v[0:15], v[88:91], v[74:77], v[0:15]
	v_add_u32_e32 v74, s3, v79
	s_add_i32 s3, s2, 0xc000
	s_cmp_lg_u32 s2, 0x18000
	s_cselect_b32 s2, s3, 0
	s_add_i32 s2, s2, 0
	v_add_u32_e32 v86, s2, v86
	v_mfma_f32_32x32x16_bf16 v[16:31], v[88:91], v[70:73], v[16:31]
	ds_read_b128 v[70:73], v74
	ds_read_b128 v[74:77], v74 offset:4096
	ds_read_b128 v[88:91], v87 offset:20480
	s_waitcnt vmcnt(0) lgkmcnt(0)
	s_barrier
	s_waitcnt lgkmcnt(0)
	v_mfma_f32_32x32x16_bf16 v[48:63], v[66:69], v[70:73], v[48:63]
	v_mfma_f32_32x32x16_bf16 v[32:47], v[66:69], v[74:77], v[32:47]
	ds_read_b128 v[66:69], v86 offset:16384
	v_mfma_f32_32x32x16_bf16 v[16:31], v[88:91], v[70:73], v[16:31]
	v_mfma_f32_32x32x16_bf16 v[0:15], v[88:91], v[74:77], v[0:15]
	v_add_u32_e32 v74, s2, v84
	ds_read_b128 v[70:73], v74
	ds_read_b128 v[74:77], v74 offset:4096
	ds_read_b128 v[86:89], v86 offset:20480
	v_add_u32_e32 v84, s2, v85
	s_waitcnt lgkmcnt(0)
	v_mfma_f32_32x32x16_bf16 v[48:63], v[66:69], v[70:73], v[48:63]
	v_mfma_f32_32x32x16_bf16 v[32:47], v[66:69], v[74:77], v[32:47]
	ds_read_b128 v[66:69], v84 offset:16384
	v_mfma_f32_32x32x16_bf16 v[16:31], v[86:89], v[70:73], v[16:31]
	v_mfma_f32_32x32x16_bf16 v[0:15], v[86:89], v[74:77], v[0:15]
	v_add_u32_e32 v74, s2, v82
	ds_read_b128 v[70:73], v74
	ds_read_b128 v[74:77], v74 offset:4096
	ds_read_b128 v[84:87], v84 offset:20480
	v_add_u32_e32 v82, s2, v83
	s_waitcnt lgkmcnt(0)
	v_mfma_f32_32x32x16_bf16 v[48:63], v[66:69], v[70:73], v[48:63]
	v_mfma_f32_32x32x16_bf16 v[32:47], v[66:69], v[74:77], v[32:47]
	ds_read_b128 v[66:69], v82 offset:16384
	v_mfma_f32_32x32x16_bf16 v[16:31], v[84:87], v[70:73], v[16:31]
	v_mfma_f32_32x32x16_bf16 v[0:15], v[84:87], v[74:77], v[0:15]
	v_add_u32_e32 v74, s2, v80
	ds_read_b128 v[70:73], v74
	ds_read_b128 v[74:77], v74 offset:4096
	ds_read_b128 v[82:85], v82 offset:20480
	v_add_u32_e32 v80, s2, v81
	s_waitcnt lgkmcnt(0)
	v_mfma_f32_32x32x16_bf16 v[48:63], v[66:69], v[70:73], v[48:63]
	v_mfma_f32_32x32x16_bf16 v[32:47], v[66:69], v[74:77], v[32:47]
	ds_read_b128 v[66:69], v80 offset:16384
	v_mfma_f32_32x32x16_bf16 v[16:31], v[82:85], v[70:73], v[16:31]
	v_mfma_f32_32x32x16_bf16 v[0:15], v[82:85], v[74:77], v[0:15]
	v_add_u32_e32 v74, s2, v79
	ds_read_b128 v[70:73], v74
	ds_read_b128 v[74:77], v74 offset:4096
	ds_read_b128 v[80:83], v80 offset:20480
	s_waitcnt vmcnt(0) lgkmcnt(0)
	s_barrier
	s_waitcnt lgkmcnt(0)
	v_mfma_f32_32x32x16_bf16 v[48:63], v[66:69], v[70:73], v[48:63]
	v_mfma_f32_32x32x16_bf16 v[32:47], v[66:69], v[74:77], v[32:47]
	v_mfma_f32_32x32x16_bf16 v[16:31], v[80:83], v[70:73], v[16:31]
	v_mfma_f32_32x32x16_bf16 v[0:15], v[80:83], v[74:77], v[0:15]

; DEV int stage_next(int s) { return (s == 2 * GS_STAGE) ? 0 : s + GS_STAGE; }
; template <int WAIT0>
; DEV void gk_main(f32x16 (&acc)[2][2], const GTile& t, int s0) {
;     ...
;   vm_wait_bar<WAIT0>();
;   int stc = s0, std_ = stage_next(stage_next(s0));
; #pragma nounroll
;   for (int kt = 0; kt < nk - 2; ++kt) {
;     GK_DMA(std_, kt + 2);
;     GK_COMPUTE(stc);
;     vm_wait_bar<6>();
;     stc = stage_next(stc); std_ = stage_next(std_);
;   }
.LBB0_741:
	s_add_i32 s20, s3, s19
	s_mov_b32 s98, s20
	s_mov_b64 s[100:101], s[10:11]
	v_add_u32_e32 v104, s99, v85
	v_add_u32_e32 v87, s99, v82
	s_add_i32 s20, s2, 0xc000
	s_cmp_lg_u32 s2, 0x18000
	s_cselect_b32 s2, s20, 0
	s_add_i32 s20, s19, 0xc000
	s_cmp_lg_u32 s19, 0x18000
	s_cselect_b32 s19, s20, 0
	s_add_u32 s10, s10, 0x80
	s_addc_u32 s11, s11, 0
	ds_read_b128 v[236:239], v104 offset:16384
	ds_read_b128 v[240:243], v87
	ds_read_b128 v[244:247], v87 offset:4096
	ds_read_b128 v[248:251], v104 offset:20480
	s_waitcnt lgkmcnt(4)
	v_mfma_f32_32x32x16_bf16 v[48:63], v[88:91], v[92:95], v[48:63]
	v_mfma_f32_32x32x16_bf16 v[32:47], v[88:91], v[96:99], v[32:47]
	s_mov_b32 m0, s98
	v_lshl_add_u64 v[254:255], v[76:77], 0, s[100:101]
	global_load_lds_dwordx4 v[254:255], off
	v_mfma_f32_32x32x16_bf16 v[16:31], v[100:103], v[92:95], v[16:31]
	v_mfma_f32_32x32x16_bf16 v[0:15], v[100:103], v[96:99], v[0:15]
	s_add_i32 m0, s98, 0x2000
	v_lshl_add_u64 v[254:255], v[74:75], 0, s[100:101]
	global_load_lds_dwordx4 v[254:255], off
	v_add_u32_e32 v104, s99, v83
	v_add_u32_e32 v87, s99, v80
	ds_read_b128 v[88:91], v104 offset:16384
	ds_read_b128 v[92:95], v87
	ds_read_b128 v[96:99], v87 offset:4096
	ds_read_b128 v[100:103], v104 offset:20480
	s_waitcnt lgkmcnt(4)
	v_mfma_f32_32x32x16_bf16 v[48:63], v[236:239], v[240:243], v[48:63]
	v_mfma_f32_32x32x16_bf16 v[32:47], v[236:239], v[244:247], v[32:47]
	s_add_i32 m0, s98, 0x4000
	v_lshl_add_u64 v[254:255], v[72:73], 0, s[100:101]
	global_load_lds_dwordx4 v[254:255], off
	v_mfma_f32_32x32x16_bf16 v[16:31], v[248:251], v[240:243], v[16:31]
	v_mfma_f32_32x32x16_bf16 v[0:15], v[248:251], v[244:247], v[0:15]
	s_add_i32 m0, s98, 0x6000
	v_lshl_add_u64 v[254:255], v[70:71], 0, s[100:101]
	global_load_lds_dwordx4 v[254:255], off
	v_add_u32_e32 v104, s99, v81
	v_add_u32_e32 v87, s99, v79
	ds_read_b128 v[236:239], v104 offset:16384
	ds_read_b128 v[240:243], v87
	ds_read_b128 v[244:247], v87 offset:4096
	ds_read_b128 v[248:251], v104 offset:20480
	s_waitcnt lgkmcnt(4)
	v_mfma_f32_32x32x16_bf16 v[48:63], v[88:91], v[92:95], v[48:63]
	v_mfma_f32_32x32x16_bf16 v[32:47], v[88:91], v[96:99], v[32:47]
	s_add_i32 m0, s98, 0x8000
	v_lshl_add_u64 v[254:255], v[68:69], 0, s[100:101]
	global_load_lds_dwordx4 v[254:255], off
	v_mfma_f32_32x32x16_bf16 v[16:31], v[100:103], v[92:95], v[16:31]
	v_mfma_f32_32x32x16_bf16 v[0:15], v[100:103], v[96:99], v[0:15]
	s_add_i32 m0, s98, 0xa000
	v_lshl_add_u64 v[254:255], v[66:67], 0, s[100:101]
	global_load_lds_dwordx4 v[254:255], off
	s_waitcnt vmcnt(6) lgkmcnt(0)
	s_barrier
	s_add_i32 s99, s2, 0
	v_add_u32_e32 v252, s99, v86
	v_add_u32_e32 v87, s99, v84
	ds_read_b128 v[88:91], v252 offset:16384
	ds_read_b128 v[92:95], v87
	ds_read_b128 v[96:99], v87 offset:4096
	ds_read_b128 v[100:103], v252 offset:20480
	s_waitcnt lgkmcnt(4)
	v_mfma_f32_32x32x16_bf16 v[48:63], v[236:239], v[240:243], v[48:63]
	v_mfma_f32_32x32x16_bf16 v[32:47], v[236:239], v[244:247], v[32:47]
	v_mfma_f32_32x32x16_bf16 v[16:31], v[248:251], v[240:243], v[16:31]
	v_mfma_f32_32x32x16_bf16 v[0:15], v[248:251], v[244:247], v[0:15]
	s_cmpk_lg_i32 s10, 0x700
	s_cbranch_scc1 .LBB0_741
; DEV int stage_next(int s) { return (s == 2 * GS_STAGE) ? 0 : s + GS_STAGE; }
; template <int WAIT0>
; DEV void gk_main(f32x16 (&acc)[2][2], const GTile& t, int s0) {
;     ...
;   vm_wait_bar<WAIT0>();
;   int stc = s0, std_ = stage_next(stage_next(s0));
; #pragma nounroll
;   for (int kt = 0; kt < nk - 2; ++kt) {
;     GK_DMA(std_, kt + 2);
;     GK_COMPUTE(stc);
;     vm_wait_bar<6>();
;     stc = stage_next(stc); std_ = stage_next(std_);
;   }
;   GK_COMPUTE(stc);
;   vm_wait_bar<0>();
;   stc = stage_next(stc);
;   GK_COMPUTE(stc);
;   vm_wait_bar<0>();
	s_waitcnt lgkmcnt(0)
	s_add_i32 s3, s2, 0
	v_add_u32_e32 v87, s3, v86
	ds_read_b128 v[66:69], v87 offset:16384
	v_add_u32_e32 v74, s3, v84
	ds_read_b128 v[70:73], v74
	ds_read_b128 v[74:77], v74 offset:4096
	ds_read_b128 v[88:91], v87 offset:20480
	v_add_u32_e32 v87, s3, v85
	s_waitcnt lgkmcnt(0)
	v_mfma_f32_32x32x16_bf16 v[0:15], v[88:91], v[74:77], v[0:15]
	v_mfma_f32_32x32x16_bf16 v[48:63], v[66:69], v[70:73], v[48:63]
	v_mfma_f32_32x32x16_bf16 v[32:47], v[66:69], v[74:77], v[32:47]
	ds_read_b128 v[66:69], v87 offset:16384
	v_add_u32_e32 v74, s3, v82
	v_mfma_f32_32x32x16_bf16 v[16:31], v[88:91], v[70:73], v[16:31]
	ds_read_b128 v[70:73], v74
	ds_read_b128 v[74:77], v74 offset:4096
	ds_read_b128 v[88:91], v87 offset:20480
	v_add_u32_e32 v87, s3, v83
	s_waitcnt lgkmcnt(0)
	v_mfma_f32_32x32x16_bf16 v[48:63], v[66:69], v[70:73], v[48:63]
	v_mfma_f32_32x32x16_bf16 v[32:47], v[66:69], v[74:77], v[32:47]
	ds_read_b128 v[66:69], v87 offset:16384
	v_mfma_f32_32x32x16_bf16 v[0:15], v[88:91], v[74:77], v[0:15]
	v_add_u32_e32 v74, s3, v80
	v_mfma_f32_32x32x16_bf16 v[16:31], v[88:91], v[70:73], v[16:31]
	ds_read_b128 v[70:73], v74
	ds_read_b128 v[74:77], v74 offset:4096
	ds_read_b128 v[88:91], v87 offset:20480
	v_add_u32_e32 v87, s3, v81
	s_waitcnt lgkmcnt(0)
	v_mfma_f32_32x32x16_bf16 v[48:63], v[66:69], v[70:73], v[48:63]
	v_mfma_f32_32x32x16_bf16 v[32:47], v[66:69], v[74:77], v[32:47]
	ds_read_b128 v[66:69], v87 offset:16384
	v_mfma_f32_32x32x16_bf16 v[0:15], v[88:91], v[74:77], v[0:15]
	v_add_u32_e32 v74, s3, v79
	s_add_i32 s3, s2, 0xc000
	s_cmp_lg_u32 s2, 0x18000
	s_cselect_b32 s2, s3, 0
	s_add_i32 s2, s2, 0
	v_add_u32_e32 v86, s2, v86
	v_mfma_f32_32x32x16_bf16 v[16:31], v[88:91], v[70:73], v[16:31]
	ds_read_b128 v[70:73], v74
	ds_read_b128 v[74:77], v74 offset:4096
	ds_read_b128 v[88:91], v87 offset:20480
	s_waitcnt vmcnt(0) lgkmcnt(0)
	s_barrier
	s_waitcnt lgkmcnt(0)
	v_mfma_f32_32x32x16_bf16 v[48:63], v[66:69], v[70:73], v[48:63]
	v_mfma_f32_32x32x16_bf16 v[32:47], v[66:69], v[74:77], v[32:47]
	ds_read_b128 v[66:69], v86 offset:16384
	v_mfma_f32_32x32x16_bf16 v[16:31], v[88:91], v[70:73], v[16:31]
	v_mfma_f32_32x32x16_bf16 v[0:15], v[88:91], v[74:77], v[0:15]
	v_add_u32_e32 v74, s2, v84
	ds_read_b128 v[70:73], v74
	ds_read_b128 v[74:77], v74 offset:4096
	ds_read_b128 v[86:89], v86 offset:20480
	v_add_u32_e32 v84, s2, v85
	s_waitcnt lgkmcnt(0)
	v_mfma_f32_32x32x16_bf16 v[48:63], v[66:69], v[70:73], v[48:63]
	v_mfma_f32_32x32x16_bf16 v[32:47], v[66:69], v[74:77], v[32:47]
	ds_read_b128 v[66:69], v84 offset:16384
	v_mfma_f32_32x32x16_bf16 v[16:31], v[86:89], v[70:73], v[16:31]
	v_mfma_f32_32x32x16_bf16 v[0:15], v[86:89], v[74:77], v[0:15]
	v_add_u32_e32 v74, s2, v82
	ds_read_b128 v[70:73], v74
	ds_read_b128 v[74:77], v74 offset:4096
	ds_read_b128 v[84:87], v84 offset:20480
	v_add_u32_e32 v82, s2, v83
	s_waitcnt lgkmcnt(0)
	v_mfma_f32_32x32x16_bf16 v[48:63], v[66:69], v[70:73], v[48:63]
	v_mfma_f32_32x32x16_bf16 v[32:47], v[66:69], v[74:77], v[32:47]
	ds_read_b128 v[66:69], v82 offset:16384
	v_mfma_f32_32x32x16_bf16 v[16:31], v[84:87], v[70:73], v[16:31]
	v_mfma_f32_32x32x16_bf16 v[0:15], v[84:87], v[74:77], v[0:15]
	v_add_u32_e32 v74, s2, v80
	ds_read_b128 v[70:73], v74
	ds_read_b128 v[74:77], v74 offset:4096
	ds_read_b128 v[82:85], v82 offset:20480
	v_add_u32_e32 v80, s2, v81
	s_waitcnt lgkmcnt(0)
	v_mfma_f32_32x32x16_bf16 v[48:63], v[66:69], v[70:73], v[48:63]
	v_mfma_f32_32x32x16_bf16 v[32:47], v[66:69], v[74:77], v[32:47]
	ds_read_b128 v[66:69], v80 offset:16384
	v_mfma_f32_32x32x16_bf16 v[16:31], v[82:85], v[70:73], v[16:31]
	v_mfma_f32_32x32x16_bf16 v[0:15], v[82:85], v[74:77], v[0:15]
	v_add_u32_e32 v74, s2, v79
	ds_read_b128 v[70:73], v74
	ds_read_b128 v[74:77], v74 offset:4096
	ds_read_b128 v[80:83], v80 offset:20480
	s_waitcnt vmcnt(0) lgkmcnt(0)
	s_barrier
	s_waitcnt lgkmcnt(0)
	v_mfma_f32_32x32x16_bf16 v[48:63], v[66:69], v[70:73], v[48:63]
	v_mfma_f32_32x32x16_bf16 v[32:47], v[66:69], v[74:77], v[32:47]
	v_mfma_f32_32x32x16_bf16 v[16:31], v[80:83], v[70:73], v[16:31]
	v_mfma_f32_32x32x16_bf16 v[0:15], v[80:83], v[74:77], v[0:15]

; DEV int stage_next(int s) { return (s == 2 * GS_STAGE) ? 0 : s + GS_STAGE; }
; template <int WAIT0>
; DEV void gk_main(f32x16 (&acc)[2][2], const GTile& t, int s0) {
;     ...
;   vm_wait_bar<WAIT0>();
;   int stc = s0, std_ = stage_next(stage_next(s0));
; #pragma nounroll
;   for (int kt = 0; kt < nk - 2; ++kt) {
;     GK_DMA(std_, kt + 2);
;     GK_COMPUTE(stc);
;     vm_wait_bar<6>();
;     stc = stage_next(stc); std_ = stage_next(std_);
;   }
.LBB0_747:
	s_add_i32 s19, s2, s3
	s_mov_b32 s98, s19
	s_mov_b64 s[100:101], s[10:11]
	v_add_u32_e32 v104, s99, v85
	v_add_u32_e32 v87, s99, v82
	s_add_i32 s19, s16, 0xc000
	s_cmp_lg_u32 s16, 0x18000
	s_cselect_b32 s16, s19, 0
	s_add_i32 s19, s3, 0xc000
	s_cmp_lg_u32 s3, 0x18000
	s_cselect_b32 s3, s19, 0
	s_add_u32 s10, s10, 0x80
	s_addc_u32 s11, s11, 0
	ds_read_b128 v[236:239], v104 offset:16384
	ds_read_b128 v[240:243], v87
	ds_read_b128 v[244:247], v87 offset:4096
	ds_read_b128 v[248:251], v104 offset:20480
	s_waitcnt lgkmcnt(4)
	v_mfma_f32_32x32x16_bf16 v[48:63], v[88:91], v[92:95], v[48:63]
	v_mfma_f32_32x32x16_bf16 v[32:47], v[88:91], v[96:99], v[32:47]
	s_mov_b32 m0, s98
	v_lshl_add_u64 v[254:255], v[76:77], 0, s[100:101]
	global_load_lds_dwordx4 v[254:255], off
	v_mfma_f32_32x32x16_bf16 v[16:31], v[100:103], v[92:95], v[16:31]
	v_mfma_f32_32x32x16_bf16 v[0:15], v[100:103], v[96:99], v[0:15]
	s_add_i32 m0, s98, 0x2000
	v_lshl_add_u64 v[254:255], v[74:75], 0, s[100:101]
	global_load_lds_dwordx4 v[254:255], off
	v_add_u32_e32 v104, s99, v83
	v_add_u32_e32 v87, s99, v80
	ds_read_b128 v[88:91], v104 offset:16384
	ds_read_b128 v[92:95], v87
	ds_read_b128 v[96:99], v87 offset:4096
	ds_read_b128 v[100:103], v104 offset:20480
	s_waitcnt lgkmcnt(4)
	v_mfma_f32_32x32x16_bf16 v[48:63], v[236:239], v[240:243], v[48:63]
	v_mfma_f32_32x32x16_bf16 v[32:47], v[236:239], v[244:247], v[32:47]
	s_add_i32 m0, s98, 0x4000
	v_lshl_add_u64 v[254:255], v[72:73], 0, s[100:101]
	global_load_lds_dwordx4 v[254:255], off
	v_mfma_f32_32x32x16_bf16 v[16:31], v[248:251], v[240:243], v[16:31]
	v_mfma_f32_32x32x16_bf16 v[0:15], v[248:251], v[244:247], v[0:15]
	s_add_i32 m0, s98, 0x6000
	v_lshl_add_u64 v[254:255], v[70:71], 0, s[100:101]
	global_load_lds_dwordx4 v[254:255], off
	v_add_u32_e32 v104, s99, v81
	v_add_u32_e32 v87, s99, v79
	ds_read_b128 v[236:239], v104 offset:16384
	ds_read_b128 v[240:243], v87
	ds_read_b128 v[244:247], v87 offset:4096
	ds_read_b128 v[248:251], v104 offset:20480
	s_waitcnt lgkmcnt(4)
	v_mfma_f32_32x32x16_bf16 v[48:63], v[88:91], v[92:95], v[48:63]
	v_mfma_f32_32x32x16_bf16 v[32:47], v[88:91], v[96:99], v[32:47]
	s_add_i32 m0, s98, 0x8000
	v_lshl_add_u64 v[254:255], v[68:69], 0, s[100:101]
	global_load_lds_dwordx4 v[254:255], off
	v_mfma_f32_32x32x16_bf16 v[16:31], v[100:103], v[92:95], v[16:31]
	v_mfma_f32_32x32x16_bf16 v[0:15], v[100:103], v[96:99], v[0:15]
	s_add_i32 m0, s98, 0xa000
	v_lshl_add_u64 v[254:255], v[66:67], 0, s[100:101]
	global_load_lds_dwordx4 v[254:255], off
	s_waitcnt vmcnt(6) lgkmcnt(0)
	s_barrier
	s_add_i32 s99, s16, 0
	v_add_u32_e32 v252, s99, v86
	v_add_u32_e32 v87, s99, v84
	ds_read_b128 v[88:91], v252 offset:16384
	ds_read_b128 v[92:95], v87
	ds_read_b128 v[96:99], v87 offset:4096
	ds_read_b128 v[100:103], v252 offset:20480
	s_waitcnt lgkmcnt(4)
	v_mfma_f32_32x32x16_bf16 v[48:63], v[236:239], v[240:243], v[48:63]
	v_mfma_f32_32x32x16_bf16 v[32:47], v[236:239], v[244:247], v[32:47]
	v_mfma_f32_32x32x16_bf16 v[16:31], v[248:251], v[240:243], v[16:31]
	v_mfma_f32_32x32x16_bf16 v[0:15], v[248:251], v[244:247], v[0:15]
	s_cmpk_lg_i32 s10, 0x700
	s_cbranch_scc1 .LBB0_747
; DEV int stage_next(int s) { return (s == 2 * GS_STAGE) ? 0 : s + GS_STAGE; }
; template <int WAIT0>
; DEV void gk_main(f32x16 (&acc)[2][2], const GTile& t, int s0) {
;     ...
;   vm_wait_bar<WAIT0>();
;   int stc = s0, std_ = stage_next(stage_next(s0));
; #pragma nounroll
;   for (int kt = 0; kt < nk - 2; ++kt) {
;     GK_DMA(std_, kt + 2);
;     GK_COMPUTE(stc);
;     vm_wait_bar<6>();
;     stc = stage_next(stc); std_ = stage_next(std_);
;   }
;   GK_COMPUTE(stc);
;   vm_wait_bar<0>();
;   stc = stage_next(stc);
;   GK_COMPUTE(stc);
;   vm_wait_bar<0>();
	s_waitcnt lgkmcnt(0)
	s_add_i32 s2, s16, 0
	v_add_u32_e32 v87, s2, v86
	ds_read_b128 v[66:69], v87 offset:16384
	v_add_u32_e32 v74, s2, v84
	ds_read_b128 v[70:73], v74
	ds_read_b128 v[74:77], v74 offset:4096
	ds_read_b128 v[88:91], v87 offset:20480
	v_add_u32_e32 v87, s2, v85
	s_waitcnt lgkmcnt(0)
	v_mfma_f32_32x32x16_bf16 v[0:15], v[88:91], v[74:77], v[0:15]
	v_mfma_f32_32x32x16_bf16 v[48:63], v[66:69], v[70:73], v[48:63]
	v_mfma_f32_32x32x16_bf16 v[32:47], v[66:69], v[74:77], v[32:47]
	ds_read_b128 v[66:69], v87 offset:16384
	v_add_u32_e32 v74, s2, v82
	v_mfma_f32_32x32x16_bf16 v[16:31], v[88:91], v[70:73], v[16:31]
	ds_read_b128 v[70:73], v74
	ds_read_b128 v[74:77], v74 offset:4096
	ds_read_b128 v[88:91], v87 offset:20480
	v_add_u32_e32 v87, s2, v83
	s_waitcnt lgkmcnt(0)
	v_mfma_f32_32x32x16_bf16 v[48:63], v[66:69], v[70:73], v[48:63]
	v_mfma_f32_32x32x16_bf16 v[32:47], v[66:69], v[74:77], v[32:47]
	ds_read_b128 v[66:69], v87 offset:16384
	v_mfma_f32_32x32x16_bf16 v[0:15], v[88:91], v[74:77], v[0:15]
	v_add_u32_e32 v74, s2, v80
	v_mfma_f32_32x32x16_bf16 v[16:31], v[88:91], v[70:73], v[16:31]
	ds_read_b128 v[70:73], v74
	ds_read_b128 v[74:77], v74 offset:4096
	ds_read_b128 v[88:91], v87 offset:20480
	v_add_u32_e32 v87, s2, v81
	s_waitcnt lgkmcnt(0)
	v_mfma_f32_32x32x16_bf16 v[48:63], v[66:69], v[70:73], v[48:63]
	v_mfma_f32_32x32x16_bf16 v[32:47], v[66:69], v[74:77], v[32:47]
	ds_read_b128 v[66:69], v87 offset:16384
	v_mfma_f32_32x32x16_bf16 v[0:15], v[88:91], v[74:77], v[0:15]
	v_add_u32_e32 v74, s2, v79
	s_add_i32 s2, s16, 0xc000
	s_cmp_lg_u32 s16, 0x18000
	s_cselect_b32 s2, s2, 0
	s_add_i32 s2, s2, 0
	v_add_u32_e32 v86, s2, v86
	v_mfma_f32_32x32x16_bf16 v[16:31], v[88:91], v[70:73], v[16:31]
	ds_read_b128 v[70:73], v74
	ds_read_b128 v[74:77], v74 offset:4096
	ds_read_b128 v[88:91], v87 offset:20480
	s_waitcnt vmcnt(0) lgkmcnt(0)
	s_barrier
	s_waitcnt lgkmcnt(0)
	v_mfma_f32_32x32x16_bf16 v[48:63], v[66:69], v[70:73], v[48:63]
	v_mfma_f32_32x32x16_bf16 v[32:47], v[66:69], v[74:77], v[32:47]
	ds_read_b128 v[66:69], v86 offset:16384
	v_mfma_f32_32x32x16_bf16 v[16:31], v[88:91], v[70:73], v[16:31]
	v_mfma_f32_32x32x16_bf16 v[0:15], v[88:91], v[74:77], v[0:15]
	v_add_u32_e32 v74, s2, v84
	ds_read_b128 v[70:73], v74
	ds_read_b128 v[74:77], v74 offset:4096
	ds_read_b128 v[86:89], v86 offset:20480
	v_add_u32_e32 v84, s2, v85
	s_waitcnt lgkmcnt(0)
	v_mfma_f32_32x32x16_bf16 v[48:63], v[66:69], v[70:73], v[48:63]
	v_mfma_f32_32x32x16_bf16 v[32:47], v[66:69], v[74:77], v[32:47]
	ds_read_b128 v[66:69], v84 offset:16384
	v_mfma_f32_32x32x16_bf16 v[16:31], v[86:89], v[70:73], v[16:31]
	v_mfma_f32_32x32x16_bf16 v[0:15], v[86:89], v[74:77], v[0:15]
	v_add_u32_e32 v74, s2, v82
	ds_read_b128 v[70:73], v74
	ds_read_b128 v[74:77], v74 offset:4096
	ds_read_b128 v[84:87], v84 offset:20480
	v_add_u32_e32 v82, s2, v83
	s_waitcnt lgkmcnt(0)
	v_mfma_f32_32x32x16_bf16 v[48:63], v[66:69], v[70:73], v[48:63]
	v_mfma_f32_32x32x16_bf16 v[32:47], v[66:69], v[74:77], v[32:47]
	ds_read_b128 v[66:69], v82 offset:16384
	v_mfma_f32_32x32x16_bf16 v[16:31], v[84:87], v[70:73], v[16:31]
	v_mfma_f32_32x32x16_bf16 v[0:15], v[84:87], v[74:77], v[0:15]
	v_add_u32_e32 v74, s2, v80
	ds_read_b128 v[70:73], v74
	ds_read_b128 v[74:77], v74 offset:4096
	ds_read_b128 v[82:85], v82 offset:20480
	v_add_u32_e32 v80, s2, v81
	s_waitcnt lgkmcnt(0)
	v_mfma_f32_32x32x16_bf16 v[48:63], v[66:69], v[70:73], v[48:63]
	v_mfma_f32_32x32x16_bf16 v[32:47], v[66:69], v[74:77], v[32:47]
	ds_read_b128 v[66:69], v80 offset:16384
	v_mfma_f32_32x32x16_bf16 v[16:31], v[82:85], v[70:73], v[16:31]
	v_mfma_f32_32x32x16_bf16 v[0:15], v[82:85], v[74:77], v[0:15]
	v_add_u32_e32 v74, s2, v79
	ds_read_b128 v[70:73], v74
	ds_read_b128 v[74:77], v74 offset:4096
	ds_read_b128 v[80:83], v80 offset:20480
	s_waitcnt vmcnt(0) lgkmcnt(0)
	s_barrier
	s_waitcnt lgkmcnt(0)
	v_mfma_f32_32x32x16_bf16 v[48:63], v[66:69], v[70:73], v[48:63]
	v_mfma_f32_32x32x16_bf16 v[32:47], v[66:69], v[74:77], v[32:47]
	v_mfma_f32_32x32x16_bf16 v[16:31], v[80:83], v[70:73], v[16:31]
	v_mfma_f32_32x32x16_bf16 v[0:15], v[80:83], v[74:77], v[0:15]
	s_add_i32 s2, s17, 1
	s_mov_b32 s16, s18
	s_cmp_eq_u32 s17, 3
	s_cbranch_scc1 .LBB0_733

; DEV int stage_next(int s) { return (s == 2 * GS_STAGE) ? 0 : s + GS_STAGE; }
; template <int WAIT0>
; DEV void gk_main(f32x16 (&acc)[2][2], const GTile& t, int s0) {
;     ...
;   vm_wait_bar<WAIT0>();
;   int stc = s0, std_ = stage_next(stage_next(s0));
; #pragma nounroll
;   for (int kt = 0; kt < nk - 2; ++kt) {
;     GK_DMA(std_, kt + 2);
;     GK_COMPUTE(stc);
;     vm_wait_bar<6>();
;     stc = stage_next(stc); std_ = stage_next(std_);
;   }
.LBB0_842:
	s_add_i32 s10, s2, s3
	s_mov_b32 s98, s10
	v_add_u32_e32 v101, s99, v82
	v_add_u32_e32 v100, s99, v79
	s_add_i32 s10, s9, 0xc000
	s_cmp_lg_u32 s9, 0x18000
	s_cselect_b32 s9, s10, 0
	s_add_i32 s10, s3, 0xc000
	s_cmp_lg_u32 s3, 0x18000
	s_cselect_b32 s3, s10, 0
	s_add_i32 s8, s8, -1
	ds_read_b128 v[236:239], v101 offset:16384
	ds_read_b128 v[240:243], v100
	ds_read_b128 v[244:247], v100 offset:4096
	ds_read_b128 v[248:251], v101 offset:20480
	s_waitcnt lgkmcnt(4)
	v_mfma_f32_32x32x16_bf16 v[48:63], v[84:87], v[88:91], v[48:63]
	v_mfma_f32_32x32x16_bf16 v[32:47], v[84:87], v[92:95], v[32:47]
	s_mov_b32 m0, s98
	v_lshl_add_u64 v[254:255], v[74:75], 0, v[120:121]
	global_load_lds_dwordx4 v[254:255], off
	v_lshl_add_u64 v[74:75], v[74:75], 0, s[94:95]
	v_mfma_f32_32x32x16_bf16 v[16:31], v[96:99], v[88:91], v[16:31]
	v_mfma_f32_32x32x16_bf16 v[0:15], v[96:99], v[92:95], v[0:15]
	s_add_i32 m0, s98, 0x2000
	v_lshl_add_u64 v[254:255], v[72:73], 0, v[120:121]
	global_load_lds_dwordx4 v[254:255], off
	v_lshl_add_u64 v[72:73], v[72:73], 0, s[94:95]
	v_add_u32_e32 v101, s99, v80
	v_add_u32_e32 v100, s99, v77
	ds_read_b128 v[84:87], v101 offset:16384
	ds_read_b128 v[88:91], v100
	ds_read_b128 v[92:95], v100 offset:4096
	ds_read_b128 v[96:99], v101 offset:20480
	s_waitcnt lgkmcnt(4)
	v_mfma_f32_32x32x16_bf16 v[48:63], v[236:239], v[240:243], v[48:63]
	v_mfma_f32_32x32x16_bf16 v[32:47], v[236:239], v[244:247], v[32:47]
	s_add_i32 m0, s98, 0x4000
	v_lshl_add_u64 v[254:255], v[70:71], 0, v[120:121]
	global_load_lds_dwordx4 v[254:255], off
	v_lshl_add_u64 v[70:71], v[70:71], 0, s[94:95]
	v_mfma_f32_32x32x16_bf16 v[16:31], v[248:251], v[240:243], v[16:31]
	v_mfma_f32_32x32x16_bf16 v[0:15], v[248:251], v[244:247], v[0:15]
	s_add_i32 m0, s98, 0x6000
	v_lshl_add_u64 v[254:255], v[68:69], 0, v[120:121]
	global_load_lds_dwordx4 v[254:255], off
	v_lshl_add_u64 v[68:69], v[68:69], 0, s[94:95]
	v_add_u32_e32 v101, s99, v78
	v_add_u32_e32 v100, s99, v76
	ds_read_b128 v[236:239], v101 offset:16384
	ds_read_b128 v[240:243], v100
	ds_read_b128 v[244:247], v100 offset:4096
	ds_read_b128 v[248:251], v101 offset:20480
	s_waitcnt lgkmcnt(4)
	v_mfma_f32_32x32x16_bf16 v[48:63], v[84:87], v[88:91], v[48:63]
	v_mfma_f32_32x32x16_bf16 v[32:47], v[84:87], v[92:95], v[32:47]
	s_add_i32 m0, s98, 0x8000
	v_lshl_add_u64 v[254:255], v[66:67], 0, v[120:121]
	global_load_lds_dwordx4 v[254:255], off
	v_lshl_add_u64 v[66:67], v[66:67], 0, s[94:95]
	v_mfma_f32_32x32x16_bf16 v[16:31], v[96:99], v[88:91], v[16:31]
	v_mfma_f32_32x32x16_bf16 v[0:15], v[96:99], v[92:95], v[0:15]
	s_add_i32 m0, s98, 0xa000
	v_lshl_add_u64 v[254:255], v[64:65], 0, v[120:121]
	global_load_lds_dwordx4 v[254:255], off
	v_lshl_add_u64 v[64:65], v[64:65], 0, s[94:95]
	s_waitcnt vmcnt(6) lgkmcnt(0)
	s_barrier
	s_add_i32 s99, s9, 0
	v_add_u32_e32 v253, s99, v81
	v_add_u32_e32 v252, s99, v83
	ds_read_b128 v[84:87], v252 offset:16384
	ds_read_b128 v[88:91], v253
	ds_read_b128 v[92:95], v253 offset:4096
	ds_read_b128 v[96:99], v252 offset:20480
	s_waitcnt lgkmcnt(4)
	v_mfma_f32_32x32x16_bf16 v[48:63], v[236:239], v[240:243], v[48:63]
	v_mfma_f32_32x32x16_bf16 v[32:47], v[236:239], v[244:247], v[32:47]
	v_mfma_f32_32x32x16_bf16 v[16:31], v[248:251], v[240:243], v[16:31]
	v_mfma_f32_32x32x16_bf16 v[0:15], v[248:251], v[244:247], v[0:15]
	s_cmp_lg_u32 s8, 0
	s_cbranch_scc1 .LBB0_842
; DEV int stage_next(int s) { return (s == 2 * GS_STAGE) ? 0 : s + GS_STAGE; }
; template <int WAIT0>
; DEV void gk_main(f32x16 (&acc)[2][2], const GTile& t, int s0) {
;     ...
;   vm_wait_bar<WAIT0>();
;   int stc = s0, std_ = stage_next(stage_next(s0));
; #pragma nounroll
;   for (int kt = 0; kt < nk - 2; ++kt) {
;     GK_DMA(std_, kt + 2);
;     GK_COMPUTE(stc);
;     vm_wait_bar<6>();
;     stc = stage_next(stc); std_ = stage_next(std_);
;   }
;   GK_COMPUTE(stc);
;   vm_wait_bar<0>();
;   stc = stage_next(stc);
;   GK_COMPUTE(stc);
;   vm_wait_bar<0>();
	s_waitcnt lgkmcnt(0)
	s_add_i32 s2, s9, 0
	v_add_u32_e32 v84, s2, v83
	ds_read_b128 v[64:67], v84 offset:16384
	v_add_u32_e32 v72, s2, v81
	ds_read_b128 v[68:71], v72
	ds_read_b128 v[72:75], v72 offset:4096
	ds_read_b128 v[84:87], v84 offset:20480
	s_waitcnt lgkmcnt(0)
	v_mfma_f32_32x32x16_bf16 v[16:31], v[84:87], v[68:71], v[16:31]
	v_mfma_f32_32x32x16_bf16 v[0:15], v[84:87], v[72:75], v[0:15]
	v_add_u32_e32 v84, s2, v82
	v_mfma_f32_32x32x16_bf16 v[48:63], v[64:67], v[68:71], v[48:63]
	v_mfma_f32_32x32x16_bf16 v[32:47], v[64:67], v[72:75], v[32:47]
	ds_read_b128 v[64:67], v84 offset:16384
	v_add_u32_e32 v72, s2, v79
	ds_read_b128 v[68:71], v72
	ds_read_b128 v[72:75], v72 offset:4096
	ds_read_b128 v[84:87], v84 offset:20480
	s_waitcnt lgkmcnt(0)
	v_mfma_f32_32x32x16_bf16 v[16:31], v[84:87], v[68:71], v[16:31]
	v_mfma_f32_32x32x16_bf16 v[0:15], v[84:87], v[72:75], v[0:15]
	v_add_u32_e32 v84, s2, v80
	v_mfma_f32_32x32x16_bf16 v[48:63], v[64:67], v[68:71], v[48:63]
	v_mfma_f32_32x32x16_bf16 v[32:47], v[64:67], v[72:75], v[32:47]
	ds_read_b128 v[64:67], v84 offset:16384
	v_add_u32_e32 v72, s2, v77
	ds_read_b128 v[68:71], v72
	ds_read_b128 v[72:75], v72 offset:4096
	ds_read_b128 v[84:87], v84 offset:20480
	s_waitcnt lgkmcnt(0)
	v_mfma_f32_32x32x16_bf16 v[16:31], v[84:87], v[68:71], v[16:31]
	v_mfma_f32_32x32x16_bf16 v[0:15], v[84:87], v[72:75], v[0:15]
	v_add_u32_e32 v84, s2, v78
	v_mfma_f32_32x32x16_bf16 v[48:63], v[64:67], v[68:71], v[48:63]
	v_mfma_f32_32x32x16_bf16 v[32:47], v[64:67], v[72:75], v[32:47]
	ds_read_b128 v[64:67], v84 offset:16384
	v_add_u32_e32 v72, s2, v76
	s_add_i32 s2, s9, 0xc000
	ds_read_b128 v[68:71], v72
	ds_read_b128 v[72:75], v72 offset:4096
	ds_read_b128 v[84:87], v84 offset:20480
	s_cmp_lg_u32 s9, 0x18000
	s_cselect_b32 s2, s2, 0
	s_add_i32 s2, s2, 0
	s_waitcnt vmcnt(0) lgkmcnt(0)
	s_barrier
	v_add_u32_e32 v83, s2, v83
	s_waitcnt lgkmcnt(0)
	v_mfma_f32_32x32x16_bf16 v[48:63], v[64:67], v[68:71], v[48:63]
	s_mov_b64 s[8:9], 0
	v_mfma_f32_32x32x16_bf16 v[32:47], v[64:67], v[72:75], v[32:47]
	ds_read_b128 v[64:67], v83 offset:16384
	v_mfma_f32_32x32x16_bf16 v[16:31], v[84:87], v[68:71], v[16:31]
	v_mfma_f32_32x32x16_bf16 v[0:15], v[84:87], v[72:75], v[0:15]
	v_add_u32_e32 v72, s2, v81
	ds_read_b128 v[68:71], v72
	ds_read_b128 v[72:75], v72 offset:4096
	ds_read_b128 v[84:87], v83 offset:20480
	v_add_u32_e32 v81, s2, v82
	s_waitcnt lgkmcnt(0)
	v_mfma_f32_32x32x16_bf16 v[48:63], v[64:67], v[68:71], v[48:63]
	v_mfma_f32_32x32x16_bf16 v[32:47], v[64:67], v[72:75], v[32:47]
	ds_read_b128 v[64:67], v81 offset:16384
	v_mfma_f32_32x32x16_bf16 v[16:31], v[84:87], v[68:71], v[16:31]
	v_mfma_f32_32x32x16_bf16 v[0:15], v[84:87], v[72:75], v[0:15]
	v_add_u32_e32 v72, s2, v79
	ds_read_b128 v[68:71], v72
	ds_read_b128 v[72:75], v72 offset:4096
	ds_read_b128 v[82:85], v81 offset:20480
	v_add_u32_e32 v79, s2, v80
	s_waitcnt lgkmcnt(0)
	v_mfma_f32_32x32x16_bf16 v[48:63], v[64:67], v[68:71], v[48:63]
	v_mfma_f32_32x32x16_bf16 v[32:47], v[64:67], v[72:75], v[32:47]
	ds_read_b128 v[64:67], v79 offset:16384
	v_mfma_f32_32x32x16_bf16 v[16:31], v[82:85], v[68:71], v[16:31]
	v_mfma_f32_32x32x16_bf16 v[0:15], v[82:85], v[72:75], v[0:15]
	v_add_u32_e32 v72, s2, v77
	ds_read_b128 v[68:71], v72
	ds_read_b128 v[72:75], v72 offset:4096
	ds_read_b128 v[80:83], v79 offset:20480
	v_add_u32_e32 v77, s2, v78
	s_waitcnt lgkmcnt(0)
	v_mfma_f32_32x32x16_bf16 v[48:63], v[64:67], v[68:71], v[48:63]
	v_mfma_f32_32x32x16_bf16 v[32:47], v[64:67], v[72:75], v[32:47]
	ds_read_b128 v[64:67], v77 offset:16384
	v_mfma_f32_32x32x16_bf16 v[16:31], v[80:83], v[68:71], v[16:31]
	v_mfma_f32_32x32x16_bf16 v[0:15], v[80:83], v[72:75], v[0:15]
	v_add_u32_e32 v72, s2, v76
	ds_read_b128 v[68:71], v72
	ds_read_b128 v[72:75], v72 offset:4096
	ds_read_b128 v[76:79], v77 offset:20480
	s_waitcnt vmcnt(0) lgkmcnt(0)
	s_barrier
	s_waitcnt lgkmcnt(0)
	v_mfma_f32_32x32x16_bf16 v[48:63], v[64:67], v[68:71], v[48:63]
	v_mfma_f32_32x32x16_bf16 v[32:47], v[64:67], v[72:75], v[32:47]
	v_mfma_f32_32x32x16_bf16 v[16:31], v[76:79], v[68:71], v[16:31]
	v_mfma_f32_32x32x16_bf16 v[0:15], v[76:79], v[72:75], v[0:15]

; DEV int stage_next(int s) { return (s == 2 * GS_STAGE) ? 0 : s + GS_STAGE; }
; template <int WAIT0>
; DEV void gk_main(f32x16 (&acc)[2][2], const GTile& t, int s0) {
;     ...
;   vm_wait_bar<WAIT0>();
;   int stc = s0, std_ = stage_next(stage_next(s0));
; #pragma nounroll
;   for (int kt = 0; kt < nk - 2; ++kt) {
;     GK_DMA(std_, kt + 2);
;     GK_COMPUTE(stc);
;     vm_wait_bar<6>();
;     stc = stage_next(stc); std_ = stage_next(std_);
;   }
.LBB0_846:
	s_add_i32 s10, s2, s3
	s_mov_b32 s98, s10
	v_add_u32_e32 v101, s99, v82
	v_add_u32_e32 v100, s99, v79
	s_add_i32 s10, s9, 0xc000
	s_cmp_lg_u32 s9, 0x18000
	s_cselect_b32 s9, s10, 0
	s_add_i32 s10, s3, 0xc000
	s_cmp_lg_u32 s3, 0x18000
	s_cselect_b32 s3, s10, 0
	s_add_i32 s8, s8, -1
	ds_read_b128 v[236:239], v101 offset:16384
	ds_read_b128 v[240:243], v100
	ds_read_b128 v[244:247], v100 offset:4096
	ds_read_b128 v[248:251], v101 offset:20480
	s_waitcnt lgkmcnt(4)
	v_mfma_f32_32x32x16_bf16 v[48:63], v[84:87], v[88:91], v[48:63]
	v_mfma_f32_32x32x16_bf16 v[32:47], v[84:87], v[92:95], v[32:47]
	s_mov_b32 m0, s98
	v_lshl_add_u64 v[254:255], v[74:75], 0, v[120:121]
	global_load_lds_dwordx4 v[254:255], off
	v_lshl_add_u64 v[74:75], v[74:75], 0, s[94:95]
	v_mfma_f32_32x32x16_bf16 v[16:31], v[96:99], v[88:91], v[16:31]
	v_mfma_f32_32x32x16_bf16 v[0:15], v[96:99], v[92:95], v[0:15]
	s_add_i32 m0, s98, 0x2000
	v_lshl_add_u64 v[254:255], v[72:73], 0, v[120:121]
	global_load_lds_dwordx4 v[254:255], off
	v_lshl_add_u64 v[72:73], v[72:73], 0, s[94:95]
	v_add_u32_e32 v101, s99, v80
	v_add_u32_e32 v100, s99, v77
	ds_read_b128 v[84:87], v101 offset:16384
	ds_read_b128 v[88:91], v100
	ds_read_b128 v[92:95], v100 offset:4096
	ds_read_b128 v[96:99], v101 offset:20480
	s_waitcnt lgkmcnt(4)
	v_mfma_f32_32x32x16_bf16 v[48:63], v[236:239], v[240:243], v[48:63]
	v_mfma_f32_32x32x16_bf16 v[32:47], v[236:239], v[244:247], v[32:47]
	s_add_i32 m0, s98, 0x4000
	v_lshl_add_u64 v[254:255], v[70:71], 0, v[120:121]
	global_load_lds_dwordx4 v[254:255], off
	v_lshl_add_u64 v[70:71], v[70:71], 0, s[94:95]
	v_mfma_f32_32x32x16_bf16 v[16:31], v[248:251], v[240:243], v[16:31]
	v_mfma_f32_32x32x16_bf16 v[0:15], v[248:251], v[244:247], v[0:15]
	s_add_i32 m0, s98, 0x6000
	v_lshl_add_u64 v[254:255], v[68:69], 0, v[120:121]
	global_load_lds_dwordx4 v[254:255], off
	v_lshl_add_u64 v[68:69], v[68:69], 0, s[94:95]
	v_add_u32_e32 v101, s99, v78
	v_add_u32_e32 v100, s99, v76
	ds_read_b128 v[236:239], v101 offset:16384
	ds_read_b128 v[240:243], v100
	ds_read_b128 v[244:247], v100 offset:4096
	ds_read_b128 v[248:251], v101 offset:20480
	s_waitcnt lgkmcnt(4)
	v_mfma_f32_32x32x16_bf16 v[48:63], v[84:87], v[88:91], v[48:63]
	v_mfma_f32_32x32x16_bf16 v[32:47], v[84:87], v[92:95], v[32:47]
	s_add_i32 m0, s98, 0x8000
	v_lshl_add_u64 v[254:255], v[66:67], 0, v[120:121]
	global_load_lds_dwordx4 v[254:255], off
	v_lshl_add_u64 v[66:67], v[66:67], 0, s[94:95]
	v_mfma_f32_32x32x16_bf16 v[16:31], v[96:99], v[88:91], v[16:31]
	v_mfma_f32_32x32x16_bf16 v[0:15], v[96:99], v[92:95], v[0:15]
	s_add_i32 m0, s98, 0xa000
	v_lshl_add_u64 v[254:255], v[64:65], 0, v[120:121]
	global_load_lds_dwordx4 v[254:255], off
	v_lshl_add_u64 v[64:65], v[64:65], 0, s[94:95]
	s_waitcnt vmcnt(6) lgkmcnt(0)
	s_barrier
	s_add_i32 s99, s9, 0
	v_add_u32_e32 v253, s99, v81
	v_add_u32_e32 v252, s99, v83
	ds_read_b128 v[84:87], v252 offset:16384
	ds_read_b128 v[88:91], v253
	ds_read_b128 v[92:95], v253 offset:4096
	ds_read_b128 v[96:99], v252 offset:20480
	s_waitcnt lgkmcnt(4)
	v_mfma_f32_32x32x16_bf16 v[48:63], v[236:239], v[240:243], v[48:63]
	v_mfma_f32_32x32x16_bf16 v[32:47], v[236:239], v[244:247], v[32:47]
	v_mfma_f32_32x32x16_bf16 v[16:31], v[248:251], v[240:243], v[16:31]
	v_mfma_f32_32x32x16_bf16 v[0:15], v[248:251], v[244:247], v[0:15]
	s_cmp_lg_u32 s8, 0
	s_cbranch_scc1 .LBB0_846
; DEV int stage_next(int s) { return (s == 2 * GS_STAGE) ? 0 : s + GS_STAGE; }
; template <int WAIT0>
; DEV void gk_main(f32x16 (&acc)[2][2], const GTile& t, int s0) {
;     ...
;   vm_wait_bar<WAIT0>();
;   int stc = s0, std_ = stage_next(stage_next(s0));
; #pragma nounroll
;   for (int kt = 0; kt < nk - 2; ++kt) {
;     GK_DMA(std_, kt + 2);
;     GK_COMPUTE(stc);
;     vm_wait_bar<6>();
;     stc = stage_next(stc); std_ = stage_next(std_);
;   }
;   GK_COMPUTE(stc);
;   vm_wait_bar<0>();
;   stc = stage_next(stc);
;   GK_COMPUTE(stc);
;   vm_wait_bar<0>();
	s_waitcnt lgkmcnt(0)
	s_add_i32 s2, s9, 0
	v_add_u32_e32 v84, s2, v83
	ds_read_b128 v[64:67], v84 offset:16384
	v_add_u32_e32 v72, s2, v81
	ds_read_b128 v[68:71], v72
	ds_read_b128 v[72:75], v72 offset:4096
	ds_read_b128 v[84:87], v84 offset:20480
	s_waitcnt lgkmcnt(0)
	v_mfma_f32_32x32x16_bf16 v[16:31], v[84:87], v[68:71], v[16:31]
	v_mfma_f32_32x32x16_bf16 v[0:15], v[84:87], v[72:75], v[0:15]
	v_add_u32_e32 v84, s2, v82
	v_mfma_f32_32x32x16_bf16 v[48:63], v[64:67], v[68:71], v[48:63]
	v_mfma_f32_32x32x16_bf16 v[32:47], v[64:67], v[72:75], v[32:47]
	ds_read_b128 v[64:67], v84 offset:16384
	v_add_u32_e32 v72, s2, v79
	ds_read_b128 v[68:71], v72
	ds_read_b128 v[72:75], v72 offset:4096
	ds_read_b128 v[84:87], v84 offset:20480
	s_waitcnt lgkmcnt(0)
	v_mfma_f32_32x32x16_bf16 v[16:31], v[84:87], v[68:71], v[16:31]
	v_mfma_f32_32x32x16_bf16 v[0:15], v[84:87], v[72:75], v[0:15]
	v_add_u32_e32 v84, s2, v80
	v_mfma_f32_32x32x16_bf16 v[48:63], v[64:67], v[68:71], v[48:63]
	v_mfma_f32_32x32x16_bf16 v[32:47], v[64:67], v[72:75], v[32:47]
	ds_read_b128 v[64:67], v84 offset:16384
	v_add_u32_e32 v72, s2, v77
	ds_read_b128 v[68:71], v72
	ds_read_b128 v[72:75], v72 offset:4096
	ds_read_b128 v[84:87], v84 offset:20480
	s_waitcnt lgkmcnt(0)
	v_mfma_f32_32x32x16_bf16 v[16:31], v[84:87], v[68:71], v[16:31]
	v_mfma_f32_32x32x16_bf16 v[0:15], v[84:87], v[72:75], v[0:15]
	v_add_u32_e32 v84, s2, v78
	v_mfma_f32_32x32x16_bf16 v[48:63], v[64:67], v[68:71], v[48:63]
	v_mfma_f32_32x32x16_bf16 v[32:47], v[64:67], v[72:75], v[32:47]
	ds_read_b128 v[64:67], v84 offset:16384
	v_add_u32_e32 v72, s2, v76
	s_add_i32 s2, s9, 0xc000
	ds_read_b128 v[68:71], v72
	ds_read_b128 v[72:75], v72 offset:4096
	ds_read_b128 v[84:87], v84 offset:20480
	s_cmp_lg_u32 s9, 0x18000
	s_cselect_b32 s2, s2, 0
	s_add_i32 s2, s2, 0
	s_waitcnt vmcnt(0) lgkmcnt(0)
	s_barrier
	v_add_u32_e32 v83, s2, v83
	s_waitcnt lgkmcnt(0)
	v_mfma_f32_32x32x16_bf16 v[48:63], v[64:67], v[68:71], v[48:63]
	v_mfma_f32_32x32x16_bf16 v[32:47], v[64:67], v[72:75], v[32:47]
	ds_read_b128 v[64:67], v83 offset:16384
	v_mfma_f32_32x32x16_bf16 v[16:31], v[84:87], v[68:71], v[16:31]
	v_mfma_f32_32x32x16_bf16 v[0:15], v[84:87], v[72:75], v[0:15]
	v_add_u32_e32 v72, s2, v81
	ds_read_b128 v[68:71], v72
	ds_read_b128 v[72:75], v72 offset:4096
	ds_read_b128 v[84:87], v83 offset:20480
	v_add_u32_e32 v81, s2, v82
	s_waitcnt lgkmcnt(0)
	v_mfma_f32_32x32x16_bf16 v[48:63], v[64:67], v[68:71], v[48:63]
	v_mfma_f32_32x32x16_bf16 v[32:47], v[64:67], v[72:75], v[32:47]
	ds_read_b128 v[64:67], v81 offset:16384
	v_mfma_f32_32x32x16_bf16 v[16:31], v[84:87], v[68:71], v[16:31]
	v_mfma_f32_32x32x16_bf16 v[0:15], v[84:87], v[72:75], v[0:15]
	v_add_u32_e32 v72, s2, v79
	ds_read_b128 v[68:71], v72
	ds_read_b128 v[72:75], v72 offset:4096
	ds_read_b128 v[82:85], v81 offset:20480
	v_add_u32_e32 v79, s2, v80
	s_waitcnt lgkmcnt(0)
	v_mfma_f32_32x32x16_bf16 v[48:63], v[64:67], v[68:71], v[48:63]
	v_mfma_f32_32x32x16_bf16 v[32:47], v[64:67], v[72:75], v[32:47]
	ds_read_b128 v[64:67], v79 offset:16384
	v_mfma_f32_32x32x16_bf16 v[16:31], v[82:85], v[68:71], v[16:31]
	v_mfma_f32_32x32x16_bf16 v[0:15], v[82:85], v[72:75], v[0:15]
	v_add_u32_e32 v72, s2, v77
	ds_read_b128 v[68:71], v72
	ds_read_b128 v[72:75], v72 offset:4096
	ds_read_b128 v[80:83], v79 offset:20480
	v_add_u32_e32 v77, s2, v78
	s_waitcnt lgkmcnt(0)
	v_mfma_f32_32x32x16_bf16 v[48:63], v[64:67], v[68:71], v[48:63]
	v_mfma_f32_32x32x16_bf16 v[32:47], v[64:67], v[72:75], v[32:47]
	ds_read_b128 v[64:67], v77 offset:16384
	v_mfma_f32_32x32x16_bf16 v[16:31], v[80:83], v[68:71], v[16:31]
	v_mfma_f32_32x32x16_bf16 v[0:15], v[80:83], v[72:75], v[0:15]
	v_add_u32_e32 v72, s2, v76
	ds_read_b128 v[68:71], v72
	ds_read_b128 v[72:75], v72 offset:4096
	ds_read_b128 v[76:79], v77 offset:20480
	s_waitcnt vmcnt(0) lgkmcnt(0)
	s_barrier
	s_waitcnt lgkmcnt(0)
	v_mfma_f32_32x32x16_bf16 v[48:63], v[64:67], v[68:71], v[48:63]
	v_mfma_f32_32x32x16_bf16 v[32:47], v[64:67], v[72:75], v[32:47]
	v_mfma_f32_32x32x16_bf16 v[16:31], v[76:79], v[68:71], v[16:31]
	v_mfma_f32_32x32x16_bf16 v[0:15], v[76:79], v[72:75], v[0:15]

; DEV int stage_next(int s) { return (s == 2 * GS_STAGE) ? 0 : s + GS_STAGE; }
; template <int WAIT0>
; DEV void gk_main(f32x16 (&acc)[2][2], const GTile& t, int s0) {
;     ...
;   vm_wait_bar<WAIT0>();
;   int stc = s0, std_ = stage_next(stage_next(s0));
; #pragma nounroll
;   for (int kt = 0; kt < nk - 2; ++kt) {
;     GK_DMA(std_, kt + 2);
;     GK_COMPUTE(stc);
;     vm_wait_bar<6>();
;     stc = stage_next(stc); std_ = stage_next(std_);
;   }
.LBB0_854:
	s_add_i32 s10, s2, s3
	s_mov_b32 s98, s10
	v_add_u32_e32 v101, s99, v82
	v_add_u32_e32 v100, s99, v79
	s_add_i32 s10, s9, 0xc000
	s_cmp_lg_u32 s9, 0x18000
	s_cselect_b32 s9, s10, 0
	s_add_i32 s10, s3, 0xc000
	s_cmp_lg_u32 s3, 0x18000
	s_cselect_b32 s3, s10, 0
	s_add_i32 s8, s8, -1
	ds_read_b128 v[236:239], v101 offset:16384
	ds_read_b128 v[240:243], v100
	ds_read_b128 v[244:247], v100 offset:4096
	ds_read_b128 v[248:251], v101 offset:20480
	s_waitcnt lgkmcnt(4)
	v_mfma_f32_32x32x16_bf16 v[48:63], v[84:87], v[88:91], v[48:63]
	v_mfma_f32_32x32x16_bf16 v[32:47], v[84:87], v[92:95], v[32:47]
	s_mov_b32 m0, s98
	v_lshl_add_u64 v[254:255], v[74:75], 0, v[120:121]
	global_load_lds_dwordx4 v[254:255], off
	v_lshl_add_u64 v[74:75], v[74:75], 0, s[94:95]
	v_mfma_f32_32x32x16_bf16 v[16:31], v[96:99], v[88:91], v[16:31]
	v_mfma_f32_32x32x16_bf16 v[0:15], v[96:99], v[92:95], v[0:15]
	s_add_i32 m0, s98, 0x2000
	v_lshl_add_u64 v[254:255], v[72:73], 0, v[120:121]
	global_load_lds_dwordx4 v[254:255], off
	v_lshl_add_u64 v[72:73], v[72:73], 0, s[94:95]
	v_add_u32_e32 v101, s99, v80
	v_add_u32_e32 v100, s99, v77
	ds_read_b128 v[84:87], v101 offset:16384
	ds_read_b128 v[88:91], v100
	ds_read_b128 v[92:95], v100 offset:4096
	ds_read_b128 v[96:99], v101 offset:20480
	s_waitcnt lgkmcnt(4)
	v_mfma_f32_32x32x16_bf16 v[48:63], v[236:239], v[240:243], v[48:63]
	v_mfma_f32_32x32x16_bf16 v[32:47], v[236:239], v[244:247], v[32:47]
	s_add_i32 m0, s98, 0x4000
	v_lshl_add_u64 v[254:255], v[70:71], 0, v[120:121]
	global_load_lds_dwordx4 v[254:255], off
	v_lshl_add_u64 v[70:71], v[70:71], 0, s[94:95]
	v_mfma_f32_32x32x16_bf16 v[16:31], v[248:251], v[240:243], v[16:31]
	v_mfma_f32_32x32x16_bf16 v[0:15], v[248:251], v[244:247], v[0:15]
	s_add_i32 m0, s98, 0x6000
	v_lshl_add_u64 v[254:255], v[68:69], 0, v[120:121]
	global_load_lds_dwordx4 v[254:255], off
	v_lshl_add_u64 v[68:69], v[68:69], 0, s[94:95]
	v_add_u32_e32 v101, s99, v78
	v_add_u32_e32 v100, s99, v76
	ds_read_b128 v[236:239], v101 offset:16384
	ds_read_b128 v[240:243], v100
	ds_read_b128 v[244:247], v100 offset:4096
	ds_read_b128 v[248:251], v101 offset:20480
	s_waitcnt lgkmcnt(4)
	v_mfma_f32_32x32x16_bf16 v[48:63], v[84:87], v[88:91], v[48:63]
	v_mfma_f32_32x32x16_bf16 v[32:47], v[84:87], v[92:95], v[32:47]
	s_add_i32 m0, s98, 0x8000
	v_lshl_add_u64 v[254:255], v[66:67], 0, v[120:121]
	global_load_lds_dwordx4 v[254:255], off
	v_lshl_add_u64 v[66:67], v[66:67], 0, s[94:95]
	v_mfma_f32_32x32x16_bf16 v[16:31], v[96:99], v[88:91], v[16:31]
	v_mfma_f32_32x32x16_bf16 v[0:15], v[96:99], v[92:95], v[0:15]
	s_add_i32 m0, s98, 0xa000
	v_lshl_add_u64 v[254:255], v[64:65], 0, v[120:121]
	global_load_lds_dwordx4 v[254:255], off
	v_lshl_add_u64 v[64:65], v[64:65], 0, s[94:95]
	s_waitcnt vmcnt(6) lgkmcnt(0)
	s_barrier
	s_add_i32 s99, s9, 0
	v_add_u32_e32 v253, s99, v81
	v_add_u32_e32 v252, s99, v83
	ds_read_b128 v[84:87], v252 offset:16384
	ds_read_b128 v[88:91], v253
	ds_read_b128 v[92:95], v253 offset:4096
	ds_read_b128 v[96:99], v252 offset:20480
	s_waitcnt lgkmcnt(4)
	v_mfma_f32_32x32x16_bf16 v[48:63], v[236:239], v[240:243], v[48:63]
	v_mfma_f32_32x32x16_bf16 v[32:47], v[236:239], v[244:247], v[32:47]
	v_mfma_f32_32x32x16_bf16 v[16:31], v[248:251], v[240:243], v[16:31]
	v_mfma_f32_32x32x16_bf16 v[0:15], v[248:251], v[244:247], v[0:15]
	s_cmp_lg_u32 s8, 0
	s_cbranch_scc1 .LBB0_854
; DEV int stage_next(int s) { return (s == 2 * GS_STAGE) ? 0 : s + GS_STAGE; }
; template <int WAIT0>
; DEV void gk_main(f32x16 (&acc)[2][2], const GTile& t, int s0) {
;     ...
;   vm_wait_bar<WAIT0>();
;   int stc = s0, std_ = stage_next(stage_next(s0));
; #pragma nounroll
;   for (int kt = 0; kt < nk - 2; ++kt) {
;     GK_DMA(std_, kt + 2);
;     GK_COMPUTE(stc);
;     vm_wait_bar<6>();
;     stc = stage_next(stc); std_ = stage_next(std_);
;   }
;   GK_COMPUTE(stc);
;   vm_wait_bar<0>();
;   stc = stage_next(stc);
;   GK_COMPUTE(stc);
;   vm_wait_bar<0>();
	s_waitcnt lgkmcnt(0)
	s_add_i32 s2, s9, 0
	v_add_u32_e32 v84, s2, v83
	ds_read_b128 v[64:67], v84 offset:16384
	v_add_u32_e32 v72, s2, v81
	ds_read_b128 v[68:71], v72
	ds_read_b128 v[72:75], v72 offset:4096
	ds_read_b128 v[84:87], v84 offset:20480
	s_waitcnt lgkmcnt(0)
	v_mfma_f32_32x32x16_bf16 v[16:31], v[84:87], v[68:71], v[16:31]
	v_mfma_f32_32x32x16_bf16 v[0:15], v[84:87], v[72:75], v[0:15]
	v_add_u32_e32 v84, s2, v82
	v_mfma_f32_32x32x16_bf16 v[48:63], v[64:67], v[68:71], v[48:63]
	v_mfma_f32_32x32x16_bf16 v[32:47], v[64:67], v[72:75], v[32:47]
	ds_read_b128 v[64:67], v84 offset:16384
	v_add_u32_e32 v72, s2, v79
	ds_read_b128 v[68:71], v72
	ds_read_b128 v[72:75], v72 offset:4096
	ds_read_b128 v[84:87], v84 offset:20480
	s_waitcnt lgkmcnt(0)
	v_mfma_f32_32x32x16_bf16 v[16:31], v[84:87], v[68:71], v[16:31]
	v_mfma_f32_32x32x16_bf16 v[0:15], v[84:87], v[72:75], v[0:15]
	v_add_u32_e32 v84, s2, v80
	v_mfma_f32_32x32x16_bf16 v[48:63], v[64:67], v[68:71], v[48:63]
	v_mfma_f32_32x32x16_bf16 v[32:47], v[64:67], v[72:75], v[32:47]
	ds_read_b128 v[64:67], v84 offset:16384
	v_add_u32_e32 v72, s2, v77
	ds_read_b128 v[68:71], v72
	ds_read_b128 v[72:75], v72 offset:4096
	ds_read_b128 v[84:87], v84 offset:20480
	s_waitcnt lgkmcnt(0)
	v_mfma_f32_32x32x16_bf16 v[16:31], v[84:87], v[68:71], v[16:31]
	v_mfma_f32_32x32x16_bf16 v[0:15], v[84:87], v[72:75], v[0:15]
	v_add_u32_e32 v84, s2, v78
	v_mfma_f32_32x32x16_bf16 v[48:63], v[64:67], v[68:71], v[48:63]
	v_mfma_f32_32x32x16_bf16 v[32:47], v[64:67], v[72:75], v[32:47]
	ds_read_b128 v[64:67], v84 offset:16384
	v_add_u32_e32 v72, s2, v76
	s_add_i32 s2, s9, 0xc000
	ds_read_b128 v[68:71], v72
	ds_read_b128 v[72:75], v72 offset:4096
	ds_read_b128 v[84:87], v84 offset:20480
	s_cmp_lg_u32 s9, 0x18000
	s_cselect_b32 s2, s2, 0
	s_add_i32 s2, s2, 0
	s_waitcnt vmcnt(0) lgkmcnt(0)
	s_barrier
	v_add_u32_e32 v83, s2, v83
	s_waitcnt lgkmcnt(0)
	v_mfma_f32_32x32x16_bf16 v[48:63], v[64:67], v[68:71], v[48:63]
	v_mfma_f32_32x32x16_bf16 v[32:47], v[64:67], v[72:75], v[32:47]
	ds_read_b128 v[64:67], v83 offset:16384
	v_mfma_f32_32x32x16_bf16 v[16:31], v[84:87], v[68:71], v[16:31]
	v_mfma_f32_32x32x16_bf16 v[0:15], v[84:87], v[72:75], v[0:15]
	v_add_u32_e32 v72, s2, v81
	ds_read_b128 v[68:71], v72
	ds_read_b128 v[72:75], v72 offset:4096
	ds_read_b128 v[84:87], v83 offset:20480
	v_add_u32_e32 v81, s2, v82
	s_waitcnt lgkmcnt(0)
	v_mfma_f32_32x32x16_bf16 v[48:63], v[64:67], v[68:71], v[48:63]
	v_mfma_f32_32x32x16_bf16 v[32:47], v[64:67], v[72:75], v[32:47]
	ds_read_b128 v[64:67], v81 offset:16384
	v_mfma_f32_32x32x16_bf16 v[16:31], v[84:87], v[68:71], v[16:31]
	v_mfma_f32_32x32x16_bf16 v[0:15], v[84:87], v[72:75], v[0:15]
	v_add_u32_e32 v72, s2, v79
	ds_read_b128 v[68:71], v72
	ds_read_b128 v[72:75], v72 offset:4096
	ds_read_b128 v[82:85], v81 offset:20480
	v_add_u32_e32 v79, s2, v80
	s_waitcnt lgkmcnt(0)
	v_mfma_f32_32x32x16_bf16 v[48:63], v[64:67], v[68:71], v[48:63]
	v_mfma_f32_32x32x16_bf16 v[32:47], v[64:67], v[72:75], v[32:47]
	ds_read_b128 v[64:67], v79 offset:16384
	v_mfma_f32_32x32x16_bf16 v[16:31], v[82:85], v[68:71], v[16:31]
	v_mfma_f32_32x32x16_bf16 v[0:15], v[82:85], v[72:75], v[0:15]
	v_add_u32_e32 v72, s2, v77
	ds_read_b128 v[68:71], v72
	ds_read_b128 v[72:75], v72 offset:4096
	ds_read_b128 v[80:83], v79 offset:20480
	v_add_u32_e32 v77, s2, v78
	s_waitcnt lgkmcnt(0)
	v_mfma_f32_32x32x16_bf16 v[48:63], v[64:67], v[68:71], v[48:63]
	v_mfma_f32_32x32x16_bf16 v[32:47], v[64:67], v[72:75], v[32:47]
	ds_read_b128 v[64:67], v77 offset:16384
	v_mfma_f32_32x32x16_bf16 v[16:31], v[80:83], v[68:71], v[16:31]
	v_mfma_f32_32x32x16_bf16 v[0:15], v[80:83], v[72:75], v[0:15]
	v_add_u32_e32 v72, s2, v76
	ds_read_b128 v[68:71], v72
	ds_read_b128 v[72:75], v72 offset:4096
	ds_read_b128 v[76:79], v77 offset:20480
	s_waitcnt vmcnt(0) lgkmcnt(0)
	s_barrier
	s_waitcnt lgkmcnt(0)
	v_mfma_f32_32x32x16_bf16 v[48:63], v[64:67], v[68:71], v[48:63]
	v_mfma_f32_32x32x16_bf16 v[32:47], v[64:67], v[72:75], v[32:47]
	v_mfma_f32_32x32x16_bf16 v[16:31], v[76:79], v[68:71], v[16:31]
	v_mfma_f32_32x32x16_bf16 v[0:15], v[76:79], v[72:75], v[0:15]
	s_add_i32 s2, s19, 1
	s_cmp_eq_u32 s19, 7
	s_mov_b64 s[8:9], 0
	s_cbranch_scc1 .LBB0_850
